# duplicate compiler lgkmcnt(0) waits after the asm wait removed in the GEMM K-loops
# baseline (speedup 1.0000x reference)
; #define PG8_STAGE(bufoff, gbase, voff) do { _Pragma("unroll") for (int _i = 0; _i < 2; ++_i) \
;         __builtin_amdgcn_global_load_lds((const unsigned*)((const char*)(gbase) + (voff)[_i]), (PG8_LAS unsigned*)(lds + (bufoff) + ldsw + _i * 8192), 16, 0, 0); } while (0)
; #define PG8_LDA(dst, b, h) do { _Pragma("unroll") for (int m = 0; m < 4; ++m) _Pragma("unroll") for (int k = 0; k < 2; ++k) dst[m][k] = *(const PG8_LAS bf16x8*)(lds + PG8_SA(b, h) + aoff + m * 2048 + k * 1024); } while (0)
; #define PG8_LDB(dst, b, h) do { _Pragma("unroll") for (int n = 0; n < 2; ++n) _Pragma("unroll") for (int k = 0; k < 2; ++k) dst[n][k] = *(const PG8_LAS bf16x8*)(lds + PG8_SB(b, h) + boff + n * 2048 + k * 1024); } while (0)
; #define PG8_MMA(ai, bj, At, Bt) do { __builtin_amdgcn_s_setprio(1); _Pragma("unroll") for (int m = 0; m < 4; ++m) _Pragma("unroll") for (int n = 0; n < 2; ++n) _Pragma("unroll") for (int k = 0; k < 2; ++k) \
;         acc[ai][bj][m][n] = __builtin_amdgcn_mfma_f32_16x16x32_bf16(Bt[n][k], At[m][k], acc[ai][bj][m][n], 0, 0, 0); __builtin_amdgcn_s_setprio(0); } while (0)
; #define PG8_WAIT_L(n) asm volatile("s_waitcnt lgkmcnt(" #n ")" ::: "memory")
; #define PG8_BAR __builtin_amdgcn_s_barrier()
; #define PG8_SCHED __builtin_amdgcn_sched_barrier(0)
; template <class Epi, class Sched>
; __device__ __forceinline__ void gemm_phase(PG8_LAS unsigned char* lds, const Gemm g, const Sched& S, const Epi& E) {
;     ...
;             PG8_LDB(B0, 0, 0); PG8_SCHED; PG8_LDA(At, 0, 0); PG8_STAGE(PG8_SA(1, 1), a1 + hstep, voffA);
;             PG8_WAIT_L(8); PG8_BAR; PG8_WAIT_L(0); PG8_MMA(0, 0, At, B0); PG8_BAR; PG8_SCHED;
;             PG8_LDB(B1, 0, 1); PG8_STAGE(PG8_SB(0, 0), b2, voffB);
;             PG8_BAR; PG8_WAIT_L(0); PG8_MMA(0, 1, At, B1); PG8_BAR;
;             PG8_LDA(At, 0, 1); PG8_STAGE(PG8_SA(0, 0), a2, voffA);
;             PG8_BAR; PG8_WAIT_L(0); PG8_MMA(1, 0, At, B0); PG8_BAR; PG8_SCHED;
.LBB0_152:
	ds_read_b128 v[128:131], v167
	ds_read_b128 v[132:135], v167 offset:1024
	ds_read_b128 v[156:159], v167 offset:2048
	ds_read_b128 v[160:163], v167 offset:3072
	s_add_u32 s34, s30, 0xfffc0080
	s_addc_u32 s35, s31, -1
	s_cmp_eq_u32 s50, 12
	s_cselect_b32 s37, s7, s35
	s_cselect_b32 s36, s23, s34
	s_cselect_b32 s35, s21, s49
	s_cselect_b32 s34, s29, s48
	v_lshl_add_u64 v[204:205], s[30:31], 0, v[148:149]
	s_add_i32 m0, s3, 0xc000
	ds_read_b128 v[172:175], v168
	ds_read_b128 v[180:183], v168 offset:1024
	ds_read_b128 v[184:187], v168 offset:2048
	ds_read_b128 v[188:191], v168 offset:3072
	ds_read_b128 v[192:195], v168 offset:4096
	ds_read_b128 v[196:199], v168 offset:5120
	ds_read_b128 v[200:203], v168 offset:6144
	ds_read_b128 v[208:211], v168 offset:7168
	global_load_lds_dwordx4 v[204:205], off
	v_lshl_add_u64 v[204:205], s[30:31], 0, v[150:151]
	s_add_i32 m0, s3, 0xe000
	s_nop 0
	global_load_lds_dwordx4 v[204:205], off
	s_waitcnt lgkmcnt(8)
	s_barrier
	s_waitcnt lgkmcnt(0)
	s_setprio 1
	v_mfma_f32_16x16x32_bf16 v[124:127], v[128:131], v[172:175], v[124:127]
	v_mfma_f32_16x16x32_bf16 v[120:123], v[156:159], v[172:175], v[120:123]
	v_mfma_f32_16x16x32_bf16 v[108:111], v[128:131], v[184:187], v[108:111]
	v_mfma_f32_16x16x32_bf16 v[104:107], v[156:159], v[184:187], v[104:107]
	v_mfma_f32_16x16x32_bf16 v[92:95], v[128:131], v[192:195], v[92:95]
	v_mfma_f32_16x16x32_bf16 v[88:91], v[156:159], v[192:195], v[88:91]
	v_mfma_f32_16x16x32_bf16 v[76:79], v[128:131], v[200:203], v[76:79]
	v_mfma_f32_16x16x32_bf16 v[72:75], v[156:159], v[200:203], v[72:75]
	v_mfma_f32_16x16x32_bf16 v[124:127], v[132:135], v[180:183], v[124:127]
	v_mfma_f32_16x16x32_bf16 v[120:123], v[160:163], v[180:183], v[120:123]
	v_mfma_f32_16x16x32_bf16 v[108:111], v[132:135], v[188:191], v[108:111]
	v_mfma_f32_16x16x32_bf16 v[104:107], v[160:163], v[188:191], v[104:107]
	v_mfma_f32_16x16x32_bf16 v[92:95], v[132:135], v[196:199], v[92:95]
	v_mfma_f32_16x16x32_bf16 v[88:91], v[160:163], v[196:199], v[88:91]
	v_mfma_f32_16x16x32_bf16 v[76:79], v[132:135], v[208:211], v[76:79]
	v_mfma_f32_16x16x32_bf16 v[72:75], v[160:163], v[208:211], v[72:75]
	s_setprio 0
	s_barrier
	s_add_i32 s51, s45, s1
	v_lshl_add_u64 v[204:205], s[34:35], 0, v[138:139]
	s_mov_b32 m0, s51
	ds_read_b128 v[212:215], v169
	ds_read_b128 v[216:219], v169 offset:1024
	ds_read_b128 v[220:223], v169 offset:2048
	ds_read_b128 v[224:227], v169 offset:3072
	global_load_lds_dwordx4 v[204:205], off
	v_lshl_add_u64 v[228:229], s[34:35], 0, v[142:143]
	s_add_i32 m0, s51, 0x2000
	s_nop 0
	global_load_lds_dwordx4 v[228:229], off
	s_barrier
	s_waitcnt lgkmcnt(0)
	s_setprio 1
	v_mfma_f32_16x16x32_bf16 v[116:119], v[212:215], v[172:175], v[116:119]
	v_mfma_f32_16x16x32_bf16 v[112:115], v[220:223], v[172:175], v[112:115]
	v_mfma_f32_16x16x32_bf16 v[100:103], v[212:215], v[184:187], v[100:103]
	v_mfma_f32_16x16x32_bf16 v[96:99], v[220:223], v[184:187], v[96:99]
	v_mfma_f32_16x16x32_bf16 v[84:87], v[212:215], v[192:195], v[84:87]
	v_mfma_f32_16x16x32_bf16 v[80:83], v[220:223], v[192:195], v[80:83]
	v_mfma_f32_16x16x32_bf16 v[68:71], v[212:215], v[200:203], v[68:71]
	v_mfma_f32_16x16x32_bf16 v[64:67], v[220:223], v[200:203], v[64:67]
	v_mfma_f32_16x16x32_bf16 v[116:119], v[216:219], v[180:183], v[116:119]
	v_mfma_f32_16x16x32_bf16 v[112:115], v[224:227], v[180:183], v[112:115]
	v_mfma_f32_16x16x32_bf16 v[100:103], v[216:219], v[188:191], v[100:103]
	v_mfma_f32_16x16x32_bf16 v[96:99], v[224:227], v[188:191], v[96:99]
	v_mfma_f32_16x16x32_bf16 v[84:87], v[216:219], v[196:199], v[84:87]
	v_mfma_f32_16x16x32_bf16 v[80:83], v[224:227], v[196:199], v[80:83]
	v_mfma_f32_16x16x32_bf16 v[68:71], v[216:219], v[208:211], v[68:71]
	v_mfma_f32_16x16x32_bf16 v[64:67], v[224:227], v[208:211], v[64:67]
	s_setprio 0
	s_mov_b32 m0, s3
	v_lshl_add_u64 v[230:231], s[36:37], 0, v[136:137]
	s_barrier
	ds_read_b128 v[172:175], v168 offset:16384
	ds_read_b128 v[180:183], v168 offset:17408
	ds_read_b128 v[184:187], v168 offset:18432
	ds_read_b128 v[188:191], v168 offset:19456
	ds_read_b128 v[192:195], v168 offset:20480
	ds_read_b128 v[196:199], v168 offset:21504
	ds_read_b128 v[200:203], v168 offset:22528
	ds_read_b128 v[208:211], v168 offset:23552
	global_load_lds_dwordx4 v[230:231], off
	v_lshl_add_u64 v[232:233], s[36:37], 0, v[140:141]
	s_mov_b32 m0, s33
	s_nop 0
	global_load_lds_dwordx4 v[232:233], off
	s_barrier
	s_waitcnt lgkmcnt(0)
	s_setprio 1
	v_mfma_f32_16x16x32_bf16 v[60:63], v[128:131], v[172:175], v[60:63]
	v_mfma_f32_16x16x32_bf16 v[56:59], v[156:159], v[172:175], v[56:59]
	v_mfma_f32_16x16x32_bf16 v[44:47], v[128:131], v[184:187], v[44:47]
	v_mfma_f32_16x16x32_bf16 v[40:43], v[156:159], v[184:187], v[40:43]
	v_mfma_f32_16x16x32_bf16 v[28:31], v[128:131], v[192:195], v[28:31]
	v_mfma_f32_16x16x32_bf16 v[24:27], v[156:159], v[192:195], v[24:27]
	v_mfma_f32_16x16x32_bf16 v[12:15], v[128:131], v[200:203], v[12:15]
	v_mfma_f32_16x16x32_bf16 v[8:11], v[156:159], v[200:203], v[8:11]
	v_mfma_f32_16x16x32_bf16 v[60:63], v[132:135], v[180:183], v[60:63]
	v_mfma_f32_16x16x32_bf16 v[56:59], v[160:163], v[180:183], v[56:59]
	v_mfma_f32_16x16x32_bf16 v[44:47], v[132:135], v[188:191], v[44:47]
	v_mfma_f32_16x16x32_bf16 v[40:43], v[160:163], v[188:191], v[40:43]
	v_mfma_f32_16x16x32_bf16 v[28:31], v[132:135], v[196:199], v[28:31]
	v_mfma_f32_16x16x32_bf16 v[24:27], v[160:163], v[196:199], v[24:27]
	v_mfma_f32_16x16x32_bf16 v[12:15], v[132:135], v[208:211], v[12:15]
	v_mfma_f32_16x16x32_bf16 v[8:11], v[160:163], v[208:211], v[8:11]
	s_setprio 0
	s_barrier
; #define PG8_STAGE(bufoff, gbase, voff) do { _Pragma("unroll") for (int _i = 0; _i < 2; ++_i) \
;         __builtin_amdgcn_global_load_lds((const unsigned*)((const char*)(gbase) + (voff)[_i]), (PG8_LAS unsigned*)(lds + (bufoff) + ldsw + _i * 8192), 16, 0, 0); } while (0)
; #define PG8_LDA(dst, b, h) do { _Pragma("unroll") for (int m = 0; m < 4; ++m) _Pragma("unroll") for (int k = 0; k < 2; ++k) dst[m][k] = *(const PG8_LAS bf16x8*)(lds + PG8_SA(b, h) + aoff + m * 2048 + k * 1024); } while (0)
; #define PG8_LDB(dst, b, h) do { _Pragma("unroll") for (int n = 0; n < 2; ++n) _Pragma("unroll") for (int k = 0; k < 2; ++k) dst[n][k] = *(const PG8_LAS bf16x8*)(lds + PG8_SB(b, h) + boff + n * 2048 + k * 1024); } while (0)
; #define PG8_MMA(ai, bj, At, Bt) do { __builtin_amdgcn_s_setprio(1); _Pragma("unroll") for (int m = 0; m < 4; ++m) _Pragma("unroll") for (int n = 0; n < 2; ++n) _Pragma("unroll") for (int k = 0; k < 2; ++k) \
;         acc[ai][bj][m][n] = __builtin_amdgcn_mfma_f32_16x16x32_bf16(Bt[n][k], At[m][k], acc[ai][bj][m][n], 0, 0, 0); __builtin_amdgcn_s_setprio(0); } while (0)
; #define PG8_WAIT_V(n) asm volatile("s_waitcnt vmcnt(" #n ")" ::: "memory")
; #define PG8_WAIT_L(n) asm volatile("s_waitcnt lgkmcnt(" #n ")" ::: "memory")
; #define PG8_BAR __builtin_amdgcn_s_barrier()
; #define PG8_SCHED __builtin_amdgcn_sched_barrier(0)
; template <class Epi, class Sched>
; __device__ __forceinline__ void gemm_phase(PG8_LAS unsigned char* lds, const Gemm g, const Sched& S, const Epi& E) {
;     ...
;             PG8_STAGE(PG8_SB(0, 1), b2 + hstep, voffB);
;             PG8_WAIT_V(6); PG8_BAR; PG8_MMA(1, 1, At, B1); PG8_BAR;
;             PG8_LDB(B0, 1, 0); PG8_SCHED; PG8_LDA(At, 1, 0); PG8_STAGE(PG8_SA(0, 1), a2 + hstep, voffA);
;             PG8_WAIT_L(8); PG8_BAR; PG8_WAIT_L(0); PG8_MMA(0, 0, At, B0); PG8_BAR; PG8_SCHED;
;             PG8_LDB(B1, 1, 1); PG8_STAGE(PG8_SB(1, 0), b3, voffB);
;             PG8_BAR; PG8_WAIT_L(0); PG8_MMA(0, 1, At, B1); PG8_BAR;
;             PG8_LDA(At, 1, 1); PG8_STAGE(PG8_SA(1, 0), a3, voffA);
	s_add_u32 s64, s34, 0x40000
	s_addc_u32 s65, s35, 0
	s_add_i32 s51, s46, s1
	v_lshl_add_u64 v[128:129], s[64:65], 0, v[138:139]
	s_mov_b32 m0, s51
	s_nop 0
	global_load_lds_dwordx4 v[128:129], off
	v_lshl_add_u64 v[128:129], s[64:65], 0, v[142:143]
	s_add_i32 m0, s51, 0x2000
	s_nop 0
	global_load_lds_dwordx4 v[128:129], off
	s_waitcnt vmcnt(6)
	s_barrier
	s_setprio 1
	v_mfma_f32_16x16x32_bf16 v[52:55], v[212:215], v[172:175], v[52:55]
	v_mfma_f32_16x16x32_bf16 v[48:51], v[220:223], v[172:175], v[48:51]
	v_mfma_f32_16x16x32_bf16 v[36:39], v[212:215], v[184:187], v[36:39]
	v_mfma_f32_16x16x32_bf16 v[32:35], v[220:223], v[184:187], v[32:35]
	v_mfma_f32_16x16x32_bf16 v[20:23], v[212:215], v[192:195], v[20:23]
	v_mfma_f32_16x16x32_bf16 v[16:19], v[220:223], v[192:195], v[16:19]
	v_mfma_f32_16x16x32_bf16 v[4:7], v[212:215], v[200:203], v[4:7]
	v_mfma_f32_16x16x32_bf16 v[0:3], v[220:223], v[200:203], v[0:3]
	v_mfma_f32_16x16x32_bf16 v[52:55], v[216:219], v[180:183], v[52:55]
	v_mfma_f32_16x16x32_bf16 v[48:51], v[224:227], v[180:183], v[48:51]
	v_mfma_f32_16x16x32_bf16 v[36:39], v[216:219], v[188:191], v[36:39]
	v_mfma_f32_16x16x32_bf16 v[32:35], v[224:227], v[188:191], v[32:35]
	v_mfma_f32_16x16x32_bf16 v[20:23], v[216:219], v[196:199], v[20:23]
	v_mfma_f32_16x16x32_bf16 v[16:19], v[224:227], v[196:199], v[16:19]
	v_mfma_f32_16x16x32_bf16 v[4:7], v[216:219], v[208:211], v[4:7]
	v_mfma_f32_16x16x32_bf16 v[0:3], v[224:227], v[208:211], v[0:3]
	s_setprio 0
	s_add_i32 s51, 0, 0x18000
	v_add_u32_e32 v144, s51, v164
	s_barrier
	ds_read_b128 v[128:131], v144
	ds_read_b128 v[132:135], v144 offset:1024
	ds_read_b128 v[156:159], v144 offset:2048
	ds_read_b128 v[160:163], v144 offset:3072
	s_add_u32 s36, s36, 0x40000
	s_addc_u32 s37, s37, 0
	s_mov_b32 m0, s38
	v_lshl_add_u64 v[212:213], s[36:37], 0, v[136:137]
	ds_read_b128 v[172:175], v168 offset:32768
	ds_read_b128 v[180:183], v168 offset:33792
	ds_read_b128 v[184:187], v168 offset:34816
	ds_read_b128 v[188:191], v168 offset:35840
	ds_read_b128 v[192:195], v168 offset:36864
	ds_read_b128 v[196:199], v168 offset:37888
	ds_read_b128 v[200:203], v168 offset:38912
	ds_read_b128 v[208:211], v168 offset:39936
	global_load_lds_dwordx4 v[212:213], off
	v_lshl_add_u64 v[212:213], s[36:37], 0, v[140:141]
	s_mov_b32 m0, s39
	s_nop 0
	global_load_lds_dwordx4 v[212:213], off
	s_waitcnt lgkmcnt(8)
	s_barrier
	s_waitcnt lgkmcnt(0)
	s_setprio 1
	v_mfma_f32_16x16x32_bf16 v[124:127], v[128:131], v[172:175], v[124:127]
	v_mfma_f32_16x16x32_bf16 v[120:123], v[156:159], v[172:175], v[120:123]
	v_mfma_f32_16x16x32_bf16 v[108:111], v[128:131], v[184:187], v[108:111]
	v_mfma_f32_16x16x32_bf16 v[104:107], v[156:159], v[184:187], v[104:107]
	v_mfma_f32_16x16x32_bf16 v[92:95], v[128:131], v[192:195], v[92:95]
	v_mfma_f32_16x16x32_bf16 v[88:91], v[156:159], v[192:195], v[88:91]
	v_mfma_f32_16x16x32_bf16 v[76:79], v[128:131], v[200:203], v[76:79]
	v_mfma_f32_16x16x32_bf16 v[72:75], v[156:159], v[200:203], v[72:75]
	v_mfma_f32_16x16x32_bf16 v[124:127], v[132:135], v[180:183], v[124:127]
	v_mfma_f32_16x16x32_bf16 v[120:123], v[160:163], v[180:183], v[120:123]
	v_mfma_f32_16x16x32_bf16 v[108:111], v[132:135], v[188:191], v[108:111]
	v_mfma_f32_16x16x32_bf16 v[104:107], v[160:163], v[188:191], v[104:107]
	v_mfma_f32_16x16x32_bf16 v[92:95], v[132:135], v[196:199], v[92:95]
	v_mfma_f32_16x16x32_bf16 v[88:91], v[160:163], v[196:199], v[88:91]
	v_mfma_f32_16x16x32_bf16 v[76:79], v[132:135], v[208:211], v[76:79]
	v_mfma_f32_16x16x32_bf16 v[72:75], v[160:163], v[208:211], v[72:75]
	s_setprio 0
	s_barrier
	s_add_i32 s36, 0, 0x1c000
	s_add_i32 s37, s51, s1
	v_add_u32_e32 v144, s36, v164
	v_lshl_add_u64 v[204:205], v[204:205], 0, s[12:13]
	s_mov_b32 m0, s37
	ds_read_b128 v[212:215], v144
	ds_read_b128 v[216:219], v144 offset:1024
	ds_read_b128 v[220:223], v144 offset:2048
	ds_read_b128 v[224:227], v144 offset:3072
	global_load_lds_dwordx4 v[204:205], off
	v_lshl_add_u64 v[204:205], v[228:229], 0, s[12:13]
	s_add_i32 m0, s37, 0x2000
	s_nop 0
	global_load_lds_dwordx4 v[204:205], off
	s_barrier
	s_waitcnt lgkmcnt(0)
	s_setprio 1
	v_mfma_f32_16x16x32_bf16 v[116:119], v[212:215], v[172:175], v[116:119]
	v_mfma_f32_16x16x32_bf16 v[112:115], v[220:223], v[172:175], v[112:115]
	v_mfma_f32_16x16x32_bf16 v[100:103], v[212:215], v[184:187], v[100:103]
	v_mfma_f32_16x16x32_bf16 v[96:99], v[220:223], v[184:187], v[96:99]
	v_mfma_f32_16x16x32_bf16 v[84:87], v[212:215], v[192:195], v[84:87]
	v_mfma_f32_16x16x32_bf16 v[80:83], v[220:223], v[192:195], v[80:83]
	v_mfma_f32_16x16x32_bf16 v[68:71], v[212:215], v[200:203], v[68:71]
	v_mfma_f32_16x16x32_bf16 v[64:67], v[220:223], v[200:203], v[64:67]
	v_mfma_f32_16x16x32_bf16 v[116:119], v[216:219], v[180:183], v[116:119]
	v_mfma_f32_16x16x32_bf16 v[112:115], v[224:227], v[180:183], v[112:115]
	v_mfma_f32_16x16x32_bf16 v[100:103], v[216:219], v[188:191], v[100:103]
	v_mfma_f32_16x16x32_bf16 v[96:99], v[224:227], v[188:191], v[96:99]
	v_mfma_f32_16x16x32_bf16 v[84:87], v[216:219], v[196:199], v[84:87]
	v_mfma_f32_16x16x32_bf16 v[80:83], v[224:227], v[196:199], v[80:83]
	v_mfma_f32_16x16x32_bf16 v[68:71], v[216:219], v[208:211], v[68:71]
	v_mfma_f32_16x16x32_bf16 v[64:67], v[224:227], v[208:211], v[64:67]
	s_setprio 0
	s_mov_b32 m0, s42
	v_lshl_add_u64 v[204:205], v[230:231], 0, s[12:13]
	s_barrier
; __device__ __forceinline__ unsigned cvt_pk_bf16(float lo, float hi) { unsigned r; asm volatile("v_cvt_pk_bf16_f32 %0, %1, %2" : "=v"(r) : "v"(lo), "v"(hi)); return r; }
; #define PG8_STAGE(bufoff, gbase, voff) do { _Pragma("unroll") for (int _i = 0; _i < 2; ++_i) \
;         __builtin_amdgcn_global_load_lds((const unsigned*)((const char*)(gbase) + (voff)[_i]), (PG8_LAS unsigned*)(lds + (bufoff) + ldsw + _i * 8192), 16, 0, 0); } while (0)
; #define PG8_LDA(dst, b, h) do { _Pragma("unroll") for (int m = 0; m < 4; ++m) _Pragma("unroll") for (int k = 0; k < 2; ++k) dst[m][k] = *(const PG8_LAS bf16x8*)(lds + PG8_SA(b, h) + aoff + m * 2048 + k * 1024); } while (0)
; #define PG8_WAIT_V(n) asm volatile("s_waitcnt vmcnt(" #n ")" ::: "memory")
; #define PG8_BAR __builtin_amdgcn_s_barrier()
; template <class Epi, class Sched>
; __device__ __forceinline__ void gemm_phase(PG8_LAS unsigned char* lds, const Gemm g, const Sched& S, const Epi& E) {
;     ...
;             PG8_LDA(At, 1, 1); PG8_STAGE(PG8_SA(1, 0), a3, voffA);
;             PG8_BAR; PG8_WAIT_L(0); PG8_MMA(1, 0, At, B0); PG8_BAR; PG8_SCHED;
;             PG8_STAGE(PG8_SB(1, 1), b3 + hstep, voffB);
;             PG8_WAIT_V(6); PG8_BAR; PG8_MMA(1, 1, At, B1); PG8_BAR;
;         }
;     __device__ __forceinline__ void operator()(const f32x4 (&acc)[2][2][4][2], const Unit& u, int wr, int wc, int fr, int fq, const float (&epre)[1]) const {
;     ...
;             const int cu = (pn - 8) * 128 + wc * 32 + 8 * fq;
; #pragma unroll
;             for (int ai = 0; ai < 2; ++ai)
; #pragma unroll
;                 for (int m = 0; m < 4; ++m) { const int row = row0 + ai * 128 + m * 16;
;                     f32x4 u0, u1;
; #pragma unroll
;                     for (int j = 0; j < 4; ++j) { u0[j] = acc[ai][0][m][0][j] * sigmoidf_(acc[ai][1][m][0][j]); u1[j] = acc[ai][0][m][1][j] * sigmoidf_(acc[ai][1][m][1][j]); }
;                     u32x4 w; w.x = cvt_pk_bf16(u0[0], u0[1]); w.y = cvt_pk_bf16(u0[2], u0[3]); w.z = cvt_pk_bf16(u1[0], u1[1]); w.w = cvt_pk_bf16(u1[2], u1[3]);
;                     *(u32x4*)(U + (size_t)row * 512 + cu) = w;
;                     if (row < MP) { const int t = row & (SEQ - 1);
;                         if (t >= SEQ - (CW - 1)) { float* o = scp + ((size_t)((row >> 11) * (CW - 1) + t - (SEQ - (CW - 1)))) * MIXB + cu; __builtin_nontemporal_store(u0, (f32x4*)o); __builtin_nontemporal_store(u1, (f32x4*)(o + 4)); }
	ds_read_b128 v[172:175], v168 offset:49152
	ds_read_b128 v[180:183], v168 offset:50176
	ds_read_b128 v[184:187], v168 offset:51200
	ds_read_b128 v[188:191], v168 offset:52224
	ds_read_b128 v[192:195], v168 offset:53248
	ds_read_b128 v[196:199], v168 offset:54272
	ds_read_b128 v[200:203], v168 offset:55296
	ds_read_b128 v[208:211], v168 offset:56320
	global_load_lds_dwordx4 v[204:205], off
	v_lshl_add_u64 v[204:205], v[232:233], 0, s[12:13]
	s_mov_b32 m0, s43
	s_nop 0
	global_load_lds_dwordx4 v[204:205], off
	s_barrier
	s_waitcnt lgkmcnt(0)
	s_setprio 1
	v_mfma_f32_16x16x32_bf16 v[60:63], v[128:131], v[172:175], v[60:63]
	v_mfma_f32_16x16x32_bf16 v[56:59], v[156:159], v[172:175], v[56:59]
	v_mfma_f32_16x16x32_bf16 v[44:47], v[128:131], v[184:187], v[44:47]
	v_mfma_f32_16x16x32_bf16 v[40:43], v[156:159], v[184:187], v[40:43]
	v_mfma_f32_16x16x32_bf16 v[28:31], v[128:131], v[192:195], v[28:31]
	v_mfma_f32_16x16x32_bf16 v[24:27], v[156:159], v[192:195], v[24:27]
	v_mfma_f32_16x16x32_bf16 v[12:15], v[128:131], v[200:203], v[12:15]
	v_mfma_f32_16x16x32_bf16 v[8:11], v[156:159], v[200:203], v[8:11]
	v_mfma_f32_16x16x32_bf16 v[60:63], v[132:135], v[180:183], v[60:63]
	v_mfma_f32_16x16x32_bf16 v[56:59], v[160:163], v[180:183], v[56:59]
	v_mfma_f32_16x16x32_bf16 v[44:47], v[132:135], v[188:191], v[44:47]
	v_mfma_f32_16x16x32_bf16 v[40:43], v[160:163], v[188:191], v[40:43]
	v_mfma_f32_16x16x32_bf16 v[28:31], v[132:135], v[196:199], v[28:31]
	v_mfma_f32_16x16x32_bf16 v[24:27], v[160:163], v[196:199], v[24:27]
	v_mfma_f32_16x16x32_bf16 v[12:15], v[132:135], v[208:211], v[12:15]
	v_mfma_f32_16x16x32_bf16 v[8:11], v[160:163], v[208:211], v[8:11]
	s_setprio 0
	s_barrier
	s_add_u32 s34, s34, 0x40080
	s_addc_u32 s35, s35, 0
	s_add_i32 s36, s36, s1
	v_lshl_add_u64 v[128:129], s[34:35], 0, v[138:139]
	s_mov_b32 m0, s36
	s_nop 0
	global_load_lds_dwordx4 v[128:129], off
	v_lshl_add_u64 v[128:129], s[34:35], 0, v[142:143]
	s_add_i32 m0, s36, 0x2000
	s_nop 0
	global_load_lds_dwordx4 v[128:129], off
	s_waitcnt vmcnt(6)
	s_barrier
	s_setprio 1
	v_mfma_f32_16x16x32_bf16 v[52:55], v[212:215], v[172:175], v[52:55]
	v_mfma_f32_16x16x32_bf16 v[48:51], v[220:223], v[172:175], v[48:51]
	v_mfma_f32_16x16x32_bf16 v[36:39], v[212:215], v[184:187], v[36:39]
	v_mfma_f32_16x16x32_bf16 v[32:35], v[220:223], v[184:187], v[32:35]
	v_mfma_f32_16x16x32_bf16 v[20:23], v[212:215], v[192:195], v[20:23]
	v_mfma_f32_16x16x32_bf16 v[16:19], v[220:223], v[192:195], v[16:19]
	v_mfma_f32_16x16x32_bf16 v[4:7], v[212:215], v[200:203], v[4:7]
	v_mfma_f32_16x16x32_bf16 v[0:3], v[220:223], v[200:203], v[0:3]
	v_mfma_f32_16x16x32_bf16 v[52:55], v[216:219], v[180:183], v[52:55]
	v_mfma_f32_16x16x32_bf16 v[48:51], v[224:227], v[180:183], v[48:51]
	v_mfma_f32_16x16x32_bf16 v[36:39], v[216:219], v[188:191], v[36:39]
	v_mfma_f32_16x16x32_bf16 v[32:35], v[224:227], v[188:191], v[32:35]
	v_mfma_f32_16x16x32_bf16 v[20:23], v[216:219], v[196:199], v[20:23]
	v_mfma_f32_16x16x32_bf16 v[16:19], v[224:227], v[196:199], v[16:19]
	v_mfma_f32_16x16x32_bf16 v[4:7], v[216:219], v[208:211], v[4:7]
	v_mfma_f32_16x16x32_bf16 v[0:3], v[224:227], v[208:211], v[0:3]
	s_setprio 0
	s_add_i32 s50, s50, 2
	s_add_u32 s30, s30, 0x100
	s_addc_u32 s31, s31, 0
	s_add_u32 s48, s48, 0x100
	s_addc_u32 s49, s49, 0
	s_cmp_gt_u32 s50, 13
	s_barrier
	s_cbranch_scc0 .LBB0_152
	s_lshl_b32 s23, s6, 8
	s_lshl_b32 s6, s28, 2
	s_lshr_b64 s[6:7], s[14:15], s6
	s_add_i32 s23, s23, s41
	s_and_b32 s21, s6, 15
	v_or_b32_e32 v156, s23, v147
	s_cmp_gt_u32 s21, 7
	s_mov_b64 s[6:7], -1
	s_cbranch_scc0 .LBB0_187
	v_mul_f32_e32 v129, 0xbfb8aa3b, v112
	v_mul_f32_e32 v130, 0xbfb8aa3b, v117
	v_exp_f32_e32 v129, v129
	v_exp_f32_e32 v131, v130
	v_mul_f32_e32 v130, 0xbfb8aa3b, v113
	v_exp_f32_e32 v132, v130
	v_add_f32_e32 v129, 1.0, v129
	v_rcp_f32_e32 v130, v129
	v_add_f32_e32 v129, 1.0, v131
	v_add_f32_e32 v131, 1.0, v132
	v_mul_f32_e32 v132, 0xbfb8aa3b, v118
	v_exp_f32_e32 v132, v132
	v_mul_f32_e32 v133, 0xbfb8aa3b, v114
	v_exp_f32_e32 v133, v133
	v_mul_f32_e32 v128, 0xbfb8aa3b, v116
	v_add_f32_e32 v132, 1.0, v132
	v_rcp_f32_e32 v134, v132
	v_add_f32_e32 v132, 1.0, v133
	v_mul_f32_e32 v133, 0xbfb8aa3b, v119
	v_exp_f32_e32 v133, v133
	v_mul_f32_e32 v135, 0xbfb8aa3b, v115
	v_exp_f32_e32 v128, v128
	v_exp_f32_e32 v157, v135
	v_rcp_f32_e32 v158, v132
	v_add_f32_e32 v132, 1.0, v133
	v_add_f32_e32 v128, 1.0, v128
	v_rcp_f32_e32 v135, v132
	v_add_f32_e32 v132, 1.0, v157
	v_rcp_f32_e32 v128, v128
	v_rcp_f32_e32 v129, v129
	v_rcp_f32_e32 v131, v131
	v_rcp_f32_e32 v159, v132
	v_ashrrev_i32_e32 v157, 31, v156
	v_readlane_b32 s6, v247, 36
	v_lshlrev_b64 v[162:163], 10, v[156:157]
	v_readlane_b32 s7, v247, 37
	v_lshl_add_u32 v144, s21, 7, v166
	v_pk_mul_f32 v[132:133], v[124:125], v[128:129]
	v_lshl_add_u64 v[162:163], s[6:7], 0, v[162:163]
	v_pk_mul_f32 v[128:129], v[120:121], v[130:131]
	v_pk_mul_f32 v[134:135], v[126:127], v[134:135]
	v_pk_mul_f32 v[130:131], v[122:123], v[158:159]
	v_lshl_add_u64 v[162:163], v[144:145], 1, v[162:163]
	v_cmp_lt_i32_e32 vcc, s47, v156
	v_cvt_pk_bf16_f32 v158, v132, v133
	v_cvt_pk_bf16_f32 v159, v134, v135
	v_cvt_pk_bf16_f32 v160, v128, v129
	v_cvt_pk_bf16_f32 v161, v130, v131
	global_store_dwordx4 v[162:163], v[158:161], off
	s_and_saveexec_b64 s[6:7], vcc
	s_cbranch_execz .LBB0_156
	v_add_u32_e32 v158, 0xffffc000, v156
	v_lshrrev_b32_e32 v158, 2, v158
	v_mad_u64_u32 v[158:159], s[28:29], v158, 30, v[146:147]
	v_mov_b32_e32 v159, v145
	v_lshlrev_b64 v[158:159], 11, v[158:159]
	v_lshl_add_u64 v[158:159], s[8:9], 0, v[158:159]
	v_lshl_add_u64 v[158:159], v[144:145], 2, v[158:159]
	global_store_dwordx4 v[158:159], v[132:135], off
	global_store_dwordx4 v[158:159], v[128:131], off offset:16

; #define PG8_STAGE(bufoff, gbase, voff) do { _Pragma("unroll") for (int _i = 0; _i < 2; ++_i) \
;         __builtin_amdgcn_global_load_lds((const unsigned*)((const char*)(gbase) + (voff)[_i]), (PG8_LAS unsigned*)(lds + (bufoff) + ldsw + _i * 8192), 16, 0, 0); } while (0)
; #define PG8_LDA(dst, b, h) do { _Pragma("unroll") for (int m = 0; m < 4; ++m) _Pragma("unroll") for (int k = 0; k < 2; ++k) dst[m][k] = *(const PG8_LAS bf16x8*)(lds + PG8_SA(b, h) + aoff + m * 2048 + k * 1024); } while (0)
; #define PG8_LDB(dst, b, h) do { _Pragma("unroll") for (int n = 0; n < 2; ++n) _Pragma("unroll") for (int k = 0; k < 2; ++k) dst[n][k] = *(const PG8_LAS bf16x8*)(lds + PG8_SB(b, h) + boff + n * 2048 + k * 1024); } while (0)
; #define PG8_MMA(ai, bj, At, Bt) do { __builtin_amdgcn_s_setprio(1); _Pragma("unroll") for (int m = 0; m < 4; ++m) _Pragma("unroll") for (int n = 0; n < 2; ++n) _Pragma("unroll") for (int k = 0; k < 2; ++k) \
;         acc[ai][bj][m][n] = __builtin_amdgcn_mfma_f32_16x16x32_bf16(Bt[n][k], At[m][k], acc[ai][bj][m][n], 0, 0, 0); __builtin_amdgcn_s_setprio(0); } while (0)
; #define PG8_WAIT_L(n) asm volatile("s_waitcnt lgkmcnt(" #n ")" ::: "memory")
; #define PG8_BAR __builtin_amdgcn_s_barrier()
; #define PG8_SCHED __builtin_amdgcn_sched_barrier(0)
; template <class Epi, class Sched>
; __device__ __forceinline__ void gemm_phase(PG8_LAS unsigned char* lds, const Gemm g, const Sched& S, const Epi& E) {
;     ...
;             PG8_LDB(B0, 0, 0); PG8_SCHED; PG8_LDA(At, 0, 0); PG8_STAGE(PG8_SA(1, 1), a1 + hstep, voffA);
;             PG8_WAIT_L(8); PG8_BAR; PG8_WAIT_L(0); PG8_MMA(0, 0, At, B0); PG8_BAR; PG8_SCHED;
;             PG8_LDB(B1, 0, 1); PG8_STAGE(PG8_SB(0, 0), b2, voffB);
;             PG8_BAR; PG8_WAIT_L(0); PG8_MMA(0, 1, At, B1); PG8_BAR;
;             PG8_LDA(At, 0, 1); PG8_STAGE(PG8_SA(0, 0), a2, voffA);
;             PG8_BAR; PG8_WAIT_L(0); PG8_MMA(1, 0, At, B0); PG8_BAR; PG8_SCHED;
.LBB0_619:
	ds_read_b128 v[128:131], v175
	ds_read_b128 v[132:135], v175 offset:1024
	ds_read_b128 v[136:139], v175 offset:2048
	ds_read_b128 v[140:143], v175 offset:3072
	s_add_u32 s28, s26, 0xfffc0080
	s_addc_u32 s29, s27, -1
	s_cmp_eq_u32 s49, 12
	s_cselect_b32 s31, s19, s29
	s_cselect_b32 s30, s45, s28
	s_cselect_b32 s29, s17, s48
	s_cselect_b32 s28, s46, s47
	v_lshl_add_u64 v[170:171], s[26:27], 0, v[154:155]
	s_add_i32 m0, s4, 0xc000
	ds_read_b128 v[162:165], v177
	ds_read_b128 v[166:169], v177 offset:1024
	ds_read_b128 v[182:185], v177 offset:2048
	ds_read_b128 v[186:189], v177 offset:3072
	ds_read_b128 v[190:193], v177 offset:4096
	ds_read_b128 v[194:197], v177 offset:5120
	ds_read_b128 v[198:201], v177 offset:6144
	ds_read_b128 v[202:205], v177 offset:7168
	global_load_lds_dwordx4 v[170:171], off
	v_lshl_add_u64 v[170:171], s[26:27], 0, v[156:157]
	s_add_i32 m0, s4, 0xe000
	s_nop 0
	global_load_lds_dwordx4 v[170:171], off
	s_waitcnt lgkmcnt(8)
	s_barrier
	s_waitcnt lgkmcnt(0)
	s_setprio 1
	v_mfma_f32_16x16x32_bf16 v[124:127], v[128:131], v[162:165], v[124:127]
	v_mfma_f32_16x16x32_bf16 v[120:123], v[136:139], v[162:165], v[120:123]
	v_mfma_f32_16x16x32_bf16 v[108:111], v[128:131], v[182:185], v[108:111]
	v_mfma_f32_16x16x32_bf16 v[104:107], v[136:139], v[182:185], v[104:107]
	v_mfma_f32_16x16x32_bf16 v[92:95], v[128:131], v[190:193], v[92:95]
	v_mfma_f32_16x16x32_bf16 v[88:91], v[136:139], v[190:193], v[88:91]
	v_mfma_f32_16x16x32_bf16 v[76:79], v[128:131], v[198:201], v[76:79]
	v_mfma_f32_16x16x32_bf16 v[72:75], v[136:139], v[198:201], v[72:75]
	v_mfma_f32_16x16x32_bf16 v[124:127], v[132:135], v[166:169], v[124:127]
	v_mfma_f32_16x16x32_bf16 v[120:123], v[140:143], v[166:169], v[120:123]
	v_mfma_f32_16x16x32_bf16 v[108:111], v[132:135], v[186:189], v[108:111]
	v_mfma_f32_16x16x32_bf16 v[104:107], v[140:143], v[186:189], v[104:107]
	v_mfma_f32_16x16x32_bf16 v[92:95], v[132:135], v[194:197], v[92:95]
	v_mfma_f32_16x16x32_bf16 v[88:91], v[140:143], v[194:197], v[88:91]
	v_mfma_f32_16x16x32_bf16 v[76:79], v[132:135], v[202:205], v[76:79]
	v_mfma_f32_16x16x32_bf16 v[72:75], v[140:143], v[202:205], v[72:75]
	s_setprio 0
	s_barrier
	s_add_i32 s50, s39, s3
	v_lshl_add_u64 v[170:171], s[28:29], 0, v[146:147]
	s_mov_b32 m0, s50
	ds_read_b128 v[208:211], v180
	ds_read_b128 v[212:215], v180 offset:1024
	ds_read_b128 v[216:219], v180 offset:2048
	ds_read_b128 v[220:223], v180 offset:3072
	global_load_lds_dwordx4 v[170:171], off
	v_lshl_add_u64 v[224:225], s[28:29], 0, v[150:151]
	s_add_i32 m0, s50, 0x2000
	s_nop 0
	global_load_lds_dwordx4 v[224:225], off
	s_barrier
	s_waitcnt lgkmcnt(0)
	s_setprio 1
	v_mfma_f32_16x16x32_bf16 v[116:119], v[208:211], v[162:165], v[116:119]
	v_mfma_f32_16x16x32_bf16 v[112:115], v[216:219], v[162:165], v[112:115]
	v_mfma_f32_16x16x32_bf16 v[100:103], v[208:211], v[182:185], v[100:103]
	v_mfma_f32_16x16x32_bf16 v[96:99], v[216:219], v[182:185], v[96:99]
	v_mfma_f32_16x16x32_bf16 v[84:87], v[208:211], v[190:193], v[84:87]
	v_mfma_f32_16x16x32_bf16 v[80:83], v[216:219], v[190:193], v[80:83]
	v_mfma_f32_16x16x32_bf16 v[68:71], v[208:211], v[198:201], v[68:71]
	v_mfma_f32_16x16x32_bf16 v[64:67], v[216:219], v[198:201], v[64:67]
	v_mfma_f32_16x16x32_bf16 v[116:119], v[212:215], v[166:169], v[116:119]
	v_mfma_f32_16x16x32_bf16 v[112:115], v[220:223], v[166:169], v[112:115]
	v_mfma_f32_16x16x32_bf16 v[100:103], v[212:215], v[186:189], v[100:103]
	v_mfma_f32_16x16x32_bf16 v[96:99], v[220:223], v[186:189], v[96:99]
	v_mfma_f32_16x16x32_bf16 v[84:87], v[212:215], v[194:197], v[84:87]
	v_mfma_f32_16x16x32_bf16 v[80:83], v[220:223], v[194:197], v[80:83]
	v_mfma_f32_16x16x32_bf16 v[68:71], v[212:215], v[202:205], v[68:71]
	v_mfma_f32_16x16x32_bf16 v[64:67], v[220:223], v[202:205], v[64:67]
	s_setprio 0
	s_mov_b32 m0, s4
	v_lshl_add_u64 v[226:227], s[30:31], 0, v[144:145]
	s_barrier
	ds_read_b128 v[162:165], v177 offset:16384
	ds_read_b128 v[166:169], v177 offset:17408
	ds_read_b128 v[182:185], v177 offset:18432
	ds_read_b128 v[186:189], v177 offset:19456
	ds_read_b128 v[190:193], v177 offset:20480
	ds_read_b128 v[194:197], v177 offset:21504
	ds_read_b128 v[198:201], v177 offset:22528
	ds_read_b128 v[202:205], v177 offset:23552
	global_load_lds_dwordx4 v[226:227], off
	v_lshl_add_u64 v[228:229], s[30:31], 0, v[148:149]
	s_mov_b32 m0, s5
	s_nop 0
	global_load_lds_dwordx4 v[228:229], off
	s_barrier
	s_waitcnt lgkmcnt(0)
	s_setprio 1
	v_mfma_f32_16x16x32_bf16 v[60:63], v[128:131], v[162:165], v[60:63]
	v_mfma_f32_16x16x32_bf16 v[56:59], v[136:139], v[162:165], v[56:59]
	v_mfma_f32_16x16x32_bf16 v[44:47], v[128:131], v[182:185], v[44:47]
	v_mfma_f32_16x16x32_bf16 v[40:43], v[136:139], v[182:185], v[40:43]
	v_mfma_f32_16x16x32_bf16 v[28:31], v[128:131], v[190:193], v[28:31]
	v_mfma_f32_16x16x32_bf16 v[24:27], v[136:139], v[190:193], v[24:27]
	v_mfma_f32_16x16x32_bf16 v[12:15], v[128:131], v[198:201], v[12:15]
	v_mfma_f32_16x16x32_bf16 v[8:11], v[136:139], v[198:201], v[8:11]
	v_mfma_f32_16x16x32_bf16 v[60:63], v[132:135], v[166:169], v[60:63]
	v_mfma_f32_16x16x32_bf16 v[56:59], v[140:143], v[166:169], v[56:59]
	v_mfma_f32_16x16x32_bf16 v[44:47], v[132:135], v[186:189], v[44:47]
	v_mfma_f32_16x16x32_bf16 v[40:43], v[140:143], v[186:189], v[40:43]
	v_mfma_f32_16x16x32_bf16 v[28:31], v[132:135], v[194:197], v[28:31]
	v_mfma_f32_16x16x32_bf16 v[24:27], v[140:143], v[194:197], v[24:27]
	v_mfma_f32_16x16x32_bf16 v[12:15], v[132:135], v[202:205], v[12:15]
	v_mfma_f32_16x16x32_bf16 v[8:11], v[140:143], v[202:205], v[8:11]
	s_setprio 0
	s_barrier
; #define PG8_STAGE(bufoff, gbase, voff) do { _Pragma("unroll") for (int _i = 0; _i < 2; ++_i) \
;         __builtin_amdgcn_global_load_lds((const unsigned*)((const char*)(gbase) + (voff)[_i]), (PG8_LAS unsigned*)(lds + (bufoff) + ldsw + _i * 8192), 16, 0, 0); } while (0)
; #define PG8_LDA(dst, b, h) do { _Pragma("unroll") for (int m = 0; m < 4; ++m) _Pragma("unroll") for (int k = 0; k < 2; ++k) dst[m][k] = *(const PG8_LAS bf16x8*)(lds + PG8_SA(b, h) + aoff + m * 2048 + k * 1024); } while (0)
; #define PG8_LDB(dst, b, h) do { _Pragma("unroll") for (int n = 0; n < 2; ++n) _Pragma("unroll") for (int k = 0; k < 2; ++k) dst[n][k] = *(const PG8_LAS bf16x8*)(lds + PG8_SB(b, h) + boff + n * 2048 + k * 1024); } while (0)
; #define PG8_MMA(ai, bj, At, Bt) do { __builtin_amdgcn_s_setprio(1); _Pragma("unroll") for (int m = 0; m < 4; ++m) _Pragma("unroll") for (int n = 0; n < 2; ++n) _Pragma("unroll") for (int k = 0; k < 2; ++k) \
;         acc[ai][bj][m][n] = __builtin_amdgcn_mfma_f32_16x16x32_bf16(Bt[n][k], At[m][k], acc[ai][bj][m][n], 0, 0, 0); __builtin_amdgcn_s_setprio(0); } while (0)
; #define PG8_WAIT_V(n) asm volatile("s_waitcnt vmcnt(" #n ")" ::: "memory")
; #define PG8_WAIT_L(n) asm volatile("s_waitcnt lgkmcnt(" #n ")" ::: "memory")
; #define PG8_BAR __builtin_amdgcn_s_barrier()
; #define PG8_SCHED __builtin_amdgcn_sched_barrier(0)
; template <class Epi, class Sched>
; __device__ __forceinline__ void gemm_phase(PG8_LAS unsigned char* lds, const Gemm g, const Sched& S, const Epi& E) {
;     ...
;             PG8_STAGE(PG8_SB(0, 1), b2 + hstep, voffB);
;             PG8_WAIT_V(6); PG8_BAR; PG8_MMA(1, 1, At, B1); PG8_BAR;
;             PG8_LDB(B0, 1, 0); PG8_SCHED; PG8_LDA(At, 1, 0); PG8_STAGE(PG8_SA(0, 1), a2 + hstep, voffA);
;             PG8_WAIT_L(8); PG8_BAR; PG8_WAIT_L(0); PG8_MMA(0, 0, At, B0); PG8_BAR; PG8_SCHED;
;             PG8_LDB(B1, 1, 1); PG8_STAGE(PG8_SB(1, 0), b3, voffB);
;             PG8_BAR; PG8_WAIT_L(0); PG8_MMA(0, 1, At, B1); PG8_BAR;
;             PG8_LDA(At, 1, 1); PG8_STAGE(PG8_SA(1, 0), a3, voffA);
	s_add_u32 s50, s28, 0x40000
	s_addc_u32 s51, s29, 0
	s_add_i32 s60, s40, s3
	v_lshl_add_u64 v[128:129], s[50:51], 0, v[146:147]
	s_mov_b32 m0, s60
	s_nop 0
	global_load_lds_dwordx4 v[128:129], off
	v_lshl_add_u64 v[128:129], s[50:51], 0, v[150:151]
	s_add_i32 m0, s60, 0x2000
	s_nop 0
	global_load_lds_dwordx4 v[128:129], off
	s_waitcnt vmcnt(6)
	s_barrier
	s_setprio 1
	v_mfma_f32_16x16x32_bf16 v[52:55], v[208:211], v[162:165], v[52:55]
	v_mfma_f32_16x16x32_bf16 v[48:51], v[216:219], v[162:165], v[48:51]
	v_mfma_f32_16x16x32_bf16 v[36:39], v[208:211], v[182:185], v[36:39]
	v_mfma_f32_16x16x32_bf16 v[32:35], v[216:219], v[182:185], v[32:35]
	v_mfma_f32_16x16x32_bf16 v[20:23], v[208:211], v[190:193], v[20:23]
	v_mfma_f32_16x16x32_bf16 v[16:19], v[216:219], v[190:193], v[16:19]
	v_mfma_f32_16x16x32_bf16 v[4:7], v[208:211], v[198:201], v[4:7]
	v_mfma_f32_16x16x32_bf16 v[0:3], v[216:219], v[198:201], v[0:3]
	v_mfma_f32_16x16x32_bf16 v[52:55], v[212:215], v[166:169], v[52:55]
	v_mfma_f32_16x16x32_bf16 v[48:51], v[220:223], v[166:169], v[48:51]
	v_mfma_f32_16x16x32_bf16 v[36:39], v[212:215], v[186:189], v[36:39]
	v_mfma_f32_16x16x32_bf16 v[32:35], v[220:223], v[186:189], v[32:35]
	v_mfma_f32_16x16x32_bf16 v[20:23], v[212:215], v[194:197], v[20:23]
	v_mfma_f32_16x16x32_bf16 v[16:19], v[220:223], v[194:197], v[16:19]
	v_mfma_f32_16x16x32_bf16 v[4:7], v[212:215], v[202:205], v[4:7]
	v_mfma_f32_16x16x32_bf16 v[0:3], v[220:223], v[202:205], v[0:3]
	s_setprio 0
	s_add_i32 s50, 0, 0x18000
	v_add_u32_e32 v140, s50, v173
	s_barrier
	ds_read_b128 v[128:131], v140
	ds_read_b128 v[132:135], v140 offset:1024
	ds_read_b128 v[136:139], v140 offset:2048
	ds_read_b128 v[140:143], v140 offset:3072
	s_add_u32 s30, s30, 0x40000
	s_addc_u32 s31, s31, 0
	s_mov_b32 m0, s33
	v_lshl_add_u64 v[208:209], s[30:31], 0, v[144:145]
	ds_read_b128 v[162:165], v177 offset:32768
	ds_read_b128 v[166:169], v177 offset:33792
	ds_read_b128 v[182:185], v177 offset:34816
	ds_read_b128 v[186:189], v177 offset:35840
	ds_read_b128 v[190:193], v177 offset:36864
	ds_read_b128 v[194:197], v177 offset:37888
	ds_read_b128 v[198:201], v177 offset:38912
	ds_read_b128 v[202:205], v177 offset:39936
	global_load_lds_dwordx4 v[208:209], off
	v_lshl_add_u64 v[208:209], s[30:31], 0, v[148:149]
	s_mov_b32 m0, s34
	s_nop 0
	global_load_lds_dwordx4 v[208:209], off
	s_waitcnt lgkmcnt(8)
	s_barrier
	s_waitcnt lgkmcnt(0)
	s_setprio 1
	v_mfma_f32_16x16x32_bf16 v[124:127], v[128:131], v[162:165], v[124:127]
	v_mfma_f32_16x16x32_bf16 v[120:123], v[136:139], v[162:165], v[120:123]
	v_mfma_f32_16x16x32_bf16 v[108:111], v[128:131], v[182:185], v[108:111]
	v_mfma_f32_16x16x32_bf16 v[104:107], v[136:139], v[182:185], v[104:107]
	v_mfma_f32_16x16x32_bf16 v[92:95], v[128:131], v[190:193], v[92:95]
	v_mfma_f32_16x16x32_bf16 v[88:91], v[136:139], v[190:193], v[88:91]
	v_mfma_f32_16x16x32_bf16 v[76:79], v[128:131], v[198:201], v[76:79]
	v_mfma_f32_16x16x32_bf16 v[72:75], v[136:139], v[198:201], v[72:75]
	v_mfma_f32_16x16x32_bf16 v[124:127], v[132:135], v[166:169], v[124:127]
	v_mfma_f32_16x16x32_bf16 v[120:123], v[140:143], v[166:169], v[120:123]
	v_mfma_f32_16x16x32_bf16 v[108:111], v[132:135], v[186:189], v[108:111]
	v_mfma_f32_16x16x32_bf16 v[104:107], v[140:143], v[186:189], v[104:107]
	v_mfma_f32_16x16x32_bf16 v[92:95], v[132:135], v[194:197], v[92:95]
	v_mfma_f32_16x16x32_bf16 v[88:91], v[140:143], v[194:197], v[88:91]
	v_mfma_f32_16x16x32_bf16 v[76:79], v[132:135], v[202:205], v[76:79]
	v_mfma_f32_16x16x32_bf16 v[72:75], v[140:143], v[202:205], v[72:75]
	s_setprio 0
	s_barrier
	s_add_i32 s30, 0, 0x1c000
	s_add_i32 s31, s50, s3
	v_add_u32_e32 v152, s30, v173
	v_lshl_add_u64 v[170:171], v[170:171], 0, s[14:15]
	s_mov_b32 m0, s31
	ds_read_b128 v[208:211], v152
	ds_read_b128 v[212:215], v152 offset:1024
	ds_read_b128 v[216:219], v152 offset:2048
	ds_read_b128 v[220:223], v152 offset:3072
	global_load_lds_dwordx4 v[170:171], off
	v_lshl_add_u64 v[170:171], v[224:225], 0, s[14:15]
	s_add_i32 m0, s31, 0x2000
	s_nop 0
	global_load_lds_dwordx4 v[170:171], off
	s_barrier
	s_waitcnt lgkmcnt(0)
	s_setprio 1
	v_mfma_f32_16x16x32_bf16 v[116:119], v[208:211], v[162:165], v[116:119]
	v_mfma_f32_16x16x32_bf16 v[112:115], v[216:219], v[162:165], v[112:115]
	v_mfma_f32_16x16x32_bf16 v[100:103], v[208:211], v[182:185], v[100:103]
	v_mfma_f32_16x16x32_bf16 v[96:99], v[216:219], v[182:185], v[96:99]
	v_mfma_f32_16x16x32_bf16 v[84:87], v[208:211], v[190:193], v[84:87]
	v_mfma_f32_16x16x32_bf16 v[80:83], v[216:219], v[190:193], v[80:83]
	v_mfma_f32_16x16x32_bf16 v[68:71], v[208:211], v[198:201], v[68:71]
	v_mfma_f32_16x16x32_bf16 v[64:67], v[216:219], v[198:201], v[64:67]
	v_mfma_f32_16x16x32_bf16 v[116:119], v[212:215], v[166:169], v[116:119]
	v_mfma_f32_16x16x32_bf16 v[112:115], v[220:223], v[166:169], v[112:115]
	v_mfma_f32_16x16x32_bf16 v[100:103], v[212:215], v[186:189], v[100:103]
	v_mfma_f32_16x16x32_bf16 v[96:99], v[220:223], v[186:189], v[96:99]
	v_mfma_f32_16x16x32_bf16 v[84:87], v[212:215], v[194:197], v[84:87]
	v_mfma_f32_16x16x32_bf16 v[80:83], v[220:223], v[194:197], v[80:83]
	v_mfma_f32_16x16x32_bf16 v[68:71], v[212:215], v[202:205], v[68:71]
	v_mfma_f32_16x16x32_bf16 v[64:67], v[220:223], v[202:205], v[64:67]
	s_setprio 0
	s_mov_b32 m0, s37
	v_lshl_add_u64 v[170:171], v[226:227], 0, s[14:15]
	s_barrier
	ds_read_b128 v[162:165], v177 offset:49152
	ds_read_b128 v[166:169], v177 offset:50176
	ds_read_b128 v[182:185], v177 offset:51200
	ds_read_b128 v[186:189], v177 offset:52224
	ds_read_b128 v[190:193], v177 offset:53248
	ds_read_b128 v[194:197], v177 offset:54272
	ds_read_b128 v[198:201], v177 offset:55296
	ds_read_b128 v[202:205], v177 offset:56320
	global_load_lds_dwordx4 v[170:171], off
	v_lshl_add_u64 v[170:171], v[228:229], 0, s[14:15]
	s_mov_b32 m0, s38
	s_nop 0
	global_load_lds_dwordx4 v[170:171], off
	s_barrier
; #define PG8_STAGE(bufoff, gbase, voff) do { _Pragma("unroll") for (int _i = 0; _i < 2; ++_i) \
;         __builtin_amdgcn_global_load_lds((const unsigned*)((const char*)(gbase) + (voff)[_i]), (PG8_LAS unsigned*)(lds + (bufoff) + ldsw + _i * 8192), 16, 0, 0); } while (0)
; #define PG8_MMA(ai, bj, At, Bt) do { __builtin_amdgcn_s_setprio(1); _Pragma("unroll") for (int m = 0; m < 4; ++m) _Pragma("unroll") for (int n = 0; n < 2; ++n) _Pragma("unroll") for (int k = 0; k < 2; ++k) \
;         acc[ai][bj][m][n] = __builtin_amdgcn_mfma_f32_16x16x32_bf16(Bt[n][k], At[m][k], acc[ai][bj][m][n], 0, 0, 0); __builtin_amdgcn_s_setprio(0); } while (0)
; #define PG8_WAIT_V(n) asm volatile("s_waitcnt vmcnt(" #n ")" ::: "memory")
; #define PG8_WAIT_L(n) asm volatile("s_waitcnt lgkmcnt(" #n ")" ::: "memory")
; #define PG8_BAR __builtin_amdgcn_s_barrier()
; #define PG8_SCHED __builtin_amdgcn_sched_barrier(0)
; template <class Epi, class Sched>
; __device__ __forceinline__ void gemm_phase(PG8_LAS unsigned char* lds, const Gemm g, const Sched& S, const Epi& E) {
;     ...
;             PG8_BAR; PG8_WAIT_L(0); PG8_MMA(1, 0, At, B0); PG8_BAR; PG8_SCHED;
;             PG8_STAGE(PG8_SB(1, 1), b3 + hstep, voffB);
;             PG8_WAIT_V(6); PG8_BAR; PG8_MMA(1, 1, At, B1); PG8_BAR;
;     __device__ __forceinline__ void operator()(const f32x4 (&acc)[2][2][4][2], const Unit& u, int wr, int wc, int fr, int fq, const float (&epre)[1]) const {
;         const int row0 = u.pm * 256 + wr * 64 + fr, col0 = u.pn * 256 + wc * 32 + 8 * fq;
; #pragma unroll
;         for (int ai = 0; ai < 2; ++ai) {
;             float ssv[4];
;             f32x4 bv[4][2][2];
; #pragma unroll
;             for (int m = 0; m < 4; ++m) { const int row = row0 + ai * 128 + m * 16;
; #pragma unroll
;                 for (int bj = 0; bj < 2; ++bj) {
;                     if (BASEBF) { unpack8(*(const u32x4*)(HB + (size_t)row * DM + col0 + bj * 128), bv[m][bj][0], bv[m][bj][1]); }
;                     else { const float* bp = (row < MP ? base0 + (size_t)row * DM : base1 + (size_t)(row - MP) * DM) + col0 + bj * 128; bv[m][bj][0] = __builtin_nontemporal_load((const f32x4*)bp); bv[m][bj][1] = __builtin_nontemporal_load((const f32x4*)(bp + 4)); } } }
	s_waitcnt lgkmcnt(0)
	s_setprio 1
	v_mfma_f32_16x16x32_bf16 v[60:63], v[128:131], v[162:165], v[60:63]
	v_mfma_f32_16x16x32_bf16 v[56:59], v[136:139], v[162:165], v[56:59]
	v_mfma_f32_16x16x32_bf16 v[44:47], v[128:131], v[182:185], v[44:47]
	v_mfma_f32_16x16x32_bf16 v[40:43], v[136:139], v[182:185], v[40:43]
	v_mfma_f32_16x16x32_bf16 v[28:31], v[128:131], v[190:193], v[28:31]
	v_mfma_f32_16x16x32_bf16 v[24:27], v[136:139], v[190:193], v[24:27]
	v_mfma_f32_16x16x32_bf16 v[12:15], v[128:131], v[198:201], v[12:15]
	v_mfma_f32_16x16x32_bf16 v[8:11], v[136:139], v[198:201], v[8:11]
	v_mfma_f32_16x16x32_bf16 v[60:63], v[132:135], v[166:169], v[60:63]
	v_mfma_f32_16x16x32_bf16 v[56:59], v[140:143], v[166:169], v[56:59]
	v_mfma_f32_16x16x32_bf16 v[44:47], v[132:135], v[186:189], v[44:47]
	v_mfma_f32_16x16x32_bf16 v[40:43], v[140:143], v[186:189], v[40:43]
	v_mfma_f32_16x16x32_bf16 v[28:31], v[132:135], v[194:197], v[28:31]
	v_mfma_f32_16x16x32_bf16 v[24:27], v[140:143], v[194:197], v[24:27]
	v_mfma_f32_16x16x32_bf16 v[12:15], v[132:135], v[202:205], v[12:15]
	v_mfma_f32_16x16x32_bf16 v[8:11], v[140:143], v[202:205], v[8:11]
	s_setprio 0
	s_barrier
	s_add_u32 s28, s28, 0x40080
	s_addc_u32 s29, s29, 0
	s_add_i32 s30, s30, s3
	v_lshl_add_u64 v[128:129], s[28:29], 0, v[146:147]
	s_mov_b32 m0, s30
	s_nop 0
	global_load_lds_dwordx4 v[128:129], off
	v_lshl_add_u64 v[128:129], s[28:29], 0, v[150:151]
	s_add_i32 m0, s30, 0x2000
	s_nop 0
	global_load_lds_dwordx4 v[128:129], off
	s_waitcnt vmcnt(6)
	s_barrier
	s_setprio 1
	v_mfma_f32_16x16x32_bf16 v[52:55], v[208:211], v[162:165], v[52:55]
	v_mfma_f32_16x16x32_bf16 v[48:51], v[216:219], v[162:165], v[48:51]
	v_mfma_f32_16x16x32_bf16 v[36:39], v[208:211], v[182:185], v[36:39]
	v_mfma_f32_16x16x32_bf16 v[32:35], v[216:219], v[182:185], v[32:35]
	v_mfma_f32_16x16x32_bf16 v[20:23], v[208:211], v[190:193], v[20:23]
	v_mfma_f32_16x16x32_bf16 v[16:19], v[216:219], v[190:193], v[16:19]
	v_mfma_f32_16x16x32_bf16 v[4:7], v[208:211], v[198:201], v[4:7]
	v_mfma_f32_16x16x32_bf16 v[0:3], v[216:219], v[198:201], v[0:3]
	v_mfma_f32_16x16x32_bf16 v[52:55], v[212:215], v[166:169], v[52:55]
	v_mfma_f32_16x16x32_bf16 v[48:51], v[220:223], v[166:169], v[48:51]
	v_mfma_f32_16x16x32_bf16 v[36:39], v[212:215], v[186:189], v[36:39]
	v_mfma_f32_16x16x32_bf16 v[32:35], v[220:223], v[186:189], v[32:35]
	v_mfma_f32_16x16x32_bf16 v[20:23], v[212:215], v[194:197], v[20:23]
	v_mfma_f32_16x16x32_bf16 v[16:19], v[220:223], v[194:197], v[16:19]
	v_mfma_f32_16x16x32_bf16 v[4:7], v[212:215], v[202:205], v[4:7]
	v_mfma_f32_16x16x32_bf16 v[0:3], v[220:223], v[202:205], v[0:3]
	s_setprio 0
	s_add_i32 s49, s49, 2
	s_add_u32 s26, s26, 0x100
	s_addc_u32 s27, s27, 0
	s_add_u32 s47, s47, 0x100
	s_addc_u32 s48, s48, 0
	s_cmp_gt_u32 s49, 13
	s_barrier
	s_cbranch_scc0 .LBB0_619
	v_lshl_add_u32 v164, s24, 8, v172
	v_ashrrev_i32_e32 v165, 31, v164
	v_add_u32_e32 v152, 0xffffc000, v164
	v_readlane_b32 s48, v247, 0
	v_lshl_or_b32 v128, s25, 8, v174
	v_lshlrev_b64 v[130:131], 12, v[152:153]
	v_readlane_b32 s49, v247, 1
	v_readlane_b32 s50, v247, 2
	v_readlane_b32 s51, v247, 3
	v_lshlrev_b64 v[132:133], 12, v[164:165]
	v_ashrrev_i32_e32 v129, 31, v128
	v_lshl_add_u64 v[130:131], s[50:51], 0, v[130:131]
	v_lshl_add_u64 v[132:133], s[48:49], 0, v[132:133]
	v_cmp_gt_i32_e32 vcc, s36, v164
	v_lshlrev_b64 v[166:167], 2, v[128:129]
	v_or_b32_e32 v232, 16, v164
	v_cndmask_b32_e32 v131, v131, v133, vcc
	v_cndmask_b32_e32 v130, v130, v132, vcc
	v_lshl_add_u64 v[130:131], v[130:131], 0, v[166:167]
	global_load_dwordx4 v[182:185], v[130:131], off nt
	global_load_dwordx4 v[186:189], v[130:131], off offset:16 nt
	global_load_dwordx4 v[190:193], v[130:131], off offset:512 nt
	global_load_dwordx4 v[194:197], v[130:131], off offset:528 nt
	v_add_u32_e32 v152, 0xffffc010, v164
	v_ashrrev_i32_e32 v233, 31, v232
	v_lshlrev_b64 v[130:131], 12, v[152:153]
	v_lshlrev_b64 v[132:133], 12, v[232:233]
	v_lshl_add_u64 v[130:131], s[50:51], 0, v[130:131]
	v_lshl_add_u64 v[132:133], s[48:49], 0, v[132:133]
	v_cmp_gt_i32_e32 vcc, s36, v232
	v_or_b32_e32 v170, 32, v164
	v_ashrrev_i32_e32 v171, 31, v170
	v_cndmask_b32_e32 v131, v131, v133, vcc
	v_cndmask_b32_e32 v130, v130, v132, vcc
	v_lshl_add_u64 v[130:131], v[130:131], 0, v[166:167]
	global_load_dwordx4 v[198:201], v[130:131], off nt
	global_load_dwordx4 v[202:205], v[130:131], off offset:16 nt
	global_load_dwordx4 v[208:211], v[130:131], off offset:528 nt
	global_load_dwordx4 v[212:215], v[130:131], off offset:512 nt
	v_lshlrev_b64 v[132:133], 11, v[164:165]
	v_add_u32_e32 v152, 0xffffc020, v164
	v_lshlrev_b64 v[162:163], 1, v[128:129]
	v_lshlrev_b64 v[128:129], 12, v[170:171]
	v_lshl_add_u64 v[132:133], s[84:85], 0, v[132:133]
	v_lshlrev_b64 v[136:137], 12, v[152:153]
	v_lshl_add_u64 v[128:129], s[48:49], 0, v[128:129]
	v_lshl_add_u64 v[234:235], v[132:133], 0, v[162:163]
	v_lshl_add_u64 v[132:133], s[50:51], 0, v[136:137]
	v_cmp_gt_i32_e32 vcc, s36, v170
	v_or_b32_e32 v168, 48, v164
	v_ashrrev_i32_e32 v169, 31, v168
	v_cndmask_b32_e32 v129, v133, v129, vcc
	v_cndmask_b32_e32 v128, v132, v128, vcc
	v_lshl_add_u64 v[128:129], v[128:129], 0, v[166:167]
	global_load_dwordx4 v[216:219], v[128:129], off offset:16 nt
	global_load_dwordx4 v[220:223], v[128:129], off nt
	global_load_dwordx4 v[224:227], v[128:129], off offset:528 nt
	global_load_dwordx4 v[228:231], v[128:129], off offset:512 nt
	v_add_u32_e32 v152, 0xffffc030, v164
	v_lshlrev_b64 v[134:135], 12, v[168:169]
	v_lshlrev_b64 v[136:137], 12, v[152:153]
	v_lshl_add_u64 v[134:135], s[48:49], 0, v[134:135]
	v_lshl_add_u64 v[130:131], s[50:51], 0, v[136:137]
	v_cmp_gt_i32_e32 vcc, s36, v168
	v_readlane_b32 s52, v247, 4
	v_readlane_b32 s53, v247, 5
	v_cndmask_b32_e32 v131, v131, v135, vcc
	v_cndmask_b32_e32 v130, v130, v134, vcc
	v_lshl_add_u64 v[132:133], v[130:131], 0, v[166:167]
	global_load_dwordx4 v[136:139], v[132:133], off offset:16 nt
	global_load_dwordx4 v[140:143], v[132:133], off nt
	global_load_dwordx4 v[128:131], v[132:133], off offset:528 nt
	s_nop 0
	global_load_dwordx4 v[132:135], v[132:133], off offset:512 nt
	v_readlane_b32 s54, v247, 6
	v_readlane_b32 s55, v247, 7
	v_readlane_b32 s56, v247, 8
	v_readlane_b32 s57, v247, 9
	v_readlane_b32 s58, v247, 10
	v_readlane_b32 s59, v247, 11
	v_readlane_b32 s60, v247, 12
	v_readlane_b32 s61, v247, 13
	v_readlane_b32 s62, v247, 14
	v_readlane_b32 s63, v247, 15
	s_waitcnt vmcnt(0)
; __device__ __forceinline__ unsigned cvt_pk_bf16(float lo, float hi) { unsigned r; asm volatile("v_cvt_pk_bf16_f32 %0, %1, %2" : "=v"(r) : "v"(lo), "v"(hi)); return r; }
;     __device__ __forceinline__ void operator()(const f32x4 (&acc)[2][2][4][2], const Unit& u, int wr, int wc, int fr, int fq, const float (&epre)[1]) const {
;     ...
;             for (int m = 0; m < 4; ++m) { const int row = row0 + ai * 128 + m * 16;
;                 float ss = 0.f;
; #pragma unroll
;                 for (int bj = 0; bj < 2; ++bj) { const f32x4 h0 = bv[m][bj][0] + acc[ai][bj][m][0], h1 = bv[m][bj][1] + acc[ai][bj][m][1];
;                     u32x4 w; w.x = cvt_pk_bf16(h0[0], h0[1]); w.y = cvt_pk_bf16(h0[2], h0[3]); w.z = cvt_pk_bf16(h1[0], h1[1]); w.w = cvt_pk_bf16(h1[2], h1[3]);
;                     *(u32x4*)(HBo + (size_t)row * DM + col0 + bj * 128) = w;
;                     ss += (h0[0] * h0[0] + h0[1] * h0[1]) + (h0[2] * h0[2] + h0[3] * h0[3]) + (h1[0] * h1[0] + h1[1] * h1[1]) + (h1[2] * h1[2] + h1[3] * h1[3]); }
;                 ssv[m] = ss;
;             }
; #pragma unroll
;             for (int m = 0; m < 4; ++m) ssv[m] += __shfl_xor(ssv[m], 16);
; #pragma unroll
;             for (int m = 0; m < 4; ++m) ssv[m] += __shfl_xor(ssv[m], 32);
	v_pk_add_f32 v[126:127], v[126:127], v[184:185]
	v_pk_add_f32 v[124:125], v[124:125], v[182:183]
	v_pk_add_f32 v[120:121], v[120:121], v[186:187]
	v_pk_add_f32 v[184:185], v[112:113], v[194:195]
	v_cvt_pk_bf16_f32 v112, v124, v125
	v_cvt_pk_bf16_f32 v113, v126, v127
	v_mul_f32_e32 v125, v125, v125
	v_mul_f32_e32 v127, v127, v127
	v_pk_add_f32 v[122:123], v[122:123], v[188:189]
	v_pk_add_f32 v[182:183], v[114:115], v[196:197]
	v_cvt_pk_bf16_f32 v114, v120, v121
	v_mul_f32_e32 v121, v121, v121
	v_fmac_f32_e32 v125, v124, v124
	v_fmac_f32_e32 v127, v126, v126
	v_cvt_pk_bf16_f32 v115, v122, v123
	v_mul_f32_e32 v123, v123, v123
	global_store_dwordx4 v[234:235], v[112:115], off
	v_fmac_f32_e32 v121, v120, v120
	v_fmac_f32_e32 v123, v122, v122
	v_add_f32_e32 v113, v125, v127
	v_add_f32_e32 v113, v113, v121
	v_pk_add_f32 v[118:119], v[118:119], v[192:193]
	v_pk_add_f32 v[116:117], v[116:117], v[190:191]
	v_add_f32_e32 v120, v123, v113
	v_cvt_pk_bf16_f32 v112, v116, v117
	v_cvt_pk_bf16_f32 v113, v118, v119
	v_cvt_pk_bf16_f32 v114, v184, v185
	v_cvt_pk_bf16_f32 v115, v182, v183
	global_store_dwordx4 v[234:235], v[112:115], off offset:256
	v_pk_add_f32 v[110:111], v[110:111], v[200:201]
	v_pk_add_f32 v[108:109], v[108:109], v[198:199]
	v_mul_f32_e32 v112, v117, v117
	v_mul_f32_e32 v113, v119, v119
	v_fmac_f32_e32 v112, v116, v116
	v_fmac_f32_e32 v113, v118, v118
	v_add_f32_e32 v112, v112, v113
	v_mul_f32_e32 v113, v185, v185
	v_fmac_f32_e32 v113, v184, v184
	v_add_f32_e32 v112, v112, v113
	v_mul_f32_e32 v113, v183, v183
	v_fmac_f32_e32 v113, v182, v182
	v_add_f32_e32 v112, v113, v112
	v_add_f32_e32 v118, v120, v112
	v_lshlrev_b64 v[112:113], 11, v[232:233]
	v_lshl_add_u64 v[112:113], s[84:85], 0, v[112:113]
	v_pk_add_f32 v[116:117], v[104:105], v[202:203]
	v_cvt_pk_bf16_f32 v104, v108, v109
	v_cvt_pk_bf16_f32 v105, v110, v111
	v_lshl_add_u64 v[112:113], v[112:113], 0, v[162:163]
	v_pk_add_f32 v[114:115], v[106:107], v[204:205]
	v_cvt_pk_bf16_f32 v106, v116, v117
	v_pk_add_f32 v[102:103], v[102:103], v[214:215]
	v_cvt_pk_bf16_f32 v107, v114, v115
	global_store_dwordx4 v[112:113], v[104:107], off
	v_pk_add_f32 v[100:101], v[100:101], v[212:213]
	v_pk_add_f32 v[94:95], v[94:95], v[222:223]
	v_mul_f32_e32 v104, v109, v109
	v_mul_f32_e32 v105, v111, v111
	v_fmac_f32_e32 v104, v108, v108
	v_fmac_f32_e32 v105, v110, v110
	v_add_f32_e32 v104, v104, v105
	v_mul_f32_e32 v105, v117, v117
	v_fmac_f32_e32 v105, v116, v116
	v_add_f32_e32 v104, v104, v105
	v_mul_f32_e32 v105, v115, v115
	v_fmac_f32_e32 v105, v114, v114
	v_pk_add_f32 v[106:107], v[96:97], v[208:209]
	v_cvt_pk_bf16_f32 v96, v100, v101
	v_cvt_pk_bf16_f32 v97, v102, v103
	v_add_f32_e32 v108, v105, v104
	v_pk_add_f32 v[104:105], v[98:99], v[210:211]
	v_cvt_pk_bf16_f32 v98, v106, v107
	v_pk_add_f32 v[92:93], v[92:93], v[220:221]
	v_cvt_pk_bf16_f32 v99, v104, v105
	global_store_dwordx4 v[112:113], v[96:99], off offset:256
	v_pk_add_f32 v[86:87], v[86:87], v[230:231]
	v_pk_add_f32 v[84:85], v[84:85], v[228:229]
	v_mul_f32_e32 v96, v101, v101
	v_mul_f32_e32 v97, v103, v103
	v_fmac_f32_e32 v96, v100, v100
	v_fmac_f32_e32 v97, v102, v102
	v_add_f32_e32 v96, v96, v97
	v_mul_f32_e32 v97, v107, v107
	v_fmac_f32_e32 v97, v106, v106
	v_add_f32_e32 v96, v96, v97
	v_mul_f32_e32 v97, v105, v105
	v_fmac_f32_e32 v97, v104, v104
	v_add_f32_e32 v96, v97, v96
	v_add_f32_e32 v102, v108, v96
	v_lshlrev_b64 v[96:97], 11, v[170:171]
	v_lshl_add_u64 v[96:97], s[84:85], 0, v[96:97]
	v_pk_add_f32 v[100:101], v[88:89], v[216:217]
	v_cvt_pk_bf16_f32 v88, v92, v93
	v_cvt_pk_bf16_f32 v89, v94, v95
	v_lshl_add_u64 v[96:97], v[96:97], 0, v[162:163]
	v_pk_add_f32 v[98:99], v[90:91], v[218:219]
	v_cvt_pk_bf16_f32 v90, v100, v101
	v_pk_add_f32 v[78:79], v[78:79], v[142:143]
	v_cvt_pk_bf16_f32 v91, v98, v99
	global_store_dwordx4 v[96:97], v[88:91], off
	v_pk_add_f32 v[76:77], v[76:77], v[140:141]
	v_pk_add_f32 v[70:71], v[70:71], v[134:135]
	v_mul_f32_e32 v88, v93, v93
	v_mul_f32_e32 v89, v95, v95
	v_fmac_f32_e32 v88, v92, v92
	v_fmac_f32_e32 v89, v94, v94
	v_add_f32_e32 v88, v88, v89
	v_mul_f32_e32 v89, v101, v101
	v_fmac_f32_e32 v89, v100, v100
	v_add_f32_e32 v88, v88, v89
	v_mul_f32_e32 v89, v99, v99
	v_fmac_f32_e32 v89, v98, v98
	v_pk_add_f32 v[90:91], v[80:81], v[224:225]
	v_cvt_pk_bf16_f32 v80, v84, v85
	v_cvt_pk_bf16_f32 v81, v86, v87
	v_add_f32_e32 v92, v89, v88
	v_pk_add_f32 v[88:89], v[82:83], v[226:227]
	v_cvt_pk_bf16_f32 v82, v90, v91
	v_pk_add_f32 v[68:69], v[68:69], v[132:133]
	v_cvt_pk_bf16_f32 v83, v88, v89
	global_store_dwordx4 v[96:97], v[80:83], off offset:256
	s_nop 1
	v_mul_f32_e32 v80, v85, v85
	v_mul_f32_e32 v81, v87, v87
	v_fmac_f32_e32 v80, v84, v84
	v_fmac_f32_e32 v81, v86, v86
	v_add_f32_e32 v80, v80, v81
	v_mul_f32_e32 v81, v91, v91
	v_fmac_f32_e32 v81, v90, v90
	v_add_f32_e32 v80, v80, v81
	v_mul_f32_e32 v81, v89, v89
	v_fmac_f32_e32 v81, v88, v88
	v_add_f32_e32 v80, v81, v80
	v_add_f32_e32 v87, v92, v80
	v_lshlrev_b64 v[80:81], 11, v[168:169]
	v_lshl_add_u64 v[80:81], s[84:85], 0, v[80:81]
	v_pk_add_f32 v[82:83], v[74:75], v[138:139]
	v_pk_add_f32 v[84:85], v[72:73], v[136:137]
	v_cvt_pk_bf16_f32 v72, v76, v77
	v_cvt_pk_bf16_f32 v73, v78, v79
	v_lshl_add_u64 v[80:81], v[80:81], 0, v[162:163]
	v_cvt_pk_bf16_f32 v74, v84, v85
	v_cvt_pk_bf16_f32 v75, v82, v83
	global_store_dwordx4 v[80:81], v[72:75], off
	s_nop 1
	v_mul_f32_e32 v72, v77, v77
	v_mul_f32_e32 v73, v79, v79
	v_pk_add_f32 v[74:75], v[64:65], v[128:129]
	v_mul_f32_e32 v64, v69, v69
	v_mul_f32_e32 v65, v71, v71
	v_fmac_f32_e32 v72, v76, v76
	v_fmac_f32_e32 v73, v78, v78
	v_fmac_f32_e32 v64, v68, v68
	v_fmac_f32_e32 v65, v70, v70
	v_add_f32_e32 v72, v72, v73
	v_mul_f32_e32 v73, v85, v85
	v_add_f32_e32 v64, v64, v65
	v_mul_f32_e32 v65, v75, v75
	v_fmac_f32_e32 v73, v84, v84
	v_pk_add_f32 v[76:77], v[66:67], v[130:131]
	v_fmac_f32_e32 v65, v74, v74
	v_add_f32_e32 v72, v72, v73
	v_mul_f32_e32 v73, v83, v83
	v_add_f32_e32 v64, v64, v65
	v_mul_f32_e32 v65, v77, v77
	v_fmac_f32_e32 v73, v82, v82
	v_fmac_f32_e32 v65, v76, v76
	v_add_f32_e32 v73, v73, v72
	v_add_f32_e32 v64, v65, v64
	v_and_b32_e32 v65, 64, v181
	v_cvt_pk_bf16_f32 v72, v68, v69
	v_add_f32_e32 v67, v73, v64
	v_xor_b32_e32 v64, 16, v181
	v_add_u32_e32 v68, 64, v65
	v_cmp_lt_i32_e32 vcc, v64, v68
	v_cvt_pk_bf16_f32 v73, v70, v71
	v_cvt_pk_bf16_f32 v74, v74, v75
	v_cvt_pk_bf16_f32 v75, v76, v77
	global_store_dwordx4 v[80:81], v[72:75], off offset:256
	v_lshl_add_u64 v[80:81], v[164:165], 2, s[10:11]
	v_cndmask_b32_e32 v64, v181, v64, vcc
	v_lshlrev_b32_e32 v86, 2, v64
	ds_bpermute_b32 v69, v86, v67
	ds_bpermute_b32 v64, v86, v118
	ds_bpermute_b32 v65, v86, v102
	ds_bpermute_b32 v66, v86, v87
	s_waitcnt lgkmcnt(0)
;     __device__ __forceinline__ void operator()(const f32x4 (&acc)[2][2][4][2], const Unit& u, int wr, int wc, int fr, int fq, const float (&epre)[1]) const {
;     ...
;             for (int m = 0; m < 4; ++m) ssv[m] += __shfl_xor(ssv[m], 16);
; #pragma unroll
;             for (int m = 0; m < 4; ++m) ssv[m] += __shfl_xor(ssv[m], 32);
;             if (fq == 0) {
; #pragma unroll
;                 for (int m = 0; m < 4; ++m) atomicAdd(sumsq + row0 + ai * 128 + m * 16, ssv[m]); }
	v_add_f32_e32 v67, v67, v69
	v_xor_b32_e32 v69, 32, v181
	v_cmp_lt_i32_e32 vcc, v69, v68
	v_add_f32_e32 v64, v118, v64
	v_add_f32_e32 v65, v102, v65
	v_cndmask_b32_e32 v68, v181, v69, vcc
	v_add_f32_e32 v66, v87, v66
	v_lshlrev_b32_e32 v87, 2, v68
	ds_bpermute_b32 v68, v87, v64
	ds_bpermute_b32 v69, v87, v65
	ds_bpermute_b32 v70, v87, v66
	ds_bpermute_b32 v71, v87, v67
	s_and_saveexec_b64 s[24:25], s[6:7]
	s_cbranch_execz .LBB0_622
	s_waitcnt lgkmcnt(3)
	v_add_f32_e32 v64, v64, v68
	s_waitcnt lgkmcnt(0)
	v_add_f32_e32 v67, v67, v71
	v_add_f32_e32 v66, v66, v70
	v_add_f32_e32 v65, v65, v69
	global_atomic_add_f32 v[80:81], v64, off
	global_atomic_add_f32 v[80:81], v65, off offset:64
	global_atomic_add_f32 v[80:81], v66, off offset:128
	global_atomic_add_f32 v[80:81], v67, off offset:192

; #define PG8_STAGE(bufoff, gbase, voff) do { _Pragma("unroll") for (int _i = 0; _i < 2; ++_i) \
;         __builtin_amdgcn_global_load_lds((const unsigned*)((const char*)(gbase) + (voff)[_i]), (PG8_LAS unsigned*)(lds + (bufoff) + ldsw + _i * 8192), 16, 0, 0); } while (0)
; #define PG8_LDA(dst, b, h) do { _Pragma("unroll") for (int m = 0; m < 4; ++m) _Pragma("unroll") for (int k = 0; k < 2; ++k) dst[m][k] = *(const PG8_LAS bf16x8*)(lds + PG8_SA(b, h) + aoff + m * 2048 + k * 1024); } while (0)
; #define PG8_LDB(dst, b, h) do { _Pragma("unroll") for (int n = 0; n < 2; ++n) _Pragma("unroll") for (int k = 0; k < 2; ++k) dst[n][k] = *(const PG8_LAS bf16x8*)(lds + PG8_SB(b, h) + boff + n * 2048 + k * 1024); } while (0)
; #define PG8_MMA(ai, bj, At, Bt) do { __builtin_amdgcn_s_setprio(1); _Pragma("unroll") for (int m = 0; m < 4; ++m) _Pragma("unroll") for (int n = 0; n < 2; ++n) _Pragma("unroll") for (int k = 0; k < 2; ++k) \
;         acc[ai][bj][m][n] = __builtin_amdgcn_mfma_f32_16x16x32_bf16(Bt[n][k], At[m][k], acc[ai][bj][m][n], 0, 0, 0); __builtin_amdgcn_s_setprio(0); } while (0)
; #define PG8_WAIT_L(n) asm volatile("s_waitcnt lgkmcnt(" #n ")" ::: "memory")
; #define PG8_BAR __builtin_amdgcn_s_barrier()
; #define PG8_SCHED __builtin_amdgcn_sched_barrier(0)
; template <class Epi, class Sched>
; __device__ __forceinline__ void gemm_phase(PG8_LAS unsigned char* lds, const Gemm g, const Sched& S, const Epi& E) {
;     ...
;             PG8_LDB(B0, 0, 0); PG8_SCHED; PG8_LDA(At, 0, 0); PG8_STAGE(PG8_SA(1, 1), a1 + hstep, voffA);
;             PG8_WAIT_L(8); PG8_BAR; PG8_WAIT_L(0); PG8_MMA(0, 0, At, B0); PG8_BAR; PG8_SCHED;
;             PG8_LDB(B1, 0, 1); PG8_STAGE(PG8_SB(0, 0), b2, voffB);
;             PG8_BAR; PG8_WAIT_L(0); PG8_MMA(0, 1, At, B1); PG8_BAR;
;             PG8_LDA(At, 0, 1); PG8_STAGE(PG8_SA(0, 0), a2, voffA);
;             PG8_BAR; PG8_WAIT_L(0); PG8_MMA(1, 0, At, B0); PG8_BAR; PG8_SCHED;
.LBB0_702:
	ds_read_b128 v[158:161], v146
	ds_read_b128 v[162:165], v146 offset:1024
	ds_read_b128 v[166:169], v146 offset:2048
	ds_read_b128 v[170:173], v146 offset:3072
	s_add_u32 s26, s24, 0xfffc0080
	s_addc_u32 s27, s25, -1
	s_cmp_eq_u32 s45, 12
	s_cselect_b32 s29, s13, s27
	s_cselect_b32 s28, s21, s26
	s_cselect_b32 s27, s9, s44
	s_cselect_b32 s26, s42, s43
	v_lshl_add_u64 v[174:175], s[24:25], 0, v[136:137]
	s_add_i32 m0, s5, 0xc000
	ds_read_b128 v[180:183], v147
	ds_read_b128 v[184:187], v147 offset:1024
	ds_read_b128 v[188:191], v147 offset:2048
	ds_read_b128 v[192:195], v147 offset:3072
	ds_read_b128 v[196:199], v147 offset:4096
	ds_read_b128 v[200:203], v147 offset:5120
	ds_read_b128 v[208:211], v147 offset:6144
	ds_read_b128 v[212:215], v147 offset:7168
	global_load_lds_dwordx4 v[174:175], off
	v_lshl_add_u64 v[174:175], s[24:25], 0, v[138:139]
	s_add_i32 m0, s5, 0xe000
	s_nop 0
	global_load_lds_dwordx4 v[174:175], off
	s_waitcnt lgkmcnt(8)
	s_barrier
	s_waitcnt lgkmcnt(0)
	s_setprio 1
	v_mfma_f32_16x16x32_bf16 v[124:127], v[158:161], v[180:183], v[124:127]
	v_mfma_f32_16x16x32_bf16 v[116:119], v[166:169], v[180:183], v[116:119]
	v_mfma_f32_16x16x32_bf16 v[108:111], v[158:161], v[188:191], v[108:111]
	v_mfma_f32_16x16x32_bf16 v[100:103], v[166:169], v[188:191], v[100:103]
	v_mfma_f32_16x16x32_bf16 v[92:95], v[158:161], v[196:199], v[92:95]
	v_mfma_f32_16x16x32_bf16 v[84:87], v[166:169], v[196:199], v[84:87]
	v_mfma_f32_16x16x32_bf16 v[76:79], v[158:161], v[208:211], v[76:79]
	v_mfma_f32_16x16x32_bf16 v[68:71], v[166:169], v[208:211], v[68:71]
	v_mfma_f32_16x16x32_bf16 v[124:127], v[162:165], v[184:187], v[124:127]
	v_mfma_f32_16x16x32_bf16 v[116:119], v[170:173], v[184:187], v[116:119]
	v_mfma_f32_16x16x32_bf16 v[108:111], v[162:165], v[192:195], v[108:111]
	v_mfma_f32_16x16x32_bf16 v[100:103], v[170:173], v[192:195], v[100:103]
	v_mfma_f32_16x16x32_bf16 v[92:95], v[162:165], v[200:203], v[92:95]
	v_mfma_f32_16x16x32_bf16 v[84:87], v[170:173], v[200:203], v[84:87]
	v_mfma_f32_16x16x32_bf16 v[76:79], v[162:165], v[212:215], v[76:79]
	v_mfma_f32_16x16x32_bf16 v[68:71], v[170:173], v[212:215], v[68:71]
	s_setprio 0
	s_barrier
	s_add_i32 s46, s38, s4
	v_lshl_add_u64 v[174:175], s[26:27], 0, v[130:131]
	s_mov_b32 m0, s46
	ds_read_b128 v[216:219], v148
	ds_read_b128 v[220:223], v148 offset:1024
	ds_read_b128 v[224:227], v148 offset:2048
	ds_read_b128 v[228:231], v148 offset:3072
	global_load_lds_dwordx4 v[174:175], off
	v_lshl_add_u64 v[204:205], s[26:27], 0, v[134:135]
	s_add_i32 m0, s46, 0x2000
	s_nop 0
	global_load_lds_dwordx4 v[204:205], off
	s_barrier
	s_waitcnt lgkmcnt(0)
	s_setprio 1
	v_mfma_f32_16x16x32_bf16 v[120:123], v[216:219], v[180:183], v[120:123]
	v_mfma_f32_16x16x32_bf16 v[112:115], v[224:227], v[180:183], v[112:115]
	v_mfma_f32_16x16x32_bf16 v[104:107], v[216:219], v[188:191], v[104:107]
	v_mfma_f32_16x16x32_bf16 v[96:99], v[224:227], v[188:191], v[96:99]
	v_mfma_f32_16x16x32_bf16 v[88:91], v[216:219], v[196:199], v[88:91]
	v_mfma_f32_16x16x32_bf16 v[80:83], v[224:227], v[196:199], v[80:83]
	v_mfma_f32_16x16x32_bf16 v[72:75], v[216:219], v[208:211], v[72:75]
	v_mfma_f32_16x16x32_bf16 v[64:67], v[224:227], v[208:211], v[64:67]
	v_mfma_f32_16x16x32_bf16 v[120:123], v[220:223], v[184:187], v[120:123]
	v_mfma_f32_16x16x32_bf16 v[112:115], v[228:231], v[184:187], v[112:115]
	v_mfma_f32_16x16x32_bf16 v[104:107], v[220:223], v[192:195], v[104:107]
	v_mfma_f32_16x16x32_bf16 v[96:99], v[228:231], v[192:195], v[96:99]
	v_mfma_f32_16x16x32_bf16 v[88:91], v[220:223], v[200:203], v[88:91]
	v_mfma_f32_16x16x32_bf16 v[80:83], v[228:231], v[200:203], v[80:83]
	v_mfma_f32_16x16x32_bf16 v[72:75], v[220:223], v[212:215], v[72:75]
	v_mfma_f32_16x16x32_bf16 v[64:67], v[228:231], v[212:215], v[64:67]
	s_setprio 0
	s_mov_b32 m0, s5
	v_lshl_add_u64 v[232:233], s[28:29], 0, v[128:129]
	s_barrier
	ds_read_b128 v[180:183], v147 offset:16384
	ds_read_b128 v[184:187], v147 offset:17408
	ds_read_b128 v[188:191], v147 offset:18432
	ds_read_b128 v[192:195], v147 offset:19456
	ds_read_b128 v[196:199], v147 offset:20480
	ds_read_b128 v[200:203], v147 offset:21504
	ds_read_b128 v[208:211], v147 offset:22528
	ds_read_b128 v[212:215], v147 offset:23552
	global_load_lds_dwordx4 v[232:233], off
	v_lshl_add_u64 v[234:235], s[28:29], 0, v[132:133]
	s_mov_b32 m0, s23
	s_nop 0
	global_load_lds_dwordx4 v[234:235], off
	s_barrier
	s_waitcnt lgkmcnt(0)
	s_setprio 1
	v_mfma_f32_16x16x32_bf16 v[60:63], v[158:161], v[180:183], v[60:63]
	v_mfma_f32_16x16x32_bf16 v[52:55], v[166:169], v[180:183], v[52:55]
	v_mfma_f32_16x16x32_bf16 v[44:47], v[158:161], v[188:191], v[44:47]
	v_mfma_f32_16x16x32_bf16 v[36:39], v[166:169], v[188:191], v[36:39]
	v_mfma_f32_16x16x32_bf16 v[28:31], v[158:161], v[196:199], v[28:31]
	v_mfma_f32_16x16x32_bf16 v[20:23], v[166:169], v[196:199], v[20:23]
	v_mfma_f32_16x16x32_bf16 v[12:15], v[158:161], v[208:211], v[12:15]
	v_mfma_f32_16x16x32_bf16 v[4:7], v[166:169], v[208:211], v[4:7]
	v_mfma_f32_16x16x32_bf16 v[60:63], v[162:165], v[184:187], v[60:63]
	v_mfma_f32_16x16x32_bf16 v[52:55], v[170:173], v[184:187], v[52:55]
	v_mfma_f32_16x16x32_bf16 v[44:47], v[162:165], v[192:195], v[44:47]
	v_mfma_f32_16x16x32_bf16 v[36:39], v[170:173], v[192:195], v[36:39]
	v_mfma_f32_16x16x32_bf16 v[28:31], v[162:165], v[200:203], v[28:31]
	v_mfma_f32_16x16x32_bf16 v[20:23], v[170:173], v[200:203], v[20:23]
	v_mfma_f32_16x16x32_bf16 v[12:15], v[162:165], v[212:215], v[12:15]
	v_mfma_f32_16x16x32_bf16 v[4:7], v[170:173], v[212:215], v[4:7]
	s_setprio 0
	s_barrier
; #define PG8_STAGE(bufoff, gbase, voff) do { _Pragma("unroll") for (int _i = 0; _i < 2; ++_i) \
;         __builtin_amdgcn_global_load_lds((const unsigned*)((const char*)(gbase) + (voff)[_i]), (PG8_LAS unsigned*)(lds + (bufoff) + ldsw + _i * 8192), 16, 0, 0); } while (0)
; #define PG8_LDA(dst, b, h) do { _Pragma("unroll") for (int m = 0; m < 4; ++m) _Pragma("unroll") for (int k = 0; k < 2; ++k) dst[m][k] = *(const PG8_LAS bf16x8*)(lds + PG8_SA(b, h) + aoff + m * 2048 + k * 1024); } while (0)
; #define PG8_LDB(dst, b, h) do { _Pragma("unroll") for (int n = 0; n < 2; ++n) _Pragma("unroll") for (int k = 0; k < 2; ++k) dst[n][k] = *(const PG8_LAS bf16x8*)(lds + PG8_SB(b, h) + boff + n * 2048 + k * 1024); } while (0)
; #define PG8_MMA(ai, bj, At, Bt) do { __builtin_amdgcn_s_setprio(1); _Pragma("unroll") for (int m = 0; m < 4; ++m) _Pragma("unroll") for (int n = 0; n < 2; ++n) _Pragma("unroll") for (int k = 0; k < 2; ++k) \
;         acc[ai][bj][m][n] = __builtin_amdgcn_mfma_f32_16x16x32_bf16(Bt[n][k], At[m][k], acc[ai][bj][m][n], 0, 0, 0); __builtin_amdgcn_s_setprio(0); } while (0)
; #define PG8_WAIT_V(n) asm volatile("s_waitcnt vmcnt(" #n ")" ::: "memory")
; #define PG8_WAIT_L(n) asm volatile("s_waitcnt lgkmcnt(" #n ")" ::: "memory")
; #define PG8_BAR __builtin_amdgcn_s_barrier()
; #define PG8_SCHED __builtin_amdgcn_sched_barrier(0)
; template <class Epi, class Sched>
; __device__ __forceinline__ void gemm_phase(PG8_LAS unsigned char* lds, const Gemm g, const Sched& S, const Epi& E) {
;     ...
;             PG8_STAGE(PG8_SB(0, 1), b2 + hstep, voffB);
;             PG8_WAIT_V(6); PG8_BAR; PG8_MMA(1, 1, At, B1); PG8_BAR;
;             PG8_LDB(B0, 1, 0); PG8_SCHED; PG8_LDA(At, 1, 0); PG8_STAGE(PG8_SA(0, 1), a2 + hstep, voffA);
;             PG8_WAIT_L(8); PG8_BAR; PG8_WAIT_L(0); PG8_MMA(0, 0, At, B0); PG8_BAR; PG8_SCHED;
;             PG8_LDB(B1, 1, 1); PG8_STAGE(PG8_SB(1, 0), b3, voffB);
;             PG8_BAR; PG8_WAIT_L(0); PG8_MMA(0, 1, At, B1); PG8_BAR;
;             PG8_LDA(At, 1, 1); PG8_STAGE(PG8_SA(1, 0), a3, voffA);
	s_add_u32 s46, s26, 0x40000
	s_addc_u32 s47, s27, 0
	s_add_i32 s48, s39, s4
	v_lshl_add_u64 v[158:159], s[46:47], 0, v[130:131]
	s_mov_b32 m0, s48
	s_nop 0
	global_load_lds_dwordx4 v[158:159], off
	v_lshl_add_u64 v[158:159], s[46:47], 0, v[134:135]
	s_add_i32 m0, s48, 0x2000
	s_nop 0
	global_load_lds_dwordx4 v[158:159], off
	s_waitcnt vmcnt(6)
	s_barrier
	s_setprio 1
	v_mfma_f32_16x16x32_bf16 v[56:59], v[216:219], v[180:183], v[56:59]
	v_mfma_f32_16x16x32_bf16 v[48:51], v[224:227], v[180:183], v[48:51]
	v_mfma_f32_16x16x32_bf16 v[40:43], v[216:219], v[188:191], v[40:43]
	v_mfma_f32_16x16x32_bf16 v[32:35], v[224:227], v[188:191], v[32:35]
	v_mfma_f32_16x16x32_bf16 v[24:27], v[216:219], v[196:199], v[24:27]
	v_mfma_f32_16x16x32_bf16 v[16:19], v[224:227], v[196:199], v[16:19]
	v_mfma_f32_16x16x32_bf16 v[8:11], v[216:219], v[208:211], v[8:11]
	v_mfma_f32_16x16x32_bf16 v[0:3], v[224:227], v[208:211], v[0:3]
	v_mfma_f32_16x16x32_bf16 v[56:59], v[220:223], v[184:187], v[56:59]
	v_mfma_f32_16x16x32_bf16 v[48:51], v[228:231], v[184:187], v[48:51]
	v_mfma_f32_16x16x32_bf16 v[40:43], v[220:223], v[192:195], v[40:43]
	v_mfma_f32_16x16x32_bf16 v[32:35], v[228:231], v[192:195], v[32:35]
	v_mfma_f32_16x16x32_bf16 v[24:27], v[220:223], v[200:203], v[24:27]
	v_mfma_f32_16x16x32_bf16 v[16:19], v[228:231], v[200:203], v[16:19]
	v_mfma_f32_16x16x32_bf16 v[8:11], v[220:223], v[212:215], v[8:11]
	v_mfma_f32_16x16x32_bf16 v[0:3], v[228:231], v[212:215], v[0:3]
	s_setprio 0
	s_add_i32 s46, 0, 0x18000
	v_add_u32_e32 v157, s46, v144
	s_barrier
	ds_read_b128 v[158:161], v157
	ds_read_b128 v[162:165], v157 offset:1024
	ds_read_b128 v[166:169], v157 offset:2048
	ds_read_b128 v[170:173], v157 offset:3072
	s_add_u32 s28, s28, 0x40000
	s_addc_u32 s29, s29, 0
	s_mov_b32 m0, s30
	v_lshl_add_u64 v[216:217], s[28:29], 0, v[128:129]
	ds_read_b128 v[180:183], v147 offset:32768
	ds_read_b128 v[184:187], v147 offset:33792
	ds_read_b128 v[188:191], v147 offset:34816
	ds_read_b128 v[192:195], v147 offset:35840
	ds_read_b128 v[196:199], v147 offset:36864
	ds_read_b128 v[200:203], v147 offset:37888
	ds_read_b128 v[208:211], v147 offset:38912
	ds_read_b128 v[212:215], v147 offset:39936
	global_load_lds_dwordx4 v[216:217], off
	v_lshl_add_u64 v[216:217], s[28:29], 0, v[132:133]
	s_mov_b32 m0, s31
	s_nop 0
	global_load_lds_dwordx4 v[216:217], off
	s_waitcnt lgkmcnt(8)
	s_barrier
	s_waitcnt lgkmcnt(0)
	s_setprio 1
	v_mfma_f32_16x16x32_bf16 v[124:127], v[158:161], v[180:183], v[124:127]
	v_mfma_f32_16x16x32_bf16 v[116:119], v[166:169], v[180:183], v[116:119]
	v_mfma_f32_16x16x32_bf16 v[108:111], v[158:161], v[188:191], v[108:111]
	v_mfma_f32_16x16x32_bf16 v[100:103], v[166:169], v[188:191], v[100:103]
	v_mfma_f32_16x16x32_bf16 v[92:95], v[158:161], v[196:199], v[92:95]
	v_mfma_f32_16x16x32_bf16 v[84:87], v[166:169], v[196:199], v[84:87]
	v_mfma_f32_16x16x32_bf16 v[76:79], v[158:161], v[208:211], v[76:79]
	v_mfma_f32_16x16x32_bf16 v[68:71], v[166:169], v[208:211], v[68:71]
	v_mfma_f32_16x16x32_bf16 v[124:127], v[162:165], v[184:187], v[124:127]
	v_mfma_f32_16x16x32_bf16 v[116:119], v[170:173], v[184:187], v[116:119]
	v_mfma_f32_16x16x32_bf16 v[108:111], v[162:165], v[192:195], v[108:111]
	v_mfma_f32_16x16x32_bf16 v[100:103], v[170:173], v[192:195], v[100:103]
	v_mfma_f32_16x16x32_bf16 v[92:95], v[162:165], v[200:203], v[92:95]
	v_mfma_f32_16x16x32_bf16 v[84:87], v[170:173], v[200:203], v[84:87]
	v_mfma_f32_16x16x32_bf16 v[76:79], v[162:165], v[212:215], v[76:79]
	v_mfma_f32_16x16x32_bf16 v[68:71], v[170:173], v[212:215], v[68:71]
	s_setprio 0
	s_barrier
	s_add_i32 s28, 0, 0x1c000
	s_add_i32 s29, s46, s4
	v_add_u32_e32 v157, s28, v144
	v_lshl_add_u64 v[174:175], v[174:175], 0, s[6:7]
	s_mov_b32 m0, s29
	ds_read_b128 v[216:219], v157
	ds_read_b128 v[220:223], v157 offset:1024
	ds_read_b128 v[224:227], v157 offset:2048
	ds_read_b128 v[228:231], v157 offset:3072
	global_load_lds_dwordx4 v[174:175], off
	v_lshl_add_u64 v[174:175], v[204:205], 0, s[6:7]
	s_add_i32 m0, s29, 0x2000
	s_nop 0
	global_load_lds_dwordx4 v[174:175], off
	s_barrier
	s_waitcnt lgkmcnt(0)
	s_setprio 1
	v_mfma_f32_16x16x32_bf16 v[120:123], v[216:219], v[180:183], v[120:123]
	v_mfma_f32_16x16x32_bf16 v[112:115], v[224:227], v[180:183], v[112:115]
	v_mfma_f32_16x16x32_bf16 v[104:107], v[216:219], v[188:191], v[104:107]
	v_mfma_f32_16x16x32_bf16 v[96:99], v[224:227], v[188:191], v[96:99]
	v_mfma_f32_16x16x32_bf16 v[88:91], v[216:219], v[196:199], v[88:91]
	v_mfma_f32_16x16x32_bf16 v[80:83], v[224:227], v[196:199], v[80:83]
	v_mfma_f32_16x16x32_bf16 v[72:75], v[216:219], v[208:211], v[72:75]
	v_mfma_f32_16x16x32_bf16 v[64:67], v[224:227], v[208:211], v[64:67]
	v_mfma_f32_16x16x32_bf16 v[120:123], v[220:223], v[184:187], v[120:123]
	v_mfma_f32_16x16x32_bf16 v[112:115], v[228:231], v[184:187], v[112:115]
	v_mfma_f32_16x16x32_bf16 v[104:107], v[220:223], v[192:195], v[104:107]
	v_mfma_f32_16x16x32_bf16 v[96:99], v[228:231], v[192:195], v[96:99]
	v_mfma_f32_16x16x32_bf16 v[88:91], v[220:223], v[200:203], v[88:91]
	v_mfma_f32_16x16x32_bf16 v[80:83], v[228:231], v[200:203], v[80:83]
	v_mfma_f32_16x16x32_bf16 v[72:75], v[220:223], v[212:215], v[72:75]
	v_mfma_f32_16x16x32_bf16 v[64:67], v[228:231], v[212:215], v[64:67]
	s_setprio 0
	s_mov_b32 m0, s34
	v_lshl_add_u64 v[174:175], v[232:233], 0, s[6:7]
	s_barrier
	ds_read_b128 v[180:183], v147 offset:49152
	ds_read_b128 v[184:187], v147 offset:50176
	ds_read_b128 v[188:191], v147 offset:51200
	ds_read_b128 v[192:195], v147 offset:52224
	ds_read_b128 v[196:199], v147 offset:53248
	ds_read_b128 v[200:203], v147 offset:54272
	ds_read_b128 v[208:211], v147 offset:55296
	ds_read_b128 v[212:215], v147 offset:56320
	global_load_lds_dwordx4 v[174:175], off
	v_lshl_add_u64 v[174:175], v[234:235], 0, s[6:7]
	s_mov_b32 m0, s35
	s_nop 0
	global_load_lds_dwordx4 v[174:175], off
	s_barrier
; __device__ __forceinline__ unsigned cvt_pk_bf16(float lo, float hi) { unsigned r; asm volatile("v_cvt_pk_bf16_f32 %0, %1, %2" : "=v"(r) : "v"(lo), "v"(hi)); return r; }
; #define PG8_STAGE(bufoff, gbase, voff) do { _Pragma("unroll") for (int _i = 0; _i < 2; ++_i) \
;         __builtin_amdgcn_global_load_lds((const unsigned*)((const char*)(gbase) + (voff)[_i]), (PG8_LAS unsigned*)(lds + (bufoff) + ldsw + _i * 8192), 16, 0, 0); } while (0)
; #define PG8_WAIT_V(n) asm volatile("s_waitcnt vmcnt(" #n ")" ::: "memory")
; #define PG8_WAIT_L(n) asm volatile("s_waitcnt lgkmcnt(" #n ")" ::: "memory")
; #define PG8_BAR __builtin_amdgcn_s_barrier()
; #define PG8_SCHED __builtin_amdgcn_sched_barrier(0)
; template <class Epi, class Sched>
; __device__ __forceinline__ void gemm_phase(PG8_LAS unsigned char* lds, const Gemm g, const Sched& S, const Epi& E) {
;     ...
;             PG8_BAR; PG8_WAIT_L(0); PG8_MMA(1, 0, At, B0); PG8_BAR; PG8_SCHED;
;             PG8_STAGE(PG8_SB(1, 1), b3 + hstep, voffB);
;             PG8_WAIT_V(6); PG8_BAR; PG8_MMA(1, 1, At, B1); PG8_BAR;
;     __device__ __forceinline__ void operator()(const f32x4 (&acc)[2][2][4][2], const Unit& u, int wr, int wc, int fr, int fq, const float (&epre)[8]) const {
;         const int row0 = u.pm * 256 + wr * 64 + fr, col0 = u.pn * 128 + wc * 32 + 8 * fq;
; #pragma unroll
;         for (int ai = 0; ai < 2; ++ai)
; #pragma unroll
;             for (int m = 0; m < 4; ++m) { const int row = row0 + ai * 128 + m * 16;
;                 const float rstd = rsqrtf(epre[ai * 4 + m] * (1.0f / DM) + EPS), c1 = -1.44269504f * rstd, c2 = rstd * rstd;
;                 f32x4 av[2];
; #pragma unroll
;                 for (int n = 0; n < 2; ++n) { const f32x4 g = acc[ai][0][m][n], t = g * c1; f32x4 e;
; #pragma unroll
;                     for (int j = 0; j < 4; ++j) e[j] = __builtin_amdgcn_exp2f(t[j]);
;                     const f32x4 d = e + 1.0f; f32x4 r;
; #pragma unroll
;                     for (int j = 0; j < 4; ++j) r[j] = frcp(d[j]);
;                     av[n] = (g * acc[ai][1][m][n]) * (r * c2); }
;                 u32x4 w; w.x = cvt_pk_bf16(av[0][0], av[0][1]); w.y = cvt_pk_bf16(av[0][2], av[0][3]); w.z = cvt_pk_bf16(av[1][0], av[1][1]); w.w = cvt_pk_bf16(av[1][2], av[1][3]);
;                 *(u32x4*)(ACT + (size_t)row * DFF + col0) = w; }
	s_waitcnt lgkmcnt(0)
	s_setprio 1
	v_mfma_f32_16x16x32_bf16 v[60:63], v[158:161], v[180:183], v[60:63]
	v_mfma_f32_16x16x32_bf16 v[52:55], v[166:169], v[180:183], v[52:55]
	v_mfma_f32_16x16x32_bf16 v[44:47], v[158:161], v[188:191], v[44:47]
	v_mfma_f32_16x16x32_bf16 v[36:39], v[166:169], v[188:191], v[36:39]
	v_mfma_f32_16x16x32_bf16 v[28:31], v[158:161], v[196:199], v[28:31]
	v_mfma_f32_16x16x32_bf16 v[20:23], v[166:169], v[196:199], v[20:23]
	v_mfma_f32_16x16x32_bf16 v[12:15], v[158:161], v[208:211], v[12:15]
	v_mfma_f32_16x16x32_bf16 v[4:7], v[166:169], v[208:211], v[4:7]
	v_mfma_f32_16x16x32_bf16 v[60:63], v[162:165], v[184:187], v[60:63]
	v_mfma_f32_16x16x32_bf16 v[52:55], v[170:173], v[184:187], v[52:55]
	v_mfma_f32_16x16x32_bf16 v[44:47], v[162:165], v[192:195], v[44:47]
	v_mfma_f32_16x16x32_bf16 v[36:39], v[170:173], v[192:195], v[36:39]
	v_mfma_f32_16x16x32_bf16 v[28:31], v[162:165], v[200:203], v[28:31]
	v_mfma_f32_16x16x32_bf16 v[20:23], v[170:173], v[200:203], v[20:23]
	v_mfma_f32_16x16x32_bf16 v[12:15], v[162:165], v[212:215], v[12:15]
	v_mfma_f32_16x16x32_bf16 v[4:7], v[170:173], v[212:215], v[4:7]
	s_setprio 0
	s_barrier
	s_add_u32 s26, s26, 0x40080
	s_addc_u32 s27, s27, 0
	s_add_i32 s28, s28, s4
	v_lshl_add_u64 v[158:159], s[26:27], 0, v[130:131]
	s_mov_b32 m0, s28
	s_nop 0
	global_load_lds_dwordx4 v[158:159], off
	v_lshl_add_u64 v[158:159], s[26:27], 0, v[134:135]
	s_add_i32 m0, s28, 0x2000
	s_nop 0
	global_load_lds_dwordx4 v[158:159], off
	s_waitcnt vmcnt(6)
	s_barrier
	s_setprio 1
	v_mfma_f32_16x16x32_bf16 v[56:59], v[216:219], v[180:183], v[56:59]
	v_mfma_f32_16x16x32_bf16 v[48:51], v[224:227], v[180:183], v[48:51]
	v_mfma_f32_16x16x32_bf16 v[40:43], v[216:219], v[188:191], v[40:43]
	v_mfma_f32_16x16x32_bf16 v[32:35], v[224:227], v[188:191], v[32:35]
	v_mfma_f32_16x16x32_bf16 v[24:27], v[216:219], v[196:199], v[24:27]
	v_mfma_f32_16x16x32_bf16 v[16:19], v[224:227], v[196:199], v[16:19]
	v_mfma_f32_16x16x32_bf16 v[8:11], v[216:219], v[208:211], v[8:11]
	v_mfma_f32_16x16x32_bf16 v[0:3], v[224:227], v[208:211], v[0:3]
	v_mfma_f32_16x16x32_bf16 v[56:59], v[220:223], v[184:187], v[56:59]
	v_mfma_f32_16x16x32_bf16 v[48:51], v[228:231], v[184:187], v[48:51]
	v_mfma_f32_16x16x32_bf16 v[40:43], v[220:223], v[192:195], v[40:43]
	v_mfma_f32_16x16x32_bf16 v[32:35], v[228:231], v[192:195], v[32:35]
	v_mfma_f32_16x16x32_bf16 v[24:27], v[220:223], v[200:203], v[24:27]
	v_mfma_f32_16x16x32_bf16 v[16:19], v[228:231], v[200:203], v[16:19]
	v_mfma_f32_16x16x32_bf16 v[8:11], v[220:223], v[212:215], v[8:11]
	v_mfma_f32_16x16x32_bf16 v[0:3], v[228:231], v[212:215], v[0:3]
	s_setprio 0
	s_add_i32 s45, s45, 2
	s_add_u32 s24, s24, 0x100
	s_addc_u32 s25, s25, 0
	s_add_u32 s43, s43, 0x100
	s_addc_u32 s44, s44, 0
	s_cmp_gt_u32 s45, 13
	s_barrier
	s_cbranch_scc0 .LBB0_702
	s_waitcnt vmcnt(0)
	v_fmamk_f32 v156, v156, 0x3a800000, v149
	v_mul_f32_e32 v157, 0x4b800000, v156
	v_cmp_gt_f32_e32 vcc, s40, v156
	v_pk_mul_f32 v[122:123], v[126:127], v[122:123]
	v_pk_mul_f32 v[120:121], v[124:125], v[120:121]
	v_cndmask_b32_e32 v156, v156, v157, vcc
	v_rsq_f32_e32 v157, v156
	v_pk_mul_f32 v[114:115], v[118:119], v[114:115]
	v_pk_mul_f32 v[112:113], v[116:117], v[112:113]
	v_lshl_or_b32 v158, s22, 7, v145
	v_mul_f32_e32 v160, 0x45800000, v157
	v_cndmask_b32_e32 v157, v157, v160, vcc
	v_mul_f32_e32 v160, 0xbfb8aa3b, v157
	v_pk_mul_f32 v[166:167], v[160:161], v[124:125] op_sel_hi:[0,1]
	v_mul_f32_e32 v162, v157, v157
	v_exp_f32_e32 v157, v166
	v_pk_mul_f32 v[164:165], v[160:161], v[126:127] op_sel_hi:[0,1]
	v_exp_f32_e32 v161, v167
	v_exp_f32_e32 v163, v164
	v_exp_f32_e32 v167, v165
	v_add_f32_e32 v157, 1.0, v157
	v_rcp_f32_e32 v164, v157
	v_add_f32_e32 v157, 1.0, v161
	v_rcp_f32_e32 v165, v157
	v_add_f32_e32 v157, 1.0, v163
	v_rcp_f32_e32 v166, v157
	v_add_f32_e32 v157, 1.0, v167
	v_rcp_f32_e32 v167, v157
	v_pk_mul_f32 v[124:125], v[162:163], v[164:165] op_sel_hi:[0,1]
	v_pk_mul_f32 v[120:121], v[124:125], v[120:121]
	v_pk_mul_f32 v[124:125], v[160:161], v[118:119] op_sel_hi:[0,1]
	v_pk_mul_f32 v[126:127], v[162:163], v[166:167] op_sel_hi:[0,1]
	v_pk_mul_f32 v[122:123], v[126:127], v[122:123]
	v_pk_mul_f32 v[126:127], v[160:161], v[116:117] op_sel_hi:[0,1]
	v_exp_f32_e32 v126, v126
	v_exp_f32_e32 v127, v127
	v_exp_f32_e32 v157, v124
	v_exp_f32_e32 v160, v125
	v_add_f32_e32 v124, 1.0, v126
	v_add_f32_e32 v125, 1.0, v127
	v_add_f32_e32 v126, 1.0, v157
	v_add_f32_e32 v127, 1.0, v160
	v_rcp_f32_e32 v126, v126
	v_rcp_f32_e32 v127, v127
	v_rcp_f32_e32 v124, v124
	v_rcp_f32_e32 v125, v125
	v_lshl_add_u32 v156, s20, 8, v143
	v_pk_mul_f32 v[118:119], v[162:163], v[126:127] op_sel_hi:[0,1]
	v_pk_mul_f32 v[114:115], v[118:119], v[114:115]
	v_pk_mul_f32 v[116:117], v[162:163], v[124:125] op_sel_hi:[0,1]
	v_pk_mul_f32 v[112:113], v[116:117], v[112:113]
	v_cvt_pk_bf16_f32 v116, v120, v121
	v_cvt_pk_bf16_f32 v117, v122, v123
	v_ashrrev_i32_e32 v159, 31, v158
	v_cvt_pk_bf16_f32 v118, v112, v113
	v_cvt_pk_bf16_f32 v119, v114, v115
	v_fmamk_f32 v114, v155, 0x3a800000, v149
	v_mul_f32_e32 v115, 0x4b800000, v114
	v_cmp_gt_f32_e32 vcc, s40, v114
	v_mov_b64_e32 v[112:113], s[82:83]
	v_mad_i64_i32 v[120:121], s[20:21], v156, s41, v[112:113]
	v_cndmask_b32_e32 v114, v114, v115, vcc
	v_rsq_f32_e32 v122, v114
	v_lshlrev_b64 v[114:115], 1, v[158:159]
	v_lshl_add_u64 v[120:121], v[120:121], 0, v[114:115]
	global_store_dwordx4 v[120:121], v[116:119], off
	v_pk_mul_f32 v[106:107], v[110:111], v[106:107]
	v_pk_mul_f32 v[104:105], v[108:109], v[104:105]
	v_mul_f32_e32 v116, 0x45800000, v122
	v_cndmask_b32_e32 v117, v122, v116, vcc
	v_mul_f32_e32 v116, 0xbfb8aa3b, v117
; __device__ __forceinline__ unsigned cvt_pk_bf16(float lo, float hi) { unsigned r; asm volatile("v_cvt_pk_bf16_f32 %0, %1, %2" : "=v"(r) : "v"(lo), "v"(hi)); return r; }
; __device__ __forceinline__ float frcp(float x) { return __builtin_amdgcn_rcpf(x); }
;     __device__ __forceinline__ void operator()(const f32x4 (&acc)[2][2][4][2], const Unit& u, int wr, int wc, int fr, int fq, const float (&epre)[8]) const {
;     ...
;             for (int m = 0; m < 4; ++m) { const int row = row0 + ai * 128 + m * 16;
;                 const float rstd = rsqrtf(epre[ai * 4 + m] * (1.0f / DM) + EPS), c1 = -1.44269504f * rstd, c2 = rstd * rstd;
;                 f32x4 av[2];
; #pragma unroll
;                 for (int n = 0; n < 2; ++n) { const f32x4 g = acc[ai][0][m][n], t = g * c1; f32x4 e;
; #pragma unroll
;                     for (int j = 0; j < 4; ++j) e[j] = __builtin_amdgcn_exp2f(t[j]);
;                     const f32x4 d = e + 1.0f; f32x4 r;
; #pragma unroll
;                     for (int j = 0; j < 4; ++j) r[j] = frcp(d[j]);
;                     av[n] = (g * acc[ai][1][m][n]) * (r * c2); }
;                 u32x4 w; w.x = cvt_pk_bf16(av[0][0], av[0][1]); w.y = cvt_pk_bf16(av[0][2], av[0][3]); w.z = cvt_pk_bf16(av[1][0], av[1][1]); w.w = cvt_pk_bf16(av[1][2], av[1][3]);
;                 *(u32x4*)(ACT + (size_t)row * DFF + col0) = w; }
	v_pk_mul_f32 v[122:123], v[116:117], v[108:109] op_sel_hi:[0,1]
	v_mul_f32_e32 v118, v117, v117
	v_pk_mul_f32 v[120:121], v[116:117], v[110:111] op_sel_hi:[0,1]
	v_exp_f32_e32 v117, v122
	v_exp_f32_e32 v119, v123
	v_exp_f32_e32 v122, v120
	v_exp_f32_e32 v123, v121
	v_add_f32_e32 v117, 1.0, v117
	v_rcp_f32_e32 v120, v117
	v_add_f32_e32 v117, 1.0, v119
	v_rcp_f32_e32 v121, v117
	v_add_f32_e32 v117, 1.0, v122
	v_rcp_f32_e32 v122, v117
	v_add_f32_e32 v117, 1.0, v123
	v_rcp_f32_e32 v123, v117
	v_pk_mul_f32 v[108:109], v[118:119], v[120:121] op_sel_hi:[0,1]
	v_pk_mul_f32 v[104:105], v[108:109], v[104:105]
	v_pk_mul_f32 v[108:109], v[116:117], v[102:103] op_sel_hi:[0,1]
	v_pk_mul_f32 v[110:111], v[118:119], v[122:123] op_sel_hi:[0,1]
	v_pk_mul_f32 v[106:107], v[110:111], v[106:107]
	v_pk_mul_f32 v[110:111], v[116:117], v[100:101] op_sel_hi:[0,1]
	v_exp_f32_e32 v110, v110
	v_exp_f32_e32 v111, v111
	v_exp_f32_e32 v116, v108
	v_exp_f32_e32 v117, v109
	v_add_f32_e32 v108, 1.0, v110
	v_add_f32_e32 v109, 1.0, v111
	v_add_f32_e32 v110, 1.0, v116
	v_add_f32_e32 v111, 1.0, v117
	v_rcp_f32_e32 v108, v108
	v_rcp_f32_e32 v109, v109
	v_rcp_f32_e32 v110, v110
	v_rcp_f32_e32 v111, v111
	v_pk_mul_f32 v[98:99], v[102:103], v[98:99]
	v_pk_mul_f32 v[96:97], v[100:101], v[96:97]
	v_pk_mul_f32 v[100:101], v[118:119], v[108:109] op_sel_hi:[0,1]
	v_pk_mul_f32 v[102:103], v[118:119], v[110:111] op_sel_hi:[0,1]
	v_pk_mul_f32 v[102:103], v[102:103], v[98:99]
	v_pk_mul_f32 v[98:99], v[100:101], v[96:97]
	v_fmamk_f32 v101, v154, 0x3a800000, v149
	v_cvt_pk_bf16_f32 v96, v104, v105
	v_cvt_pk_bf16_f32 v97, v106, v107
	v_cvt_pk_bf16_f32 v98, v98, v99
	v_cvt_pk_bf16_f32 v99, v102, v103
	v_mul_f32_e32 v102, 0x4b800000, v101
	v_cmp_gt_f32_e32 vcc, s40, v101
	v_or_b32_e32 v100, 16, v156
	v_pk_mul_f32 v[90:91], v[94:95], v[90:91]
	v_cndmask_b32_e32 v101, v101, v102, vcc
	v_rsq_f32_e32 v102, v101
	v_mad_i64_i32 v[100:101], s[20:21], v100, s41, v[112:113]
	v_lshl_add_u64 v[100:101], v[100:101], 0, v[114:115]
	global_store_dwordx4 v[100:101], v[96:99], off
	v_pk_mul_f32 v[88:89], v[92:93], v[88:89]
	v_pk_mul_f32 v[82:83], v[86:87], v[82:83]
	v_mul_f32_e32 v96, 0x45800000, v102
	v_cndmask_b32_e32 v97, v102, v96, vcc
	v_mul_f32_e32 v96, 0xbfb8aa3b, v97
	v_pk_mul_f32 v[102:103], v[96:97], v[92:93] op_sel_hi:[0,1]
	v_mul_f32_e32 v98, v97, v97
	v_pk_mul_f32 v[100:101], v[96:97], v[94:95] op_sel_hi:[0,1]
	v_exp_f32_e32 v97, v102
	v_exp_f32_e32 v99, v103
	v_exp_f32_e32 v102, v100
	v_exp_f32_e32 v103, v101
	v_add_f32_e32 v97, 1.0, v97
	v_rcp_f32_e32 v100, v97
	v_add_f32_e32 v97, 1.0, v99
	v_rcp_f32_e32 v101, v97
	v_add_f32_e32 v97, 1.0, v102
	v_rcp_f32_e32 v102, v97
	v_add_f32_e32 v97, 1.0, v103
	v_rcp_f32_e32 v103, v97
	v_pk_mul_f32 v[92:93], v[98:99], v[100:101] op_sel_hi:[0,1]
	v_pk_mul_f32 v[88:89], v[92:93], v[88:89]
	v_pk_mul_f32 v[92:93], v[96:97], v[86:87] op_sel_hi:[0,1]
	v_pk_mul_f32 v[94:95], v[98:99], v[102:103] op_sel_hi:[0,1]
	v_pk_mul_f32 v[90:91], v[94:95], v[90:91]
	v_pk_mul_f32 v[94:95], v[96:97], v[84:85] op_sel_hi:[0,1]
	v_exp_f32_e32 v94, v94
	v_exp_f32_e32 v95, v95
	v_exp_f32_e32 v96, v92
	v_exp_f32_e32 v97, v93
	v_add_f32_e32 v92, 1.0, v94
	v_add_f32_e32 v93, 1.0, v95
	v_add_f32_e32 v94, 1.0, v96
	v_add_f32_e32 v95, 1.0, v97
	v_rcp_f32_e32 v92, v92
	v_rcp_f32_e32 v93, v93
	v_rcp_f32_e32 v94, v94
	v_rcp_f32_e32 v95, v95
	v_pk_mul_f32 v[80:81], v[84:85], v[80:81]
	v_pk_mul_f32 v[84:85], v[98:99], v[92:93] op_sel_hi:[0,1]
	v_pk_mul_f32 v[74:75], v[78:79], v[74:75]
	v_pk_mul_f32 v[86:87], v[98:99], v[94:95] op_sel_hi:[0,1]
	v_pk_mul_f32 v[86:87], v[86:87], v[82:83]
	v_pk_mul_f32 v[82:83], v[84:85], v[80:81]
	v_fmamk_f32 v85, v153, 0x3a800000, v149
	v_cvt_pk_bf16_f32 v80, v88, v89
	v_cvt_pk_bf16_f32 v81, v90, v91
	v_cvt_pk_bf16_f32 v82, v82, v83
	v_cvt_pk_bf16_f32 v83, v86, v87
	v_mul_f32_e32 v86, 0x4b800000, v85
	v_cmp_gt_f32_e32 vcc, s40, v85
	v_or_b32_e32 v84, 32, v156
	v_pk_mul_f32 v[72:73], v[76:77], v[72:73]
	v_cndmask_b32_e32 v85, v85, v86, vcc
	v_rsq_f32_e32 v86, v85
	v_mad_i64_i32 v[84:85], s[20:21], v84, s41, v[112:113]
	v_lshl_add_u64 v[84:85], v[84:85], 0, v[114:115]
	global_store_dwordx4 v[84:85], v[80:83], off
	v_pk_mul_f32 v[66:67], v[70:71], v[66:67]
	v_pk_mul_f32 v[64:65], v[68:69], v[64:65]
	v_mul_f32_e32 v80, 0x45800000, v86
	v_cndmask_b32_e32 v81, v86, v80, vcc
	v_mul_f32_e32 v80, 0xbfb8aa3b, v81
	v_pk_mul_f32 v[86:87], v[80:81], v[76:77] op_sel_hi:[0,1]
	v_mul_f32_e32 v82, v81, v81
	v_pk_mul_f32 v[84:85], v[80:81], v[78:79] op_sel_hi:[0,1]
	v_exp_f32_e32 v81, v86
	v_exp_f32_e32 v83, v87
	v_exp_f32_e32 v86, v84
	v_exp_f32_e32 v87, v85
	v_add_f32_e32 v81, 1.0, v81
	v_rcp_f32_e32 v84, v81
	v_add_f32_e32 v81, 1.0, v83
	v_rcp_f32_e32 v85, v81
	v_add_f32_e32 v81, 1.0, v86
	v_rcp_f32_e32 v86, v81
	v_add_f32_e32 v81, 1.0, v87
	v_rcp_f32_e32 v87, v81
	v_pk_mul_f32 v[76:77], v[82:83], v[84:85] op_sel_hi:[0,1]
	v_pk_mul_f32 v[72:73], v[76:77], v[72:73]
	v_pk_mul_f32 v[76:77], v[80:81], v[70:71] op_sel_hi:[0,1]
	v_pk_mul_f32 v[78:79], v[82:83], v[86:87] op_sel_hi:[0,1]
	v_pk_mul_f32 v[74:75], v[78:79], v[74:75]
	v_pk_mul_f32 v[78:79], v[80:81], v[68:69] op_sel_hi:[0,1]
	v_exp_f32_e32 v78, v78
	v_exp_f32_e32 v79, v79
	v_exp_f32_e32 v80, v76
	v_exp_f32_e32 v81, v77
	v_add_f32_e32 v76, 1.0, v78
	v_add_f32_e32 v77, 1.0, v79
	v_add_f32_e32 v78, 1.0, v80
	v_add_f32_e32 v79, 1.0, v81
	v_rcp_f32_e32 v76, v76
	v_rcp_f32_e32 v77, v77
	v_rcp_f32_e32 v78, v78
	v_rcp_f32_e32 v79, v79
	v_pk_mul_f32 v[58:59], v[62:63], v[58:59]
	v_pk_mul_f32 v[68:69], v[82:83], v[76:77] op_sel_hi:[0,1]
	v_pk_mul_f32 v[56:57], v[60:61], v[56:57]
	v_pk_mul_f32 v[70:71], v[82:83], v[78:79] op_sel_hi:[0,1]
; __device__ __forceinline__ unsigned cvt_pk_bf16(float lo, float hi) { unsigned r; asm volatile("v_cvt_pk_bf16_f32 %0, %1, %2" : "=v"(r) : "v"(lo), "v"(hi)); return r; }
; __device__ __forceinline__ float frcp(float x) { return __builtin_amdgcn_rcpf(x); }
;     __device__ __forceinline__ void operator()(const f32x4 (&acc)[2][2][4][2], const Unit& u, int wr, int wc, int fr, int fq, const float (&epre)[8]) const {
;     ...
;             for (int m = 0; m < 4; ++m) { const int row = row0 + ai * 128 + m * 16;
;                 const float rstd = rsqrtf(epre[ai * 4 + m] * (1.0f / DM) + EPS), c1 = -1.44269504f * rstd, c2 = rstd * rstd;
;                 f32x4 av[2];
; #pragma unroll
;                 for (int n = 0; n < 2; ++n) { const f32x4 g = acc[ai][0][m][n], t = g * c1; f32x4 e;
; #pragma unroll
;                     for (int j = 0; j < 4; ++j) e[j] = __builtin_amdgcn_exp2f(t[j]);
;                     const f32x4 d = e + 1.0f; f32x4 r;
; #pragma unroll
;                     for (int j = 0; j < 4; ++j) r[j] = frcp(d[j]);
;                     av[n] = (g * acc[ai][1][m][n]) * (r * c2); }
;                 u32x4 w; w.x = cvt_pk_bf16(av[0][0], av[0][1]); w.y = cvt_pk_bf16(av[0][2], av[0][3]); w.z = cvt_pk_bf16(av[1][0], av[1][1]); w.w = cvt_pk_bf16(av[1][2], av[1][3]);
;                 *(u32x4*)(ACT + (size_t)row * DFF + col0) = w; }
	v_pk_mul_f32 v[70:71], v[70:71], v[66:67]
	v_pk_mul_f32 v[66:67], v[68:69], v[64:65]
	v_cvt_pk_bf16_f32 v64, v72, v73
	v_cvt_pk_bf16_f32 v65, v74, v75
	v_or_b32_e32 v68, 48, v156
	v_cvt_pk_bf16_f32 v66, v66, v67
	v_cvt_pk_bf16_f32 v67, v70, v71
	v_fmamk_f32 v70, v152, 0x3a800000, v149
	v_mul_f32_e32 v71, 0x4b800000, v70
	v_cmp_gt_f32_e32 vcc, s40, v70
	v_mad_i64_i32 v[68:69], s[20:21], v68, s41, v[112:113]
	s_nop 0
	v_cndmask_b32_e32 v70, v70, v71, vcc
	v_rsq_f32_e32 v70, v70
	v_lshl_add_u64 v[68:69], v[68:69], 0, v[114:115]
	global_store_dwordx4 v[68:69], v[64:67], off
	v_pk_mul_f32 v[50:51], v[54:55], v[50:51]
	v_pk_mul_f32 v[48:49], v[52:53], v[48:49]
	v_mul_f32_e32 v64, 0x45800000, v70
	v_cndmask_b32_e32 v66, v70, v64, vcc
	v_add_u32_e32 v65, 0x80, v156
	v_mul_f32_e32 v64, 0xbfb8aa3b, v66
	v_pk_mul_f32 v[70:71], v[64:65], v[60:61] op_sel_hi:[0,1]
	v_exp_f32_e32 v67, v70
	v_pk_mul_f32 v[68:69], v[64:65], v[62:63] op_sel_hi:[0,1]
	v_exp_f32_e32 v70, v71
	v_exp_f32_e32 v71, v68
	v_exp_f32_e32 v72, v69
	v_add_f32_e32 v67, 1.0, v67
	v_rcp_f32_e32 v68, v67
	v_add_f32_e32 v67, 1.0, v70
	v_rcp_f32_e32 v69, v67
	v_add_f32_e32 v67, 1.0, v71
	v_rcp_f32_e32 v70, v67
	v_add_f32_e32 v67, 1.0, v72
	v_rcp_f32_e32 v71, v67
	v_mul_f32_e32 v66, v66, v66
	v_pk_mul_f32 v[60:61], v[66:67], v[68:69] op_sel_hi:[0,1]
	v_pk_mul_f32 v[56:57], v[60:61], v[56:57]
	v_pk_mul_f32 v[62:63], v[66:67], v[70:71] op_sel_hi:[0,1]
	v_pk_mul_f32 v[58:59], v[62:63], v[58:59]
	v_pk_mul_f32 v[60:61], v[64:65], v[54:55] op_sel_hi:[0,1]
	v_pk_mul_f32 v[62:63], v[64:65], v[52:53] op_sel_hi:[0,1]
	v_exp_f32_e32 v62, v62
	v_exp_f32_e32 v63, v63
	v_exp_f32_e32 v64, v60
	v_exp_f32_e32 v67, v61
	v_add_f32_e32 v60, 1.0, v62
	v_add_f32_e32 v61, 1.0, v63
	v_add_f32_e32 v62, 1.0, v64
	v_add_f32_e32 v63, 1.0, v67
	v_rcp_f32_e32 v60, v60
	v_rcp_f32_e32 v61, v61
	v_rcp_f32_e32 v62, v62
	v_rcp_f32_e32 v63, v63
	v_pk_mul_f32 v[42:43], v[46:47], v[42:43]
	v_pk_mul_f32 v[52:53], v[66:67], v[60:61] op_sel_hi:[0,1]
	v_pk_mul_f32 v[40:41], v[44:45], v[40:41]
	v_pk_mul_f32 v[54:55], v[66:67], v[62:63] op_sel_hi:[0,1]
	v_pk_mul_f32 v[54:55], v[54:55], v[50:51]
	v_pk_mul_f32 v[50:51], v[52:53], v[48:49]
	v_fmamk_f32 v52, v151, 0x3a800000, v149
	v_mul_f32_e32 v53, 0x4b800000, v52
	v_cmp_gt_f32_e32 vcc, s40, v52
	v_cvt_pk_bf16_f32 v48, v56, v57
	v_cvt_pk_bf16_f32 v49, v58, v59
	v_cvt_pk_bf16_f32 v50, v50, v51
	v_cvt_pk_bf16_f32 v51, v54, v55
	v_pk_mul_f32 v[34:35], v[38:39], v[34:35]
	s_nop 0
	v_cndmask_b32_e32 v52, v52, v53, vcc
	v_rsq_f32_e32 v54, v52
	v_mad_i64_i32 v[52:53], s[20:21], v65, s41, v[112:113]
	v_lshl_add_u64 v[52:53], v[52:53], 0, v[114:115]
	global_store_dwordx4 v[52:53], v[48:51], off
	v_pk_mul_f32 v[32:33], v[36:37], v[32:33]
	v_pk_mul_f32 v[26:27], v[30:31], v[26:27]
	v_mul_f32_e32 v48, 0x45800000, v54
	v_cndmask_b32_e32 v49, v54, v48, vcc
	v_mul_f32_e32 v48, 0xbfb8aa3b, v49
	v_pk_mul_f32 v[54:55], v[48:49], v[44:45] op_sel_hi:[0,1]
	v_mul_f32_e32 v50, v49, v49
	v_pk_mul_f32 v[52:53], v[48:49], v[46:47] op_sel_hi:[0,1]
	v_exp_f32_e32 v49, v54
	v_exp_f32_e32 v51, v55
	v_exp_f32_e32 v54, v52
	v_exp_f32_e32 v55, v53
	v_add_f32_e32 v49, 1.0, v49
	v_rcp_f32_e32 v52, v49
	v_add_f32_e32 v49, 1.0, v51
	v_rcp_f32_e32 v53, v49
	v_add_f32_e32 v49, 1.0, v54
	v_rcp_f32_e32 v54, v49
	v_add_f32_e32 v49, 1.0, v55
	v_rcp_f32_e32 v55, v49
	v_pk_mul_f32 v[44:45], v[50:51], v[52:53] op_sel_hi:[0,1]
	v_pk_mul_f32 v[40:41], v[44:45], v[40:41]
	v_pk_mul_f32 v[44:45], v[48:49], v[38:39] op_sel_hi:[0,1]
	v_pk_mul_f32 v[46:47], v[50:51], v[54:55] op_sel_hi:[0,1]
	v_pk_mul_f32 v[42:43], v[46:47], v[42:43]
	v_pk_mul_f32 v[46:47], v[48:49], v[36:37] op_sel_hi:[0,1]
	v_exp_f32_e32 v46, v46
	v_exp_f32_e32 v47, v47
	v_exp_f32_e32 v48, v44
	v_exp_f32_e32 v49, v45
	v_add_f32_e32 v44, 1.0, v46
	v_add_f32_e32 v45, 1.0, v47
	v_add_f32_e32 v46, 1.0, v48
	v_add_f32_e32 v47, 1.0, v49
	v_rcp_f32_e32 v44, v44
	v_rcp_f32_e32 v45, v45
	v_rcp_f32_e32 v46, v46
	v_rcp_f32_e32 v47, v47
	v_pk_mul_f32 v[24:25], v[28:29], v[24:25]
	v_pk_mul_f32 v[36:37], v[50:51], v[44:45] op_sel_hi:[0,1]
	v_pk_mul_f32 v[18:19], v[22:23], v[18:19]
	v_pk_mul_f32 v[38:39], v[50:51], v[46:47] op_sel_hi:[0,1]
	v_pk_mul_f32 v[38:39], v[38:39], v[34:35]
	v_pk_mul_f32 v[34:35], v[36:37], v[32:33]
	v_fmamk_f32 v37, v150, 0x3a800000, v149
	v_cvt_pk_bf16_f32 v32, v40, v41
	v_cvt_pk_bf16_f32 v33, v42, v43
	v_cvt_pk_bf16_f32 v34, v34, v35
	v_cvt_pk_bf16_f32 v35, v38, v39
	v_mul_f32_e32 v38, 0x4b800000, v37
	v_cmp_gt_f32_e32 vcc, s40, v37
	v_add_u32_e32 v36, 0x90, v156
	v_pk_mul_f32 v[16:17], v[20:21], v[16:17]
; __device__ __forceinline__ unsigned cvt_pk_bf16(float lo, float hi) { unsigned r; asm volatile("v_cvt_pk_bf16_f32 %0, %1, %2" : "=v"(r) : "v"(lo), "v"(hi)); return r; }
; __device__ __forceinline__ float frcp(float x) { return __builtin_amdgcn_rcpf(x); }
;     __device__ __forceinline__ void preload(const Unit& u, int wr, int fr, float (&pre)[8]) const { const int row0 = u.pm * 256 + wr * 64 + fr;
; #pragma unroll
;         for (int ai = 0; ai < 2; ++ai)
; #pragma unroll
;             for (int m = 0; m < 4; ++m) pre[ai * 4 + m] = sumsq[row0 + ai * 128 + m * 16]; }
;     __device__ __forceinline__ void operator()(const f32x4 (&acc)[2][2][4][2], const Unit& u, int wr, int wc, int fr, int fq, const float (&epre)[8]) const {
;     ...
;             for (int m = 0; m < 4; ++m) { const int row = row0 + ai * 128 + m * 16;
;                 const float rstd = rsqrtf(epre[ai * 4 + m] * (1.0f / DM) + EPS), c1 = -1.44269504f * rstd, c2 = rstd * rstd;
;                 f32x4 av[2];
; #pragma unroll
;                 for (int n = 0; n < 2; ++n) { const f32x4 g = acc[ai][0][m][n], t = g * c1; f32x4 e;
; #pragma unroll
;                     for (int j = 0; j < 4; ++j) e[j] = __builtin_amdgcn_exp2f(t[j]);
;                     const f32x4 d = e + 1.0f; f32x4 r;
; #pragma unroll
;                     for (int j = 0; j < 4; ++j) r[j] = frcp(d[j]);
;                     av[n] = (g * acc[ai][1][m][n]) * (r * c2); }
;                 u32x4 w; w.x = cvt_pk_bf16(av[0][0], av[0][1]); w.y = cvt_pk_bf16(av[0][2], av[0][3]); w.z = cvt_pk_bf16(av[1][0], av[1][1]); w.w = cvt_pk_bf16(av[1][2], av[1][3]);
;                 *(u32x4*)(ACT + (size_t)row * DFF + col0) = w; }
	v_cndmask_b32_e32 v37, v37, v38, vcc
	v_rsq_f32_e32 v38, v37
	v_mad_i64_i32 v[36:37], s[20:21], v36, s41, v[112:113]
	v_lshl_add_u64 v[36:37], v[36:37], 0, v[114:115]
	global_store_dwordx4 v[36:37], v[32:35], off
	v_pk_mul_f32 v[10:11], v[14:15], v[10:11]
	v_pk_mul_f32 v[8:9], v[12:13], v[8:9]
	v_mul_f32_e32 v32, 0x45800000, v38
	v_cndmask_b32_e32 v33, v38, v32, vcc
	v_mul_f32_e32 v32, 0xbfb8aa3b, v33
	v_pk_mul_f32 v[38:39], v[32:33], v[28:29] op_sel_hi:[0,1]
	v_mul_f32_e32 v34, v33, v33
	v_pk_mul_f32 v[36:37], v[32:33], v[30:31] op_sel_hi:[0,1]
	v_exp_f32_e32 v33, v38
	v_exp_f32_e32 v35, v39
	v_exp_f32_e32 v38, v36
	v_exp_f32_e32 v39, v37
	v_add_f32_e32 v33, 1.0, v33
	v_rcp_f32_e32 v36, v33
	v_add_f32_e32 v33, 1.0, v35
	v_rcp_f32_e32 v37, v33
	v_add_f32_e32 v33, 1.0, v38
	v_rcp_f32_e32 v38, v33
	v_add_f32_e32 v33, 1.0, v39
	v_rcp_f32_e32 v39, v33
	v_pk_mul_f32 v[28:29], v[34:35], v[36:37] op_sel_hi:[0,1]
	v_pk_mul_f32 v[24:25], v[28:29], v[24:25]
	v_pk_mul_f32 v[28:29], v[32:33], v[22:23] op_sel_hi:[0,1]
	v_pk_mul_f32 v[30:31], v[34:35], v[38:39] op_sel_hi:[0,1]
	v_pk_mul_f32 v[26:27], v[30:31], v[26:27]
	v_pk_mul_f32 v[30:31], v[32:33], v[20:21] op_sel_hi:[0,1]
	v_exp_f32_e32 v30, v30
	v_exp_f32_e32 v31, v31
	v_exp_f32_e32 v32, v28
	v_exp_f32_e32 v33, v29
	v_add_f32_e32 v28, 1.0, v30
	v_add_f32_e32 v29, 1.0, v31
	v_add_f32_e32 v30, 1.0, v32
	v_add_f32_e32 v31, 1.0, v33
	v_rcp_f32_e32 v28, v28
	v_rcp_f32_e32 v29, v29
	v_rcp_f32_e32 v30, v30
	v_rcp_f32_e32 v31, v31
	v_pk_mul_f32 v[2:3], v[6:7], v[2:3]
	v_pk_mul_f32 v[20:21], v[34:35], v[28:29] op_sel_hi:[0,1]
	v_pk_mul_f32 v[0:1], v[4:5], v[0:1]
	v_pk_mul_f32 v[22:23], v[34:35], v[30:31] op_sel_hi:[0,1]
	v_pk_mul_f32 v[22:23], v[22:23], v[18:19]
	v_pk_mul_f32 v[18:19], v[20:21], v[16:17]
	v_fmamk_f32 v21, v142, 0x3a800000, v149
	v_cvt_pk_bf16_f32 v16, v24, v25
	v_cvt_pk_bf16_f32 v17, v26, v27
	v_cvt_pk_bf16_f32 v18, v18, v19
	v_cvt_pk_bf16_f32 v19, v22, v23
	v_mul_f32_e32 v22, 0x4b800000, v21
	v_cmp_gt_f32_e32 vcc, s40, v21
	v_add_u32_e32 v20, 0xa0, v156
	s_nop 0
	v_cndmask_b32_e32 v21, v21, v22, vcc
	v_rsq_f32_e32 v22, v21
	v_mad_i64_i32 v[20:21], s[20:21], v20, s41, v[112:113]
	v_lshl_add_u64 v[20:21], v[20:21], 0, v[114:115]
	global_store_dwordx4 v[20:21], v[16:19], off
	s_nop 1
	v_mul_f32_e32 v16, 0x45800000, v22
	v_cndmask_b32_e32 v17, v22, v16, vcc
	v_mul_f32_e32 v16, 0xbfb8aa3b, v17
	v_pk_mul_f32 v[22:23], v[16:17], v[12:13] op_sel_hi:[0,1]
	v_mul_f32_e32 v18, v17, v17
	v_pk_mul_f32 v[20:21], v[16:17], v[14:15] op_sel_hi:[0,1]
	v_exp_f32_e32 v17, v22
	v_exp_f32_e32 v19, v23
	v_exp_f32_e32 v22, v20
	v_exp_f32_e32 v23, v21
	v_add_f32_e32 v17, 1.0, v17
	v_rcp_f32_e32 v20, v17
	v_add_f32_e32 v17, 1.0, v19
	v_rcp_f32_e32 v21, v17
	v_add_f32_e32 v17, 1.0, v22
	v_rcp_f32_e32 v22, v17
	v_add_f32_e32 v17, 1.0, v23
	v_rcp_f32_e32 v23, v17
	v_pk_mul_f32 v[12:13], v[18:19], v[20:21] op_sel_hi:[0,1]
	v_pk_mul_f32 v[8:9], v[12:13], v[8:9]
	v_pk_mul_f32 v[12:13], v[16:17], v[6:7] op_sel_hi:[0,1]
	v_pk_mul_f32 v[14:15], v[18:19], v[22:23] op_sel_hi:[0,1]
	v_pk_mul_f32 v[10:11], v[14:15], v[10:11]
	v_pk_mul_f32 v[14:15], v[16:17], v[4:5] op_sel_hi:[0,1]
	v_exp_f32_e32 v14, v14
	v_exp_f32_e32 v15, v15
	v_exp_f32_e32 v16, v12
	v_exp_f32_e32 v17, v13
	v_add_f32_e32 v12, 1.0, v14
	v_add_f32_e32 v13, 1.0, v15
	v_add_f32_e32 v14, 1.0, v16
	v_add_f32_e32 v15, 1.0, v17
	v_rcp_f32_e32 v12, v12
	v_rcp_f32_e32 v13, v13
	v_rcp_f32_e32 v14, v14
	v_rcp_f32_e32 v15, v15
	s_and_b64 vcc, s[16:17], exec
	v_pk_mul_f32 v[4:5], v[18:19], v[12:13] op_sel_hi:[0,1]
	v_pk_mul_f32 v[6:7], v[18:19], v[14:15] op_sel_hi:[0,1]
	v_pk_mul_f32 v[6:7], v[6:7], v[2:3]
	v_pk_mul_f32 v[2:3], v[4:5], v[0:1]
	v_add_u32_e32 v4, 0xb0, v156
	v_mad_i64_i32 v[4:5], s[20:21], v4, s41, v[112:113]
	v_lshl_add_u64 v[4:5], v[4:5], 0, v[114:115]
	s_mov_b64 s[20:21], -1
	v_cvt_pk_bf16_f32 v0, v8, v9
	v_cvt_pk_bf16_f32 v1, v10, v11
	v_cvt_pk_bf16_f32 v2, v2, v3
	v_cvt_pk_bf16_f32 v3, v6, v7
	global_store_dwordx4 v[4:5], v[0:3], off
	s_cbranch_vccz .LBB0_695
	s_nop 0
	v_lshl_add_u32 v0, s12, 8, v143
	v_ashrrev_i32_e32 v1, 31, v0
	v_lshl_add_u64 v[0:1], v[0:1], 2, s[10:11]
	global_load_dword v156, v[0:1], off
	global_load_dword v155, v[0:1], off offset:64
	global_load_dword v154, v[0:1], off offset:128
	global_load_dword v153, v[0:1], off offset:192
	global_load_dword v152, v[0:1], off offset:512
	global_load_dword v151, v[0:1], off offset:576
	global_load_dword v150, v[0:1], off offset:640
	global_load_dword v142, v[0:1], off offset:704
	s_mov_b64 s[20:21], 0
	s_branch .LBB0_695

; #define PG8_STAGE(bufoff, gbase, voff) do { _Pragma("unroll") for (int _i = 0; _i < 2; ++_i) \
;         __builtin_amdgcn_global_load_lds((const unsigned*)((const char*)(gbase) + (voff)[_i]), (PG8_LAS unsigned*)(lds + (bufoff) + ldsw + _i * 8192), 16, 0, 0); } while (0)
; #define PG8_LDA(dst, b, h) do { _Pragma("unroll") for (int m = 0; m < 4; ++m) _Pragma("unroll") for (int k = 0; k < 2; ++k) dst[m][k] = *(const PG8_LAS bf16x8*)(lds + PG8_SA(b, h) + aoff + m * 2048 + k * 1024); } while (0)
; #define PG8_LDB(dst, b, h) do { _Pragma("unroll") for (int n = 0; n < 2; ++n) _Pragma("unroll") for (int k = 0; k < 2; ++k) dst[n][k] = *(const PG8_LAS bf16x8*)(lds + PG8_SB(b, h) + boff + n * 2048 + k * 1024); } while (0)
; #define PG8_MMA(ai, bj, At, Bt) do { __builtin_amdgcn_s_setprio(1); _Pragma("unroll") for (int m = 0; m < 4; ++m) _Pragma("unroll") for (int n = 0; n < 2; ++n) _Pragma("unroll") for (int k = 0; k < 2; ++k) \
;         acc[ai][bj][m][n] = __builtin_amdgcn_mfma_f32_16x16x32_bf16(Bt[n][k], At[m][k], acc[ai][bj][m][n], 0, 0, 0); __builtin_amdgcn_s_setprio(0); } while (0)
; #define PG8_WAIT_L(n) asm volatile("s_waitcnt lgkmcnt(" #n ")" ::: "memory")
; #define PG8_BAR __builtin_amdgcn_s_barrier()
; #define PG8_SCHED __builtin_amdgcn_sched_barrier(0)
; template <class Epi, class Sched>
; __device__ __forceinline__ void gemm_phase(PG8_LAS unsigned char* lds, const Gemm g, const Sched& S, const Epi& E) {
;     ...
;             PG8_LDB(B0, 0, 0); PG8_SCHED; PG8_LDA(At, 0, 0); PG8_STAGE(PG8_SA(1, 1), a1 + hstep, voffA);
;             PG8_WAIT_L(8); PG8_BAR; PG8_WAIT_L(0); PG8_MMA(0, 0, At, B0); PG8_BAR; PG8_SCHED;
;             PG8_LDB(B1, 0, 1); PG8_STAGE(PG8_SB(0, 0), b2, voffB);
;             PG8_BAR; PG8_WAIT_L(0); PG8_MMA(0, 1, At, B1); PG8_BAR;
;             PG8_LDA(At, 0, 1); PG8_STAGE(PG8_SA(0, 0), a2, voffA);
;             PG8_BAR; PG8_WAIT_L(0); PG8_MMA(1, 0, At, B0); PG8_BAR; PG8_SCHED;
.LBB0_780:
	ds_read_b128 v[144:147], v188
	ds_read_b128 v[148:151], v188 offset:1024
	ds_read_b128 v[152:155], v188 offset:2048
	ds_read_b128 v[156:159], v188 offset:3072
	s_add_u32 s28, s26, 0x100
	s_addc_u32 s29, s27, 0
	s_cmp_eq_u32 s50, 40
	s_cselect_b32 s35, s11, s29
	s_cselect_b32 s34, s10, s28
	s_cselect_b32 s31, s13, s49
	s_cselect_b32 s30, s12, s48
	v_lshl_add_u64 v[184:185], s[26:27], 0, v[136:137]
	s_add_i32 m0, s33, 0xc000
	ds_read_b128 v[160:163], v189
	ds_read_b128 v[164:167], v189 offset:1024
	ds_read_b128 v[168:171], v189 offset:2048
	ds_read_b128 v[172:175], v189 offset:3072
	ds_read_b128 v[180:183], v189 offset:4096
	ds_read_b128 v[192:195], v189 offset:5120
	ds_read_b128 v[196:199], v189 offset:6144
	ds_read_b128 v[200:203], v189 offset:7168
	global_load_lds_dwordx4 v[184:185], off
	v_lshl_add_u64 v[184:185], s[26:27], 0, v[138:139]
	s_add_i32 m0, s33, 0xe000
	s_nop 0
	global_load_lds_dwordx4 v[184:185], off
	s_waitcnt lgkmcnt(8)
	s_barrier
	s_waitcnt lgkmcnt(0)
	s_setprio 1
	v_mfma_f32_16x16x32_bf16 v[124:127], v[144:147], v[160:163], v[124:127]
	v_mfma_f32_16x16x32_bf16 v[120:123], v[152:155], v[160:163], v[120:123]
	v_mfma_f32_16x16x32_bf16 v[108:111], v[144:147], v[168:171], v[108:111]
	v_mfma_f32_16x16x32_bf16 v[104:107], v[152:155], v[168:171], v[104:107]
	v_mfma_f32_16x16x32_bf16 v[92:95], v[144:147], v[180:183], v[92:95]
	v_mfma_f32_16x16x32_bf16 v[88:91], v[152:155], v[180:183], v[88:91]
	v_mfma_f32_16x16x32_bf16 v[76:79], v[144:147], v[196:199], v[76:79]
	v_mfma_f32_16x16x32_bf16 v[72:75], v[152:155], v[196:199], v[72:75]
	v_mfma_f32_16x16x32_bf16 v[124:127], v[148:151], v[164:167], v[124:127]
	v_mfma_f32_16x16x32_bf16 v[120:123], v[156:159], v[164:167], v[120:123]
	v_mfma_f32_16x16x32_bf16 v[108:111], v[148:151], v[172:175], v[108:111]
	v_mfma_f32_16x16x32_bf16 v[104:107], v[156:159], v[172:175], v[104:107]
	v_mfma_f32_16x16x32_bf16 v[92:95], v[148:151], v[192:195], v[92:95]
	v_mfma_f32_16x16x32_bf16 v[88:91], v[156:159], v[192:195], v[88:91]
	v_mfma_f32_16x16x32_bf16 v[76:79], v[148:151], v[200:203], v[76:79]
	v_mfma_f32_16x16x32_bf16 v[72:75], v[156:159], v[200:203], v[72:75]
	s_setprio 0
	s_barrier
	s_add_i32 s26, s42, s5
	v_lshl_add_u64 v[184:185], s[30:31], 0, v[130:131]
	s_mov_b32 m0, s26
	ds_read_b128 v[208:211], v190
	ds_read_b128 v[212:215], v190 offset:1024
	ds_read_b128 v[216:219], v190 offset:2048
	ds_read_b128 v[220:223], v190 offset:3072
	global_load_lds_dwordx4 v[184:185], off
	v_lshl_add_u64 v[204:205], s[30:31], 0, v[134:135]
	s_add_i32 m0, s26, 0x2000
	s_nop 0
	global_load_lds_dwordx4 v[204:205], off
	s_barrier
	s_waitcnt lgkmcnt(0)
	s_setprio 1
	v_mfma_f32_16x16x32_bf16 v[116:119], v[208:211], v[160:163], v[116:119]
	v_mfma_f32_16x16x32_bf16 v[112:115], v[216:219], v[160:163], v[112:115]
	v_mfma_f32_16x16x32_bf16 v[100:103], v[208:211], v[168:171], v[100:103]
	v_mfma_f32_16x16x32_bf16 v[96:99], v[216:219], v[168:171], v[96:99]
	v_mfma_f32_16x16x32_bf16 v[84:87], v[208:211], v[180:183], v[84:87]
	v_mfma_f32_16x16x32_bf16 v[80:83], v[216:219], v[180:183], v[80:83]
	v_mfma_f32_16x16x32_bf16 v[68:71], v[208:211], v[196:199], v[68:71]
	v_mfma_f32_16x16x32_bf16 v[64:67], v[216:219], v[196:199], v[64:67]
	v_mfma_f32_16x16x32_bf16 v[116:119], v[212:215], v[164:167], v[116:119]
	v_mfma_f32_16x16x32_bf16 v[112:115], v[220:223], v[164:167], v[112:115]
	v_mfma_f32_16x16x32_bf16 v[100:103], v[212:215], v[172:175], v[100:103]
	v_mfma_f32_16x16x32_bf16 v[96:99], v[220:223], v[172:175], v[96:99]
	v_mfma_f32_16x16x32_bf16 v[84:87], v[212:215], v[192:195], v[84:87]
	v_mfma_f32_16x16x32_bf16 v[80:83], v[220:223], v[192:195], v[80:83]
	v_mfma_f32_16x16x32_bf16 v[68:71], v[212:215], v[200:203], v[68:71]
	v_mfma_f32_16x16x32_bf16 v[64:67], v[220:223], v[200:203], v[64:67]
	s_setprio 0
	s_mov_b32 m0, s33
	v_lshl_add_u64 v[224:225], s[34:35], 0, v[128:129]
	s_barrier
	ds_read_b128 v[160:163], v189 offset:16384
	ds_read_b128 v[164:167], v189 offset:17408
	ds_read_b128 v[168:171], v189 offset:18432
	ds_read_b128 v[172:175], v189 offset:19456
	ds_read_b128 v[180:183], v189 offset:20480
	ds_read_b128 v[192:195], v189 offset:21504
	ds_read_b128 v[196:199], v189 offset:22528
	ds_read_b128 v[200:203], v189 offset:23552
	global_load_lds_dwordx4 v[224:225], off
	v_lshl_add_u64 v[226:227], s[34:35], 0, v[132:133]
	s_mov_b32 m0, s36
	s_nop 0
	global_load_lds_dwordx4 v[226:227], off
	s_barrier
	s_waitcnt lgkmcnt(0)
	s_setprio 1
	v_mfma_f32_16x16x32_bf16 v[60:63], v[144:147], v[160:163], v[60:63]
	v_mfma_f32_16x16x32_bf16 v[56:59], v[152:155], v[160:163], v[56:59]
	v_mfma_f32_16x16x32_bf16 v[44:47], v[144:147], v[168:171], v[44:47]
	v_mfma_f32_16x16x32_bf16 v[40:43], v[152:155], v[168:171], v[40:43]
	v_mfma_f32_16x16x32_bf16 v[28:31], v[144:147], v[180:183], v[28:31]
	v_mfma_f32_16x16x32_bf16 v[24:27], v[152:155], v[180:183], v[24:27]
	v_mfma_f32_16x16x32_bf16 v[12:15], v[144:147], v[196:199], v[12:15]
	v_mfma_f32_16x16x32_bf16 v[8:11], v[152:155], v[196:199], v[8:11]
	v_mfma_f32_16x16x32_bf16 v[60:63], v[148:151], v[164:167], v[60:63]
	v_mfma_f32_16x16x32_bf16 v[56:59], v[156:159], v[164:167], v[56:59]
	v_mfma_f32_16x16x32_bf16 v[44:47], v[148:151], v[172:175], v[44:47]
	v_mfma_f32_16x16x32_bf16 v[40:43], v[156:159], v[172:175], v[40:43]
	v_mfma_f32_16x16x32_bf16 v[28:31], v[148:151], v[192:195], v[28:31]
	v_mfma_f32_16x16x32_bf16 v[24:27], v[156:159], v[192:195], v[24:27]
	v_mfma_f32_16x16x32_bf16 v[12:15], v[148:151], v[200:203], v[12:15]
	v_mfma_f32_16x16x32_bf16 v[8:11], v[156:159], v[200:203], v[8:11]
	s_setprio 0
	s_barrier
; #define PG8_STAGE(bufoff, gbase, voff) do { _Pragma("unroll") for (int _i = 0; _i < 2; ++_i) \
;         __builtin_amdgcn_global_load_lds((const unsigned*)((const char*)(gbase) + (voff)[_i]), (PG8_LAS unsigned*)(lds + (bufoff) + ldsw + _i * 8192), 16, 0, 0); } while (0)
; #define PG8_LDA(dst, b, h) do { _Pragma("unroll") for (int m = 0; m < 4; ++m) _Pragma("unroll") for (int k = 0; k < 2; ++k) dst[m][k] = *(const PG8_LAS bf16x8*)(lds + PG8_SA(b, h) + aoff + m * 2048 + k * 1024); } while (0)
; #define PG8_LDB(dst, b, h) do { _Pragma("unroll") for (int n = 0; n < 2; ++n) _Pragma("unroll") for (int k = 0; k < 2; ++k) dst[n][k] = *(const PG8_LAS bf16x8*)(lds + PG8_SB(b, h) + boff + n * 2048 + k * 1024); } while (0)
; #define PG8_MMA(ai, bj, At, Bt) do { __builtin_amdgcn_s_setprio(1); _Pragma("unroll") for (int m = 0; m < 4; ++m) _Pragma("unroll") for (int n = 0; n < 2; ++n) _Pragma("unroll") for (int k = 0; k < 2; ++k) \
;         acc[ai][bj][m][n] = __builtin_amdgcn_mfma_f32_16x16x32_bf16(Bt[n][k], At[m][k], acc[ai][bj][m][n], 0, 0, 0); __builtin_amdgcn_s_setprio(0); } while (0)
; #define PG8_WAIT_V(n) asm volatile("s_waitcnt vmcnt(" #n ")" ::: "memory")
; #define PG8_WAIT_L(n) asm volatile("s_waitcnt lgkmcnt(" #n ")" ::: "memory")
; #define PG8_BAR __builtin_amdgcn_s_barrier()
; #define PG8_SCHED __builtin_amdgcn_sched_barrier(0)
; template <class Epi, class Sched>
; __device__ __forceinline__ void gemm_phase(PG8_LAS unsigned char* lds, const Gemm g, const Sched& S, const Epi& E) {
;     ...
;             PG8_STAGE(PG8_SB(0, 1), b2 + hstep, voffB);
;             PG8_WAIT_V(6); PG8_BAR; PG8_MMA(1, 1, At, B1); PG8_BAR;
;             PG8_LDB(B0, 1, 0); PG8_SCHED; PG8_LDA(At, 1, 0); PG8_STAGE(PG8_SA(0, 1), a2 + hstep, voffA);
;             PG8_WAIT_L(8); PG8_BAR; PG8_WAIT_L(0); PG8_MMA(0, 0, At, B0); PG8_BAR; PG8_SCHED;
;             PG8_LDB(B1, 1, 1); PG8_STAGE(PG8_SB(1, 0), b3, voffB);
;             PG8_BAR; PG8_WAIT_L(0); PG8_MMA(0, 1, At, B1); PG8_BAR;
;             PG8_LDA(At, 1, 1); PG8_STAGE(PG8_SA(1, 0), a3, voffA);
	s_add_u32 s26, s30, 0xb0000
	s_addc_u32 s27, s31, 0
	s_add_i32 s51, s43, s5
	v_lshl_add_u64 v[144:145], s[26:27], 0, v[130:131]
	s_mov_b32 m0, s51
	s_nop 0
	global_load_lds_dwordx4 v[144:145], off
	v_lshl_add_u64 v[144:145], s[26:27], 0, v[134:135]
	s_add_i32 m0, s51, 0x2000
	s_nop 0
	global_load_lds_dwordx4 v[144:145], off
	s_waitcnt vmcnt(6)
	s_barrier
	s_setprio 1
	v_mfma_f32_16x16x32_bf16 v[52:55], v[208:211], v[160:163], v[52:55]
	v_mfma_f32_16x16x32_bf16 v[48:51], v[216:219], v[160:163], v[48:51]
	v_mfma_f32_16x16x32_bf16 v[36:39], v[208:211], v[168:171], v[36:39]
	v_mfma_f32_16x16x32_bf16 v[32:35], v[216:219], v[168:171], v[32:35]
	v_mfma_f32_16x16x32_bf16 v[20:23], v[208:211], v[180:183], v[20:23]
	v_mfma_f32_16x16x32_bf16 v[16:19], v[216:219], v[180:183], v[16:19]
	v_mfma_f32_16x16x32_bf16 v[4:7], v[208:211], v[196:199], v[4:7]
	v_mfma_f32_16x16x32_bf16 v[0:3], v[216:219], v[196:199], v[0:3]
	v_mfma_f32_16x16x32_bf16 v[52:55], v[212:215], v[164:167], v[52:55]
	v_mfma_f32_16x16x32_bf16 v[48:51], v[220:223], v[164:167], v[48:51]
	v_mfma_f32_16x16x32_bf16 v[36:39], v[212:215], v[172:175], v[36:39]
	v_mfma_f32_16x16x32_bf16 v[32:35], v[220:223], v[172:175], v[32:35]
	v_mfma_f32_16x16x32_bf16 v[20:23], v[212:215], v[192:195], v[20:23]
	v_mfma_f32_16x16x32_bf16 v[16:19], v[220:223], v[192:195], v[16:19]
	v_mfma_f32_16x16x32_bf16 v[4:7], v[212:215], v[200:203], v[4:7]
	v_mfma_f32_16x16x32_bf16 v[0:3], v[220:223], v[200:203], v[0:3]
	s_setprio 0
	s_add_i32 s51, 0, 0x18000
	v_add_u32_e32 v156, s51, v186
	s_barrier
	ds_read_b128 v[144:147], v156
	ds_read_b128 v[148:151], v156 offset:1024
	ds_read_b128 v[152:155], v156 offset:2048
	ds_read_b128 v[156:159], v156 offset:3072
	s_add_u32 s26, s34, 0xb0000
	s_addc_u32 s27, s35, 0
	s_mov_b32 m0, s37
	v_lshl_add_u64 v[208:209], s[26:27], 0, v[128:129]
	ds_read_b128 v[160:163], v189 offset:32768
	ds_read_b128 v[164:167], v189 offset:33792
	ds_read_b128 v[168:171], v189 offset:34816
	ds_read_b128 v[172:175], v189 offset:35840
	ds_read_b128 v[180:183], v189 offset:36864
	ds_read_b128 v[192:195], v189 offset:37888
	ds_read_b128 v[196:199], v189 offset:38912
	ds_read_b128 v[200:203], v189 offset:39936
	global_load_lds_dwordx4 v[208:209], off
	v_lshl_add_u64 v[208:209], s[26:27], 0, v[132:133]
	s_mov_b32 m0, s38
	s_nop 0
	global_load_lds_dwordx4 v[208:209], off
	s_waitcnt lgkmcnt(8)
	s_barrier
	s_waitcnt lgkmcnt(0)
	s_setprio 1
	v_mfma_f32_16x16x32_bf16 v[124:127], v[144:147], v[160:163], v[124:127]
	v_mfma_f32_16x16x32_bf16 v[120:123], v[152:155], v[160:163], v[120:123]
	v_mfma_f32_16x16x32_bf16 v[108:111], v[144:147], v[168:171], v[108:111]
	v_mfma_f32_16x16x32_bf16 v[104:107], v[152:155], v[168:171], v[104:107]
	v_mfma_f32_16x16x32_bf16 v[92:95], v[144:147], v[180:183], v[92:95]
	v_mfma_f32_16x16x32_bf16 v[88:91], v[152:155], v[180:183], v[88:91]
	v_mfma_f32_16x16x32_bf16 v[76:79], v[144:147], v[196:199], v[76:79]
	v_mfma_f32_16x16x32_bf16 v[72:75], v[152:155], v[196:199], v[72:75]
	v_mfma_f32_16x16x32_bf16 v[124:127], v[148:151], v[164:167], v[124:127]
	v_mfma_f32_16x16x32_bf16 v[120:123], v[156:159], v[164:167], v[120:123]
	v_mfma_f32_16x16x32_bf16 v[108:111], v[148:151], v[172:175], v[108:111]
	v_mfma_f32_16x16x32_bf16 v[104:107], v[156:159], v[172:175], v[104:107]
	v_mfma_f32_16x16x32_bf16 v[92:95], v[148:151], v[192:195], v[92:95]
	v_mfma_f32_16x16x32_bf16 v[88:91], v[156:159], v[192:195], v[88:91]
	v_mfma_f32_16x16x32_bf16 v[76:79], v[148:151], v[200:203], v[76:79]
	v_mfma_f32_16x16x32_bf16 v[72:75], v[156:159], v[200:203], v[72:75]
	s_setprio 0
	s_barrier
	s_add_i32 s34, 0, 0x1c000
	s_add_i32 s26, s51, s5
	v_add_u32_e32 v207, s34, v186
	v_lshl_add_u64 v[184:185], v[184:185], 0, s[16:17]
	s_mov_b32 m0, s26
	ds_read_b128 v[208:211], v207
	ds_read_b128 v[212:215], v207 offset:1024
	ds_read_b128 v[216:219], v207 offset:2048
	ds_read_b128 v[220:223], v207 offset:3072
	global_load_lds_dwordx4 v[184:185], off
	v_lshl_add_u64 v[184:185], v[204:205], 0, s[16:17]
	s_add_i32 m0, s26, 0x2000
	s_nop 0
	global_load_lds_dwordx4 v[184:185], off
	s_barrier
	s_waitcnt lgkmcnt(0)
	s_setprio 1
	v_mfma_f32_16x16x32_bf16 v[116:119], v[208:211], v[160:163], v[116:119]
	v_mfma_f32_16x16x32_bf16 v[112:115], v[216:219], v[160:163], v[112:115]
	v_mfma_f32_16x16x32_bf16 v[100:103], v[208:211], v[168:171], v[100:103]
	v_mfma_f32_16x16x32_bf16 v[96:99], v[216:219], v[168:171], v[96:99]
	v_mfma_f32_16x16x32_bf16 v[84:87], v[208:211], v[180:183], v[84:87]
	v_mfma_f32_16x16x32_bf16 v[80:83], v[216:219], v[180:183], v[80:83]
	v_mfma_f32_16x16x32_bf16 v[68:71], v[208:211], v[196:199], v[68:71]
	v_mfma_f32_16x16x32_bf16 v[64:67], v[216:219], v[196:199], v[64:67]
	v_mfma_f32_16x16x32_bf16 v[116:119], v[212:215], v[164:167], v[116:119]
	v_mfma_f32_16x16x32_bf16 v[112:115], v[220:223], v[164:167], v[112:115]
	v_mfma_f32_16x16x32_bf16 v[100:103], v[212:215], v[172:175], v[100:103]
	v_mfma_f32_16x16x32_bf16 v[96:99], v[220:223], v[172:175], v[96:99]
	v_mfma_f32_16x16x32_bf16 v[84:87], v[212:215], v[192:195], v[84:87]
	v_mfma_f32_16x16x32_bf16 v[80:83], v[220:223], v[192:195], v[80:83]
	v_mfma_f32_16x16x32_bf16 v[68:71], v[212:215], v[200:203], v[68:71]
	v_mfma_f32_16x16x32_bf16 v[64:67], v[220:223], v[200:203], v[64:67]
	s_setprio 0
	s_mov_b32 m0, s40
	v_lshl_add_u64 v[184:185], v[224:225], 0, s[16:17]
	s_barrier
	ds_read_b128 v[160:163], v189 offset:49152
	ds_read_b128 v[164:167], v189 offset:50176
	ds_read_b128 v[168:171], v189 offset:51200
	ds_read_b128 v[172:175], v189 offset:52224
	ds_read_b128 v[180:183], v189 offset:53248
	ds_read_b128 v[192:195], v189 offset:54272
	ds_read_b128 v[196:199], v189 offset:55296
	ds_read_b128 v[200:203], v189 offset:56320
	global_load_lds_dwordx4 v[184:185], off
	v_lshl_add_u64 v[184:185], v[226:227], 0, s[16:17]
	s_mov_b32 m0, s41
	s_nop 0
	global_load_lds_dwordx4 v[184:185], off
	s_barrier
; #define PG8_STAGE(bufoff, gbase, voff) do { _Pragma("unroll") for (int _i = 0; _i < 2; ++_i) \
;         __builtin_amdgcn_global_load_lds((const unsigned*)((const char*)(gbase) + (voff)[_i]), (PG8_LAS unsigned*)(lds + (bufoff) + ldsw + _i * 8192), 16, 0, 0); } while (0)
; #define PG8_MMA(ai, bj, At, Bt) do { __builtin_amdgcn_s_setprio(1); _Pragma("unroll") for (int m = 0; m < 4; ++m) _Pragma("unroll") for (int n = 0; n < 2; ++n) _Pragma("unroll") for (int k = 0; k < 2; ++k) \
;         acc[ai][bj][m][n] = __builtin_amdgcn_mfma_f32_16x16x32_bf16(Bt[n][k], At[m][k], acc[ai][bj][m][n], 0, 0, 0); __builtin_amdgcn_s_setprio(0); } while (0)
; #define PG8_WAIT_V(n) asm volatile("s_waitcnt vmcnt(" #n ")" ::: "memory")
; #define PG8_WAIT_L(n) asm volatile("s_waitcnt lgkmcnt(" #n ")" ::: "memory")
; #define PG8_BAR __builtin_amdgcn_s_barrier()
; #define PG8_SCHED __builtin_amdgcn_sched_barrier(0)
; template <class Epi, class Sched>
; __device__ __forceinline__ void gemm_phase(PG8_LAS unsigned char* lds, const Gemm g, const Sched& S, const Epi& E) {
;     ...
;             PG8_BAR; PG8_WAIT_L(0); PG8_MMA(1, 0, At, B0); PG8_BAR; PG8_SCHED;
;             PG8_STAGE(PG8_SB(1, 1), b3 + hstep, voffB);
;             PG8_WAIT_V(6); PG8_BAR; PG8_MMA(1, 1, At, B1); PG8_BAR;
;     __device__ __forceinline__ void operator()(const f32x4 (&acc)[2][2][4][2], const Unit& u, int wr, int wc, int fr, int fq, const float (&epre)[1]) const {
;         const int row0 = u.pm * 256 + wr * 64 + fr, col0 = u.pn * 256 + wc * 32 + 8 * fq;
; #pragma unroll
;         for (int ai = 0; ai < 2; ++ai) {
;             float ssv[4];
;             f32x4 bv[4][2][2];
; #pragma unroll
;             for (int m = 0; m < 4; ++m) { const int row = row0 + ai * 128 + m * 16;
; #pragma unroll
;                 for (int bj = 0; bj < 2; ++bj) {
;                     if (BASEBF) { unpack8(*(const u32x4*)(HB + (size_t)row * DM + col0 + bj * 128), bv[m][bj][0], bv[m][bj][1]); }
	s_waitcnt lgkmcnt(0)
	s_setprio 1
	v_mfma_f32_16x16x32_bf16 v[60:63], v[144:147], v[160:163], v[60:63]
	v_mfma_f32_16x16x32_bf16 v[56:59], v[152:155], v[160:163], v[56:59]
	v_mfma_f32_16x16x32_bf16 v[44:47], v[144:147], v[168:171], v[44:47]
	v_mfma_f32_16x16x32_bf16 v[40:43], v[152:155], v[168:171], v[40:43]
	v_mfma_f32_16x16x32_bf16 v[28:31], v[144:147], v[180:183], v[28:31]
	v_mfma_f32_16x16x32_bf16 v[24:27], v[152:155], v[180:183], v[24:27]
	v_mfma_f32_16x16x32_bf16 v[12:15], v[144:147], v[196:199], v[12:15]
	v_mfma_f32_16x16x32_bf16 v[8:11], v[152:155], v[196:199], v[8:11]
	v_mfma_f32_16x16x32_bf16 v[60:63], v[148:151], v[164:167], v[60:63]
	v_mfma_f32_16x16x32_bf16 v[56:59], v[156:159], v[164:167], v[56:59]
	v_mfma_f32_16x16x32_bf16 v[44:47], v[148:151], v[172:175], v[44:47]
	v_mfma_f32_16x16x32_bf16 v[40:43], v[156:159], v[172:175], v[40:43]
	v_mfma_f32_16x16x32_bf16 v[28:31], v[148:151], v[192:195], v[28:31]
	v_mfma_f32_16x16x32_bf16 v[24:27], v[156:159], v[192:195], v[24:27]
	v_mfma_f32_16x16x32_bf16 v[12:15], v[148:151], v[200:203], v[12:15]
	v_mfma_f32_16x16x32_bf16 v[8:11], v[156:159], v[200:203], v[8:11]
	s_setprio 0
	s_barrier
	s_add_u32 s26, s30, 0xb0080
	s_addc_u32 s27, s31, 0
	s_add_i32 s30, s34, s5
	v_lshl_add_u64 v[144:145], s[26:27], 0, v[130:131]
	s_mov_b32 m0, s30
	s_nop 0
	global_load_lds_dwordx4 v[144:145], off
	v_lshl_add_u64 v[144:145], s[26:27], 0, v[134:135]
	s_add_i32 m0, s30, 0x2000
	s_nop 0
	global_load_lds_dwordx4 v[144:145], off
	s_waitcnt vmcnt(6)
	s_barrier
	s_setprio 1
	v_mfma_f32_16x16x32_bf16 v[52:55], v[208:211], v[160:163], v[52:55]
	v_mfma_f32_16x16x32_bf16 v[48:51], v[216:219], v[160:163], v[48:51]
	v_mfma_f32_16x16x32_bf16 v[36:39], v[208:211], v[168:171], v[36:39]
	v_mfma_f32_16x16x32_bf16 v[32:35], v[216:219], v[168:171], v[32:35]
	v_mfma_f32_16x16x32_bf16 v[20:23], v[208:211], v[180:183], v[20:23]
	v_mfma_f32_16x16x32_bf16 v[16:19], v[216:219], v[180:183], v[16:19]
	v_mfma_f32_16x16x32_bf16 v[4:7], v[208:211], v[196:199], v[4:7]
	v_mfma_f32_16x16x32_bf16 v[0:3], v[216:219], v[196:199], v[0:3]
	v_mfma_f32_16x16x32_bf16 v[52:55], v[212:215], v[164:167], v[52:55]
	v_mfma_f32_16x16x32_bf16 v[48:51], v[220:223], v[164:167], v[48:51]
	v_mfma_f32_16x16x32_bf16 v[36:39], v[212:215], v[172:175], v[36:39]
	v_mfma_f32_16x16x32_bf16 v[32:35], v[220:223], v[172:175], v[32:35]
	v_mfma_f32_16x16x32_bf16 v[20:23], v[212:215], v[192:195], v[20:23]
	v_mfma_f32_16x16x32_bf16 v[16:19], v[220:223], v[192:195], v[16:19]
	v_mfma_f32_16x16x32_bf16 v[4:7], v[212:215], v[200:203], v[4:7]
	v_mfma_f32_16x16x32_bf16 v[0:3], v[220:223], v[200:203], v[0:3]
	s_setprio 0
	s_add_i32 s50, s50, 2
	s_add_u32 s48, s48, 0x100
	s_addc_u32 s49, s49, 0
	s_cmp_gt_u32 s50, 41
	s_mov_b64 s[26:27], s[28:29]
	s_barrier
	s_cbranch_scc0 .LBB0_780
	v_lshl_or_b32 v144, s47, 8, v187
	v_lshl_add_u32 v150, s46, 8, v177
	v_ashrrev_i32_e32 v145, 31, v144
	v_ashrrev_i32_e32 v151, 31, v150
	v_lshlrev_b64 v[144:145], 1, v[144:145]
	v_lshl_add_u64 v[146:147], s[84:85], 0, v[144:145]
	v_lshlrev_b64 v[148:149], 11, v[150:151]
	v_lshl_add_u64 v[152:153], v[146:147], 0, v[148:149]
	global_load_dwordx4 v[154:157], v[152:153], off
	global_load_dwordx4 v[158:161], v[152:153], off offset:256
	v_or_b32_e32 v152, 16, v150
	v_ashrrev_i32_e32 v153, 31, v152
	v_lshlrev_b64 v[184:185], 11, v[152:153]
	v_lshl_add_u64 v[152:153], v[146:147], 0, v[184:185]
	global_load_dwordx4 v[164:167], v[152:153], off
	global_load_dwordx4 v[168:171], v[152:153], off offset:256
	v_or_b32_e32 v152, 32, v150
	v_ashrrev_i32_e32 v153, 31, v152
	v_lshlrev_b64 v[162:163], 11, v[152:153]
	v_lshl_add_u64 v[152:153], v[146:147], 0, v[162:163]
	global_load_dwordx4 v[172:175], v[152:153], off
	global_load_dwordx4 v[192:195], v[152:153], off offset:256
	v_or_b32_e32 v152, 48, v150
	v_ashrrev_i32_e32 v153, 31, v152
	v_lshlrev_b64 v[152:153], 11, v[152:153]
	v_lshl_add_u64 v[180:181], v[146:147], 0, v[152:153]
	global_load_dwordx4 v[196:199], v[180:181], off
	global_load_dwordx4 v[200:203], v[180:181], off offset:256
	s_waitcnt vmcnt(0)
	v_lshlrev_b32_e32 v204, 16, v154
	v_and_b32_e32 v205, 0xffff0000, v154
	v_lshlrev_b32_e32 v208, 16, v155
	v_and_b32_e32 v209, 0xffff0000, v155
	v_lshlrev_b32_e32 v210, 16, v156
	v_and_b32_e32 v211, 0xffff0000, v156
	v_lshlrev_b32_e32 v226, 16, v166
	v_and_b32_e32 v227, 0xffff0000, v166
	v_lshlrev_b32_e32 v228, 16, v167
	v_and_b32_e32 v229, 0xffff0000, v167
	v_lshlrev_b32_e32 v234, 16, v170
	v_and_b32_e32 v235, 0xffff0000, v170
	v_lshlrev_b32_e32 v236, 16, v171
	v_and_b32_e32 v237, 0xffff0000, v171
	v_lshlrev_b32_e32 v212, 16, v157
	v_lshlrev_b32_e32 v166, 16, v196
	v_and_b32_e32 v167, 0xffff0000, v196
	v_lshlrev_b32_e32 v170, 16, v197
	v_and_b32_e32 v171, 0xffff0000, v197
	v_lshl_add_u64 v[196:197], s[84:85], 0, v[148:149]
	v_and_b32_e32 v213, 0xffff0000, v157
	v_lshlrev_b32_e32 v238, 16, v172
	v_and_b32_e32 v239, 0xffff0000, v172
	v_lshlrev_b32_e32 v240, 16, v173
	v_and_b32_e32 v241, 0xffff0000, v173
	v_lshlrev_b32_e32 v172, 16, v194
	v_and_b32_e32 v173, 0xffff0000, v194
	v_lshlrev_b32_e32 v180, 16, v195
	v_and_b32_e32 v181, 0xffff0000, v195
	v_pk_add_f32 v[126:127], v[126:127], v[208:209]
	v_pk_add_f32 v[124:125], v[124:125], v[204:205]
	v_pk_add_f32 v[194:195], v[120:121], v[210:211]
	v_cvt_pk_bf16_f32 v120, v124, v125
	v_cvt_pk_bf16_f32 v121, v126, v127
	v_lshl_add_u64 v[196:197], v[196:197], 0, v[144:145]
	v_lshlrev_b32_e32 v242, 16, v174
	v_and_b32_e32 v243, 0xffff0000, v174
	v_lshlrev_b32_e32 v244, 16, v175
	v_and_b32_e32 v245, 0xffff0000, v175
	v_lshlrev_b32_e32 v174, 16, v192
	v_and_b32_e32 v175, 0xffff0000, v192
	v_lshlrev_b32_e32 v182, 16, v193
; __device__ __forceinline__ unsigned cvt_pk_bf16(float lo, float hi) { unsigned r; asm volatile("v_cvt_pk_bf16_f32 %0, %1, %2" : "=v"(r) : "v"(lo), "v"(hi)); return r; }
;     __device__ __forceinline__ void operator()(const f32x4 (&acc)[2][2][4][2], const Unit& u, int wr, int wc, int fr, int fq, const float (&epre)[1]) const {
;     ...
;             for (int m = 0; m < 4; ++m) { const int row = row0 + ai * 128 + m * 16;
;                 float ss = 0.f;
; #pragma unroll
;                 for (int bj = 0; bj < 2; ++bj) { const f32x4 h0 = bv[m][bj][0] + acc[ai][bj][m][0], h1 = bv[m][bj][1] + acc[ai][bj][m][1];
;                     u32x4 w; w.x = cvt_pk_bf16(h0[0], h0[1]); w.y = cvt_pk_bf16(h0[2], h0[3]); w.z = cvt_pk_bf16(h1[0], h1[1]); w.w = cvt_pk_bf16(h1[2], h1[3]);
;                     *(u32x4*)(HBo + (size_t)row * DM + col0 + bj * 128) = w;
;                     ss += (h0[0] * h0[0] + h0[1] * h0[1]) + (h0[2] * h0[2] + h0[3] * h0[3]) + (h1[0] * h1[0] + h1[1] * h1[1]) + (h1[2] * h1[2] + h1[3] * h1[3]); }
;                 ssv[m] = ss;
;             }
	v_and_b32_e32 v183, 0xffff0000, v193
	v_pk_add_f32 v[192:193], v[122:123], v[212:213]
	v_cvt_pk_bf16_f32 v122, v194, v195
	v_lshlrev_b32_e32 v214, 16, v158
	v_cvt_pk_bf16_f32 v123, v192, v193
	global_store_dwordx4 v[196:197], v[120:123], off
	v_and_b32_e32 v215, 0xffff0000, v158
	v_lshlrev_b32_e32 v216, 16, v159
	v_mul_f32_e32 v120, v125, v125
	v_mul_f32_e32 v121, v127, v127
	v_fmac_f32_e32 v120, v124, v124
	v_fmac_f32_e32 v121, v126, v126
	v_add_f32_e32 v120, v120, v121
	v_mul_f32_e32 v121, v195, v195
	v_fmac_f32_e32 v121, v194, v194
	v_and_b32_e32 v217, 0xffff0000, v159
	v_lshlrev_b32_e32 v218, 16, v160
	v_and_b32_e32 v219, 0xffff0000, v160
	v_add_f32_e32 v120, v121, v120
	v_mul_f32_e32 v121, v193, v193
	v_lshlrev_b32_e32 v220, 16, v161
	v_and_b32_e32 v221, 0xffff0000, v161
	v_fmac_f32_e32 v121, v192, v192
	v_pk_add_f32 v[118:119], v[118:119], v[216:217]
	v_pk_add_f32 v[116:117], v[116:117], v[214:215]
	v_pk_add_f32 v[122:123], v[112:113], v[218:219]
	v_cvt_pk_bf16_f32 v112, v116, v117
	v_cvt_pk_bf16_f32 v113, v118, v119
	v_add_f32_e32 v124, v121, v120
	v_pk_add_f32 v[120:121], v[114:115], v[220:221]
	v_cvt_pk_bf16_f32 v114, v122, v123
	v_lshlrev_b32_e32 v222, 16, v164
	v_cvt_pk_bf16_f32 v115, v120, v121
	global_store_dwordx4 v[196:197], v[112:115], off offset:256
	v_and_b32_e32 v223, 0xffff0000, v164
	v_lshlrev_b32_e32 v224, 16, v165
	v_mul_f32_e32 v112, v117, v117
	v_mul_f32_e32 v113, v119, v119
	v_fmac_f32_e32 v112, v116, v116
	v_fmac_f32_e32 v113, v118, v118
	v_add_f32_e32 v112, v112, v113
	v_mul_f32_e32 v113, v123, v123
	v_fmac_f32_e32 v113, v122, v122
	v_add_f32_e32 v112, v113, v112
	v_mul_f32_e32 v113, v121, v121
	v_and_b32_e32 v225, 0xffff0000, v165
	v_fmac_f32_e32 v113, v120, v120
	v_lshl_add_u64 v[116:117], s[84:85], 0, v[184:185]
	v_add_f32_e32 v112, v113, v112
	v_pk_add_f32 v[110:111], v[110:111], v[224:225]
	v_pk_add_f32 v[108:109], v[108:109], v[222:223]
	v_pk_add_f32 v[114:115], v[104:105], v[226:227]
	v_cvt_pk_bf16_f32 v104, v108, v109
	v_cvt_pk_bf16_f32 v105, v110, v111
	v_lshl_add_u64 v[116:117], v[116:117], 0, v[144:145]
	v_add_f32_e32 v118, v124, v112
	v_pk_add_f32 v[112:113], v[106:107], v[228:229]
	v_cvt_pk_bf16_f32 v106, v114, v115
	v_lshlrev_b32_e32 v230, 16, v168
	v_cvt_pk_bf16_f32 v107, v112, v113
	global_store_dwordx4 v[116:117], v[104:107], off
	v_and_b32_e32 v231, 0xffff0000, v168
	v_lshlrev_b32_e32 v232, 16, v169
	v_mul_f32_e32 v104, v109, v109
	v_mul_f32_e32 v105, v111, v111
	v_fmac_f32_e32 v104, v108, v108
	v_fmac_f32_e32 v105, v110, v110
	v_add_f32_e32 v104, v104, v105
	v_mul_f32_e32 v105, v115, v115
	v_fmac_f32_e32 v105, v114, v114
	v_and_b32_e32 v233, 0xffff0000, v169
	v_add_f32_e32 v104, v105, v104
	v_mul_f32_e32 v105, v113, v113
	v_fmac_f32_e32 v105, v112, v112
	v_pk_add_f32 v[102:103], v[102:103], v[232:233]
	v_pk_add_f32 v[100:101], v[100:101], v[230:231]
	v_pk_add_f32 v[106:107], v[96:97], v[234:235]
	v_cvt_pk_bf16_f32 v96, v100, v101
	v_cvt_pk_bf16_f32 v97, v102, v103
	v_add_f32_e32 v108, v105, v104
	v_pk_add_f32 v[104:105], v[98:99], v[236:237]
	v_cvt_pk_bf16_f32 v98, v106, v107
	v_pk_add_f32 v[94:95], v[94:95], v[240:241]
	v_cvt_pk_bf16_f32 v99, v104, v105
	global_store_dwordx4 v[116:117], v[96:99], off offset:256
	v_pk_add_f32 v[92:93], v[92:93], v[238:239]
	v_pk_add_f32 v[86:87], v[86:87], v[182:183]
	v_mul_f32_e32 v96, v101, v101
	v_mul_f32_e32 v97, v103, v103
	v_fmac_f32_e32 v96, v100, v100
	v_fmac_f32_e32 v97, v102, v102
	v_add_f32_e32 v96, v96, v97
	v_mul_f32_e32 v97, v107, v107
	v_fmac_f32_e32 v97, v106, v106
	v_add_f32_e32 v96, v97, v96
	v_mul_f32_e32 v97, v105, v105
	v_fmac_f32_e32 v97, v104, v104
	v_lshl_add_u64 v[100:101], s[84:85], 0, v[162:163]
	v_add_f32_e32 v96, v97, v96
	v_pk_add_f32 v[98:99], v[88:89], v[242:243]
	v_cvt_pk_bf16_f32 v88, v92, v93
	v_cvt_pk_bf16_f32 v89, v94, v95
	v_lshl_add_u64 v[100:101], v[100:101], 0, v[144:145]
	v_add_f32_e32 v102, v108, v96
	v_pk_add_f32 v[96:97], v[90:91], v[244:245]
	v_cvt_pk_bf16_f32 v90, v98, v99
	v_pk_add_f32 v[84:85], v[84:85], v[174:175]
	v_cvt_pk_bf16_f32 v91, v96, v97
	global_store_dwordx4 v[100:101], v[88:91], off
; __device__ __forceinline__ unsigned cvt_pk_bf16(float lo, float hi) { unsigned r; asm volatile("v_cvt_pk_bf16_f32 %0, %1, %2" : "=v"(r) : "v"(lo), "v"(hi)); return r; }
;     __device__ __forceinline__ void operator()(const f32x4 (&acc)[2][2][4][2], const Unit& u, int wr, int wc, int fr, int fq, const float (&epre)[1]) const {
;     ...
;             for (int m = 0; m < 4; ++m) { const int row = row0 + ai * 128 + m * 16;
;                 float ss = 0.f;
; #pragma unroll
;                 for (int bj = 0; bj < 2; ++bj) { const f32x4 h0 = bv[m][bj][0] + acc[ai][bj][m][0], h1 = bv[m][bj][1] + acc[ai][bj][m][1];
;                     u32x4 w; w.x = cvt_pk_bf16(h0[0], h0[1]); w.y = cvt_pk_bf16(h0[2], h0[3]); w.z = cvt_pk_bf16(h1[0], h1[1]); w.w = cvt_pk_bf16(h1[2], h1[3]);
;                     *(u32x4*)(HBo + (size_t)row * DM + col0 + bj * 128) = w;
;                     ss += (h0[0] * h0[0] + h0[1] * h0[1]) + (h0[2] * h0[2] + h0[3] * h0[3]) + (h1[0] * h1[0] + h1[1] * h1[1]) + (h1[2] * h1[2] + h1[3] * h1[3]); }
;                 ssv[m] = ss;
;             }
; #pragma unroll
;             for (int m = 0; m < 4; ++m) ssv[m] += __shfl_xor(ssv[m], 16);
; #pragma unroll
;             for (int m = 0; m < 4; ++m) ssv[m] += __shfl_xor(ssv[m], 32);
;             if (fq == 0) {
; #pragma unroll
;                 for (int m = 0; m < 4; ++m) atomicAdd(sumsq + row0 + ai * 128 + m * 16, ssv[m]); }
	v_lshlrev_b32_e32 v164, 16, v198
	v_and_b32_e32 v165, 0xffff0000, v198
	v_mul_f32_e32 v88, v93, v93
	v_mul_f32_e32 v89, v95, v95
	v_fmac_f32_e32 v88, v92, v92
	v_fmac_f32_e32 v89, v94, v94
	v_add_f32_e32 v88, v88, v89
	v_mul_f32_e32 v89, v99, v99
	v_fmac_f32_e32 v89, v98, v98
	v_add_f32_e32 v88, v89, v88
	v_mul_f32_e32 v89, v97, v97
	v_fmac_f32_e32 v89, v96, v96
	v_pk_add_f32 v[90:91], v[80:81], v[172:173]
	v_cvt_pk_bf16_f32 v80, v84, v85
	v_cvt_pk_bf16_f32 v81, v86, v87
	v_add_f32_e32 v92, v89, v88
	v_pk_add_f32 v[88:89], v[82:83], v[180:181]
	v_cvt_pk_bf16_f32 v82, v90, v91
	v_lshlrev_b32_e32 v168, 16, v199
	v_cvt_pk_bf16_f32 v83, v88, v89
	global_store_dwordx4 v[100:101], v[80:83], off offset:256
	v_and_b32_e32 v169, 0xffff0000, v199
	v_lshlrev_b32_e32 v156, 16, v200
	v_mul_f32_e32 v80, v85, v85
	v_mul_f32_e32 v81, v87, v87
	v_fmac_f32_e32 v80, v84, v84
	v_fmac_f32_e32 v81, v86, v86
	v_add_f32_e32 v80, v80, v81
	v_mul_f32_e32 v81, v91, v91
	v_fmac_f32_e32 v81, v90, v90
	v_add_f32_e32 v80, v81, v80
	v_mul_f32_e32 v81, v89, v89
	v_fmac_f32_e32 v81, v88, v88
	v_lshl_add_u64 v[84:85], s[84:85], 0, v[152:153]
	v_and_b32_e32 v157, 0xffff0000, v200
	v_lshlrev_b32_e32 v160, 16, v201
	v_and_b32_e32 v161, 0xffff0000, v201
	v_add_f32_e32 v80, v81, v80
	v_pk_add_f32 v[78:79], v[78:79], v[170:171]
	v_pk_add_f32 v[76:77], v[76:77], v[166:167]
	v_pk_add_f32 v[82:83], v[72:73], v[164:165]
	v_cvt_pk_bf16_f32 v72, v76, v77
	v_cvt_pk_bf16_f32 v73, v78, v79
	v_lshl_add_u64 v[84:85], v[84:85], 0, v[144:145]
	v_lshlrev_b32_e32 v158, 16, v203
	v_and_b32_e32 v159, 0xffff0000, v203
	v_add_f32_e32 v86, v92, v80
	v_pk_add_f32 v[80:81], v[74:75], v[168:169]
	v_cvt_pk_bf16_f32 v74, v82, v83
	v_pk_add_f32 v[70:71], v[70:71], v[160:161]
	v_cvt_pk_bf16_f32 v75, v80, v81
	global_store_dwordx4 v[84:85], v[72:75], off
	v_pk_add_f32 v[68:69], v[68:69], v[156:157]
	v_lshlrev_b32_e32 v154, 16, v202
	v_mul_f32_e32 v73, v79, v79
	v_and_b32_e32 v155, 0xffff0000, v202
	v_mul_f32_e32 v72, v77, v77
	v_fmac_f32_e32 v73, v78, v78
	v_pk_add_f32 v[78:79], v[66:67], v[158:159]
	v_mul_f32_e32 v66, v69, v69
	v_mul_f32_e32 v67, v71, v71
	v_fmac_f32_e32 v72, v76, v76
	v_pk_add_f32 v[64:65], v[64:65], v[154:155]
	v_fmac_f32_e32 v66, v68, v68
	v_fmac_f32_e32 v67, v70, v70
	v_add_f32_e32 v72, v72, v73
	v_mul_f32_e32 v73, v83, v83
	v_add_f32_e32 v66, v66, v67
	v_mul_f32_e32 v67, v65, v65
	v_fmac_f32_e32 v73, v82, v82
	v_fmac_f32_e32 v67, v64, v64
	v_add_f32_e32 v72, v73, v72
	v_mul_f32_e32 v73, v81, v81
	v_add_f32_e32 v66, v67, v66
	v_mul_f32_e32 v67, v79, v79
	v_fmac_f32_e32 v73, v80, v80
	v_fmac_f32_e32 v67, v78, v78
	v_add_f32_e32 v72, v73, v72
	v_add_f32_e32 v66, v67, v66
	v_and_b32_e32 v67, 64, v191
	v_cvt_pk_bf16_f32 v74, v68, v69
	v_add_f32_e32 v69, v72, v66
	v_xor_b32_e32 v66, 16, v191
	v_add_u32_e32 v72, 64, v67
	v_cmp_lt_i32_e32 vcc, v66, v72
	v_cvt_pk_bf16_f32 v75, v70, v71
	v_xor_b32_e32 v70, 32, v191
	v_cvt_pk_bf16_f32 v76, v64, v65
	v_lshl_add_u64 v[64:65], v[150:151], 2, s[14:15]
	v_cndmask_b32_e32 v66, v191, v66, vcc
	v_lshlrev_b32_e32 v94, 2, v66
	ds_bpermute_b32 v66, v94, v118
	ds_bpermute_b32 v67, v94, v102
	ds_bpermute_b32 v68, v94, v86
	ds_bpermute_b32 v73, v94, v69
	v_cmp_lt_i32_e32 vcc, v70, v72
	s_waitcnt lgkmcnt(0)
	v_add_f32_e32 v66, v118, v66
	v_add_f32_e32 v67, v102, v67
	v_cndmask_b32_e32 v70, v191, v70, vcc
	v_add_f32_e32 v68, v86, v68
	v_add_f32_e32 v69, v69, v73
	v_lshlrev_b32_e32 v95, 2, v70
	ds_bpermute_b32 v70, v95, v66
	ds_bpermute_b32 v71, v95, v67
	ds_bpermute_b32 v72, v95, v68
	ds_bpermute_b32 v73, v95, v69
	v_cvt_pk_bf16_f32 v77, v78, v79
	global_store_dwordx4 v[84:85], v[74:77], off offset:256
	s_and_saveexec_b64 s[26:27], s[6:7]
	s_cbranch_execz .LBB0_783
	s_waitcnt lgkmcnt(3)
	v_add_f32_e32 v66, v66, v70
	s_waitcnt lgkmcnt(0)
	v_add_f32_e32 v69, v69, v73
	v_add_f32_e32 v68, v68, v72
	v_add_f32_e32 v67, v67, v71
	global_atomic_add_f32 v[64:65], v66, off
	global_atomic_add_f32 v[64:65], v67, off offset:64
	global_atomic_add_f32 v[64:65], v68, off offset:128
	global_atomic_add_f32 v[64:65], v69, off offset:192

; #define PG8_STAGE(bufoff, gbase, voff) do { _Pragma("unroll") for (int _i = 0; _i < 2; ++_i) \
;         __builtin_amdgcn_global_load_lds((const unsigned*)((const char*)(gbase) + (voff)[_i]), (PG8_LAS unsigned*)(lds + (bufoff) + ldsw + _i * 8192), 16, 0, 0); } while (0)
; #define PG8_LDA(dst, b, h) do { _Pragma("unroll") for (int m = 0; m < 4; ++m) _Pragma("unroll") for (int k = 0; k < 2; ++k) dst[m][k] = *(const PG8_LAS bf16x8*)(lds + PG8_SA(b, h) + aoff + m * 2048 + k * 1024); } while (0)
; #define PG8_LDB(dst, b, h) do { _Pragma("unroll") for (int n = 0; n < 2; ++n) _Pragma("unroll") for (int k = 0; k < 2; ++k) dst[n][k] = *(const PG8_LAS bf16x8*)(lds + PG8_SB(b, h) + boff + n * 2048 + k * 1024); } while (0)
; #define PG8_MMA(ai, bj, At, Bt) do { __builtin_amdgcn_s_setprio(1); _Pragma("unroll") for (int m = 0; m < 4; ++m) _Pragma("unroll") for (int n = 0; n < 2; ++n) _Pragma("unroll") for (int k = 0; k < 2; ++k) \
;         acc[ai][bj][m][n] = __builtin_amdgcn_mfma_f32_16x16x32_bf16(Bt[n][k], At[m][k], acc[ai][bj][m][n], 0, 0, 0); __builtin_amdgcn_s_setprio(0); } while (0)
; template <class Epi, class Sched>
; __device__ __forceinline__ void gemm_phase(PG8_LAS unsigned char* lds, const Gemm g, const Sched& S, const Epi& E) {
;     ...
;         const bool has_next = S.next(ui + 1, nxt);
;         const char* nA = has_next ? (const char*)g.A + (size_t)nxt.pm * tstep : cA; const char* nB = has_next ? (const char*)g.Bt + (size_t)nxt.pn * tstep : cB;
;         for (int t = 0; t < nt; t += 2) {
;             const bool last = (t == nt - 2);
;             const char* a1 = cA + (size_t)(t + 1) * kstep;
;             const char* a2 = last ? nA : cA + (size_t)(t + 2) * kstep; const char* b2 = last ? nB : cB + (size_t)(t + 2) * kstep;
;             const char* a3 = a2 + kstep; const char* b3 = b2 + kstep;
;             if (last && has_next) S.a_ready(nxt);
;             PG8_LDB(B0, 0, 0); PG8_SCHED; PG8_LDA(At, 0, 0); PG8_STAGE(PG8_SA(1, 1), a1 + hstep, voffA);
;             PG8_WAIT_L(8); PG8_BAR; PG8_WAIT_L(0); PG8_MMA(0, 0, At, B0); PG8_BAR; PG8_SCHED;
;             PG8_LDB(B1, 0, 1); PG8_STAGE(PG8_SB(0, 0), b2, voffB);
;             PG8_BAR; PG8_WAIT_L(0); PG8_MMA(0, 1, At, B1); PG8_BAR;
;             PG8_LDA(At, 0, 1); PG8_STAGE(PG8_SA(0, 0), a2, voffA);
;             PG8_BAR; PG8_WAIT_L(0); PG8_MMA(1, 0, At, B0); PG8_BAR; PG8_SCHED;
.LBB0_857:
	s_ashr_i32 s31, s30, 31
	s_lshl_b64 s[34:35], s[30:31], 17
	s_add_u32 s34, s74, s34
	v_cmp_lt_i64_e32 vcc, s[26:27], v[48:49]
	s_addc_u32 s35, s75, s35
	ds_read_b128 v[0:3], v57
	ds_read_b128 v[4:7], v57 offset:1024
	ds_read_b128 v[8:11], v57 offset:2048
	ds_read_b128 v[12:15], v57 offset:3072
	s_and_b64 s[36:37], vcc, exec
	s_cselect_b32 s47, s35, s41
	s_cselect_b32 s46, s34, s40
	s_ashr_i32 s29, s28, 31
	s_lshl_b64 s[36:37], s[28:29], 17
	s_add_u32 s36, s8, s36
	s_addc_u32 s37, s9, s37
	s_and_b64 s[44:45], vcc, exec
	s_cselect_b32 s45, s37, s43
	s_cselect_b32 s44, s36, s42
	s_add_u32 s64, s40, 0x10080
	s_addc_u32 s65, s41, 0
	s_mov_b32 m0, s51
	v_lshl_add_u64 v[52:53], s[64:65], 0, v[40:41]
	ds_read_b128 v[16:19], v58
	ds_read_b128 v[20:23], v58 offset:1024
	ds_read_b128 v[24:27], v58 offset:2048
	ds_read_b128 v[28:31], v58 offset:3072
	ds_read_b128 v[32:35], v58 offset:4096
	ds_read_b128 v[36:39], v58 offset:5120
	ds_read_b128 v[60:63], v58 offset:6144
	ds_read_b128 v[64:67], v58 offset:7168
	global_load_lds_dwordx4 v[52:53], off
	v_lshl_add_u64 v[52:53], s[64:65], 0, v[44:45]
	s_mov_b32 m0, s52
	s_nop 0
	global_load_lds_dwordx4 v[52:53], off
	s_waitcnt lgkmcnt(8)
	s_barrier
	s_waitcnt lgkmcnt(0)
	s_setprio 1
	v_mfma_f32_16x16x32_bf16 v[68:71], v[0:3], v[16:19], 0
	v_mfma_f32_16x16x32_bf16 v[72:75], v[8:11], v[16:19], 0
	v_mfma_f32_16x16x32_bf16 v[76:79], v[0:3], v[24:27], 0
	v_mfma_f32_16x16x32_bf16 v[80:83], v[8:11], v[24:27], 0
	v_mfma_f32_16x16x32_bf16 v[84:87], v[0:3], v[32:35], 0
	v_mfma_f32_16x16x32_bf16 v[88:91], v[8:11], v[32:35], 0
	v_mfma_f32_16x16x32_bf16 v[92:95], v[0:3], v[60:63], 0
	v_mfma_f32_16x16x32_bf16 v[96:99], v[8:11], v[60:63], 0
	v_mfma_f32_16x16x32_bf16 v[68:71], v[4:7], v[20:23], v[68:71]
	v_mfma_f32_16x16x32_bf16 v[72:75], v[12:15], v[20:23], v[72:75]
	v_mfma_f32_16x16x32_bf16 v[76:79], v[4:7], v[28:31], v[76:79]
	v_mfma_f32_16x16x32_bf16 v[80:83], v[12:15], v[28:31], v[80:83]
	v_mfma_f32_16x16x32_bf16 v[84:87], v[4:7], v[36:39], v[84:87]
	v_mfma_f32_16x16x32_bf16 v[88:91], v[12:15], v[36:39], v[88:91]
	v_mfma_f32_16x16x32_bf16 v[92:95], v[4:7], v[64:67], v[92:95]
	v_mfma_f32_16x16x32_bf16 v[96:99], v[12:15], v[64:67], v[96:99]
	s_setprio 0
	s_barrier
	v_lshl_add_u64 v[52:53], s[42:43], 0, v[42:43]
	s_mov_b32 m0, s54
	v_lshl_add_u64 v[116:117], v[52:53], 0, s[12:13]
	v_lshl_add_u64 v[204:205], s[42:43], 0, v[46:47]
	s_add_i32 s3, s54, 0x2000
	ds_read_b128 v[100:103], v59
	ds_read_b128 v[104:107], v59 offset:1024
	ds_read_b128 v[108:111], v59 offset:2048
	ds_read_b128 v[112:115], v59 offset:3072
	global_load_lds_dwordx4 v[116:117], off
	v_lshl_add_u64 v[116:117], v[204:205], 0, s[12:13]
	s_mov_b32 m0, s3
	s_nop 0
	global_load_lds_dwordx4 v[116:117], off
	s_barrier
	s_waitcnt lgkmcnt(0)
	s_setprio 1
	v_mfma_f32_16x16x32_bf16 v[116:119], v[100:103], v[16:19], 0
	v_mfma_f32_16x16x32_bf16 v[16:19], v[108:111], v[16:19], 0
	v_mfma_f32_16x16x32_bf16 v[116:119], v[104:107], v[20:23], v[116:119]
	v_mfma_f32_16x16x32_bf16 v[16:19], v[112:115], v[20:23], v[16:19]
	v_mfma_f32_16x16x32_bf16 v[20:23], v[100:103], v[24:27], 0
	v_mfma_f32_16x16x32_bf16 v[24:27], v[108:111], v[24:27], 0
	v_mfma_f32_16x16x32_bf16 v[20:23], v[104:107], v[28:31], v[20:23]
	v_mfma_f32_16x16x32_bf16 v[24:27], v[112:115], v[28:31], v[24:27]
	v_mfma_f32_16x16x32_bf16 v[28:31], v[100:103], v[32:35], 0
	v_mfma_f32_16x16x32_bf16 v[32:35], v[108:111], v[32:35], 0
	v_mfma_f32_16x16x32_bf16 v[28:31], v[104:107], v[36:39], v[28:31]
	v_mfma_f32_16x16x32_bf16 v[32:35], v[112:115], v[36:39], v[32:35]
	v_mfma_f32_16x16x32_bf16 v[36:39], v[100:103], v[60:63], 0
	v_mfma_f32_16x16x32_bf16 v[60:63], v[108:111], v[60:63], 0
	v_mfma_f32_16x16x32_bf16 v[36:39], v[104:107], v[64:67], v[36:39]
	v_mfma_f32_16x16x32_bf16 v[60:63], v[112:115], v[64:67], v[60:63]
	s_setprio 0
	v_lshl_add_u64 v[220:221], s[40:41], 0, v[40:41]
	s_mov_b32 m0, s4
	v_lshl_add_u64 v[148:149], v[220:221], 0, s[12:13]
	v_lshl_add_u64 v[222:223], s[40:41], 0, v[44:45]
	s_barrier
	ds_read_b128 v[64:67], v58 offset:16384
	ds_read_b128 v[120:123], v58 offset:17408
	ds_read_b128 v[124:127], v58 offset:18432
	ds_read_b128 v[128:131], v58 offset:19456
	ds_read_b128 v[132:135], v58 offset:20480
	ds_read_b128 v[136:139], v58 offset:21504
	ds_read_b128 v[140:143], v58 offset:22528
	ds_read_b128 v[144:147], v58 offset:23552
	global_load_lds_dwordx4 v[148:149], off
	v_lshl_add_u64 v[148:149], v[222:223], 0, s[12:13]
	s_mov_b32 m0, s5
	s_nop 0
	global_load_lds_dwordx4 v[148:149], off
	s_barrier
	s_waitcnt lgkmcnt(0)
	s_setprio 1
	v_mfma_f32_16x16x32_bf16 v[148:151], v[0:3], v[64:67], 0
	v_mfma_f32_16x16x32_bf16 v[156:159], v[0:3], v[124:127], 0
	v_mfma_f32_16x16x32_bf16 v[164:167], v[0:3], v[132:135], 0
	v_mfma_f32_16x16x32_bf16 v[0:3], v[0:3], v[140:143], 0
	v_mfma_f32_16x16x32_bf16 v[148:151], v[4:7], v[120:123], v[148:151]
	v_mfma_f32_16x16x32_bf16 v[152:155], v[8:11], v[64:67], 0
	v_mfma_f32_16x16x32_bf16 v[156:159], v[4:7], v[128:131], v[156:159]
	v_mfma_f32_16x16x32_bf16 v[160:163], v[8:11], v[124:127], 0
	v_mfma_f32_16x16x32_bf16 v[164:167], v[4:7], v[136:139], v[164:167]
	v_mfma_f32_16x16x32_bf16 v[168:171], v[8:11], v[132:135], 0
	v_mfma_f32_16x16x32_bf16 v[0:3], v[4:7], v[144:147], v[0:3]
	v_mfma_f32_16x16x32_bf16 v[4:7], v[8:11], v[140:143], 0
	v_mfma_f32_16x16x32_bf16 v[152:155], v[12:15], v[120:123], v[152:155]
	v_mfma_f32_16x16x32_bf16 v[160:163], v[12:15], v[128:131], v[160:163]
	v_mfma_f32_16x16x32_bf16 v[168:171], v[12:15], v[136:139], v[168:171]
	v_mfma_f32_16x16x32_bf16 v[4:7], v[12:15], v[144:147], v[4:7]
	s_setprio 0
	s_barrier
; #define PG8_STAGE(bufoff, gbase, voff) do { _Pragma("unroll") for (int _i = 0; _i < 2; ++_i) \
;         __builtin_amdgcn_global_load_lds((const unsigned*)((const char*)(gbase) + (voff)[_i]), (PG8_LAS unsigned*)(lds + (bufoff) + ldsw + _i * 8192), 16, 0, 0); } while (0)
; #define PG8_LDA(dst, b, h) do { _Pragma("unroll") for (int m = 0; m < 4; ++m) _Pragma("unroll") for (int k = 0; k < 2; ++k) dst[m][k] = *(const PG8_LAS bf16x8*)(lds + PG8_SA(b, h) + aoff + m * 2048 + k * 1024); } while (0)
; #define PG8_LDB(dst, b, h) do { _Pragma("unroll") for (int n = 0; n < 2; ++n) _Pragma("unroll") for (int k = 0; k < 2; ++k) dst[n][k] = *(const PG8_LAS bf16x8*)(lds + PG8_SB(b, h) + boff + n * 2048 + k * 1024); } while (0)
; #define PG8_MMA(ai, bj, At, Bt) do { __builtin_amdgcn_s_setprio(1); _Pragma("unroll") for (int m = 0; m < 4; ++m) _Pragma("unroll") for (int n = 0; n < 2; ++n) _Pragma("unroll") for (int k = 0; k < 2; ++k) \
;         acc[ai][bj][m][n] = __builtin_amdgcn_mfma_f32_16x16x32_bf16(Bt[n][k], At[m][k], acc[ai][bj][m][n], 0, 0, 0); __builtin_amdgcn_s_setprio(0); } while (0)
; #define PG8_WAIT_V(n) asm volatile("s_waitcnt vmcnt(" #n ")" ::: "memory")
; #define PG8_WAIT_L(n) asm volatile("s_waitcnt lgkmcnt(" #n ")" ::: "memory")
; #define PG8_BAR __builtin_amdgcn_s_barrier()
; #define PG8_SCHED __builtin_amdgcn_sched_barrier(0)
; template <class Epi, class Sched>
; __device__ __forceinline__ void gemm_phase(PG8_LAS unsigned char* lds, const Gemm g, const Sched& S, const Epi& E) {
;     ...
;             PG8_STAGE(PG8_SB(0, 1), b2 + hstep, voffB);
;             PG8_WAIT_V(6); PG8_BAR; PG8_MMA(1, 1, At, B1); PG8_BAR;
;             PG8_LDB(B0, 1, 0); PG8_SCHED; PG8_LDA(At, 1, 0); PG8_STAGE(PG8_SA(0, 1), a2 + hstep, voffA);
;             PG8_WAIT_L(8); PG8_BAR; PG8_WAIT_L(0); PG8_MMA(0, 0, At, B0); PG8_BAR; PG8_SCHED;
;             PG8_LDB(B1, 1, 1); PG8_STAGE(PG8_SB(1, 0), b3, voffB);
;             PG8_BAR; PG8_WAIT_L(0); PG8_MMA(0, 1, At, B1); PG8_BAR;
;             PG8_LDA(At, 1, 1); PG8_STAGE(PG8_SA(1, 0), a3, voffA);
	s_add_u32 s64, s42, 0x10100
	s_addc_u32 s65, s43, 0
	s_add_i32 s31, s53, s1
	v_lshl_add_u64 v[8:9], s[64:65], 0, v[42:43]
	s_mov_b32 m0, s31
	s_add_i32 s29, s31, 0x2000
	global_load_lds_dwordx4 v[8:9], off
	v_lshl_add_u64 v[8:9], s[64:65], 0, v[46:47]
	s_mov_b32 m0, s29
	s_nop 0
	global_load_lds_dwordx4 v[8:9], off
	s_waitcnt vmcnt(6)
	s_barrier
	s_setprio 1
	v_mfma_f32_16x16x32_bf16 v[8:11], v[100:103], v[64:67], 0
	v_mfma_f32_16x16x32_bf16 v[12:15], v[108:111], v[64:67], 0
	v_mfma_f32_16x16x32_bf16 v[8:11], v[104:107], v[120:123], v[8:11]
	v_mfma_f32_16x16x32_bf16 v[12:15], v[112:115], v[120:123], v[12:15]
	v_mfma_f32_16x16x32_bf16 v[64:67], v[100:103], v[124:127], 0
	v_mfma_f32_16x16x32_bf16 v[120:123], v[108:111], v[124:127], 0
	v_mfma_f32_16x16x32_bf16 v[124:127], v[100:103], v[132:135], 0
	v_mfma_f32_16x16x32_bf16 v[100:103], v[100:103], v[140:143], 0
	v_mfma_f32_16x16x32_bf16 v[64:67], v[104:107], v[128:131], v[64:67]
	v_mfma_f32_16x16x32_bf16 v[120:123], v[112:115], v[128:131], v[120:123]
	v_mfma_f32_16x16x32_bf16 v[124:127], v[104:107], v[136:139], v[124:127]
	v_mfma_f32_16x16x32_bf16 v[128:131], v[108:111], v[132:135], 0
	v_mfma_f32_16x16x32_bf16 v[100:103], v[104:107], v[144:147], v[100:103]
	v_mfma_f32_16x16x32_bf16 v[104:107], v[108:111], v[140:143], 0
	v_mfma_f32_16x16x32_bf16 v[128:131], v[112:115], v[136:139], v[128:131]
	v_mfma_f32_16x16x32_bf16 v[104:107], v[112:115], v[144:147], v[104:107]
	s_setprio 0
	s_add_i32 s56, 0, 0x18000
	v_add_u32_e32 v177, s56, v55
	s_barrier
	ds_read_b128 v[108:111], v177
	ds_read_b128 v[112:115], v177 offset:1024
	ds_read_b128 v[132:135], v177 offset:2048
	ds_read_b128 v[136:139], v177 offset:3072
	s_add_u32 s64, s40, 0x10100
	s_addc_u32 s65, s41, 0
	s_mov_b32 m0, s33
	v_lshl_add_u64 v[200:201], s[64:65], 0, v[40:41]
	ds_read_b128 v[140:143], v58 offset:32768
	ds_read_b128 v[144:147], v58 offset:33792
	ds_read_b128 v[172:175], v58 offset:34816
	ds_read_b128 v[180:183], v58 offset:35840
	ds_read_b128 v[184:187], v58 offset:36864
	ds_read_b128 v[188:191], v58 offset:37888
	ds_read_b128 v[192:195], v58 offset:38912
	ds_read_b128 v[196:199], v58 offset:39936
	global_load_lds_dwordx4 v[200:201], off
	v_lshl_add_u64 v[200:201], s[64:65], 0, v[44:45]
	s_mov_b32 m0, s39
	s_nop 0
	global_load_lds_dwordx4 v[200:201], off
	s_waitcnt lgkmcnt(8)
	s_barrier
	s_waitcnt lgkmcnt(0)
	s_setprio 1
	v_mfma_f32_16x16x32_bf16 v[68:71], v[108:111], v[140:143], v[68:71]
	v_mfma_f32_16x16x32_bf16 v[72:75], v[132:135], v[140:143], v[72:75]
	v_mfma_f32_16x16x32_bf16 v[76:79], v[108:111], v[172:175], v[76:79]
	v_mfma_f32_16x16x32_bf16 v[80:83], v[132:135], v[172:175], v[80:83]
	v_mfma_f32_16x16x32_bf16 v[84:87], v[108:111], v[184:187], v[84:87]
	v_mfma_f32_16x16x32_bf16 v[88:91], v[132:135], v[184:187], v[88:91]
	v_mfma_f32_16x16x32_bf16 v[92:95], v[108:111], v[192:195], v[92:95]
	v_mfma_f32_16x16x32_bf16 v[96:99], v[132:135], v[192:195], v[96:99]
	v_mfma_f32_16x16x32_bf16 v[68:71], v[112:115], v[144:147], v[68:71]
	v_mfma_f32_16x16x32_bf16 v[72:75], v[136:139], v[144:147], v[72:75]
	v_mfma_f32_16x16x32_bf16 v[76:79], v[112:115], v[180:183], v[76:79]
	v_mfma_f32_16x16x32_bf16 v[80:83], v[136:139], v[180:183], v[80:83]
	v_mfma_f32_16x16x32_bf16 v[84:87], v[112:115], v[188:191], v[84:87]
	v_mfma_f32_16x16x32_bf16 v[88:91], v[136:139], v[188:191], v[88:91]
	v_mfma_f32_16x16x32_bf16 v[92:95], v[112:115], v[196:199], v[92:95]
	v_mfma_f32_16x16x32_bf16 v[96:99], v[136:139], v[196:199], v[96:99]
	s_setprio 0
	s_barrier
	s_add_i32 s57, 0, 0x1c000
	s_add_i32 s65, s56, s1
	v_add_u32_e32 v207, s57, v55
	v_lshl_add_u64 v[52:53], v[52:53], 0, s[16:17]
	s_mov_b32 m0, s65
	s_add_i32 s64, s65, 0x2000
	ds_read_b128 v[200:203], v207
	ds_read_b128 v[208:211], v207 offset:1024
	ds_read_b128 v[212:215], v207 offset:2048
	ds_read_b128 v[216:219], v207 offset:3072
	global_load_lds_dwordx4 v[52:53], off
	v_lshl_add_u64 v[52:53], v[204:205], 0, s[16:17]
	s_mov_b32 m0, s64
	s_nop 0
	global_load_lds_dwordx4 v[52:53], off
	s_barrier
	s_waitcnt lgkmcnt(0)
	s_setprio 1
	v_mfma_f32_16x16x32_bf16 v[116:119], v[200:203], v[140:143], v[116:119]
	v_mfma_f32_16x16x32_bf16 v[16:19], v[212:215], v[140:143], v[16:19]
	v_mfma_f32_16x16x32_bf16 v[20:23], v[200:203], v[172:175], v[20:23]
	v_mfma_f32_16x16x32_bf16 v[24:27], v[212:215], v[172:175], v[24:27]
	v_mfma_f32_16x16x32_bf16 v[28:31], v[200:203], v[184:187], v[28:31]
	v_mfma_f32_16x16x32_bf16 v[32:35], v[212:215], v[184:187], v[32:35]
	v_mfma_f32_16x16x32_bf16 v[36:39], v[200:203], v[192:195], v[36:39]
	v_mfma_f32_16x16x32_bf16 v[60:63], v[212:215], v[192:195], v[60:63]
	v_mfma_f32_16x16x32_bf16 v[116:119], v[208:211], v[144:147], v[116:119]
	v_mfma_f32_16x16x32_bf16 v[16:19], v[216:219], v[144:147], v[16:19]
	v_mfma_f32_16x16x32_bf16 v[20:23], v[208:211], v[180:183], v[20:23]
	v_mfma_f32_16x16x32_bf16 v[24:27], v[216:219], v[180:183], v[24:27]
	v_mfma_f32_16x16x32_bf16 v[28:31], v[208:211], v[188:191], v[28:31]
	v_mfma_f32_16x16x32_bf16 v[32:35], v[216:219], v[188:191], v[32:35]
	v_mfma_f32_16x16x32_bf16 v[36:39], v[208:211], v[196:199], v[36:39]
	v_mfma_f32_16x16x32_bf16 v[60:63], v[216:219], v[196:199], v[60:63]
	s_setprio 0
	s_mov_b32 m0, s48
	v_lshl_add_u64 v[52:53], v[220:221], 0, s[16:17]
	s_barrier
	ds_read_b128 v[140:143], v58 offset:49152
	ds_read_b128 v[144:147], v58 offset:50176
	ds_read_b128 v[172:175], v58 offset:51200
	ds_read_b128 v[180:183], v58 offset:52224
	ds_read_b128 v[184:187], v58 offset:53248
	ds_read_b128 v[188:191], v58 offset:54272
	ds_read_b128 v[192:195], v58 offset:55296
	ds_read_b128 v[196:199], v58 offset:56320
	global_load_lds_dwordx4 v[52:53], off
	v_lshl_add_u64 v[52:53], v[222:223], 0, s[16:17]
	s_mov_b32 m0, s49
	s_nop 0
	global_load_lds_dwordx4 v[52:53], off
	s_barrier
; #define PG8_STAGE(bufoff, gbase, voff) do { _Pragma("unroll") for (int _i = 0; _i < 2; ++_i) \
;         __builtin_amdgcn_global_load_lds((const unsigned*)((const char*)(gbase) + (voff)[_i]), (PG8_LAS unsigned*)(lds + (bufoff) + ldsw + _i * 8192), 16, 0, 0); } while (0)
; #define PG8_LDA(dst, b, h) do { _Pragma("unroll") for (int m = 0; m < 4; ++m) _Pragma("unroll") for (int k = 0; k < 2; ++k) dst[m][k] = *(const PG8_LAS bf16x8*)(lds + PG8_SA(b, h) + aoff + m * 2048 + k * 1024); } while (0)
; #define PG8_LDB(dst, b, h) do { _Pragma("unroll") for (int n = 0; n < 2; ++n) _Pragma("unroll") for (int k = 0; k < 2; ++k) dst[n][k] = *(const PG8_LAS bf16x8*)(lds + PG8_SB(b, h) + boff + n * 2048 + k * 1024); } while (0)
; #define PG8_WAIT_V(n) asm volatile("s_waitcnt vmcnt(" #n ")" ::: "memory")
; #define PG8_WAIT_L(n) asm volatile("s_waitcnt lgkmcnt(" #n ")" ::: "memory")
; #define PG8_BAR __builtin_amdgcn_s_barrier()
; #define PG8_SCHED __builtin_amdgcn_sched_barrier(0)
; template <class Epi, class Sched>
; __device__ __forceinline__ void gemm_phase(PG8_LAS unsigned char* lds, const Gemm g, const Sched& S, const Epi& E) {
;     ...
;             PG8_LDB(B0, 0, 0); PG8_SCHED; PG8_LDA(At, 0, 0); PG8_STAGE(PG8_SA(1, 1), a1 + hstep, voffA);
;             PG8_WAIT_L(8); PG8_BAR; PG8_WAIT_L(0); PG8_MMA(0, 0, At, B0); PG8_BAR; PG8_SCHED;
;             PG8_LDB(B1, 0, 1); PG8_STAGE(PG8_SB(0, 0), b2, voffB);
;             PG8_BAR; PG8_WAIT_L(0); PG8_MMA(0, 1, At, B1); PG8_BAR;
;             PG8_LDA(At, 0, 1); PG8_STAGE(PG8_SA(0, 0), a2, voffA);
;             PG8_BAR; PG8_WAIT_L(0); PG8_MMA(1, 0, At, B0); PG8_BAR; PG8_SCHED;
;             PG8_STAGE(PG8_SB(0, 1), b2 + hstep, voffB);
;             PG8_WAIT_V(6); PG8_BAR; PG8_MMA(1, 1, At, B1); PG8_BAR;
;             PG8_LDB(B0, 1, 0); PG8_SCHED; PG8_LDA(At, 1, 0); PG8_STAGE(PG8_SA(0, 1), a2 + hstep, voffA);
;             PG8_WAIT_L(8); PG8_BAR; PG8_WAIT_L(0); PG8_MMA(0, 0, At, B0); PG8_BAR; PG8_SCHED;
;             PG8_LDB(B1, 1, 1); PG8_STAGE(PG8_SB(1, 0), b3, voffB);
;             PG8_BAR; PG8_WAIT_L(0); PG8_MMA(0, 1, At, B1); PG8_BAR;
;             PG8_LDA(At, 1, 1); PG8_STAGE(PG8_SA(1, 0), a3, voffA);
;             PG8_BAR; PG8_WAIT_L(0); PG8_MMA(1, 0, At, B0); PG8_BAR; PG8_SCHED;
;             PG8_STAGE(PG8_SB(1, 1), b3 + hstep, voffB);
;             PG8_WAIT_V(6); PG8_BAR; PG8_MMA(1, 1, At, B1); PG8_BAR;
	s_waitcnt lgkmcnt(0)
	s_setprio 1
	v_mfma_f32_16x16x32_bf16 v[148:151], v[108:111], v[140:143], v[148:151]
	v_mfma_f32_16x16x32_bf16 v[152:155], v[132:135], v[140:143], v[152:155]
	v_mfma_f32_16x16x32_bf16 v[156:159], v[108:111], v[172:175], v[156:159]
	v_mfma_f32_16x16x32_bf16 v[160:163], v[132:135], v[172:175], v[160:163]
	v_mfma_f32_16x16x32_bf16 v[164:167], v[108:111], v[184:187], v[164:167]
	v_mfma_f32_16x16x32_bf16 v[168:171], v[132:135], v[184:187], v[168:171]
	v_mfma_f32_16x16x32_bf16 v[0:3], v[108:111], v[192:195], v[0:3]
	v_mfma_f32_16x16x32_bf16 v[4:7], v[132:135], v[192:195], v[4:7]
	v_mfma_f32_16x16x32_bf16 v[148:151], v[112:115], v[144:147], v[148:151]
	v_mfma_f32_16x16x32_bf16 v[152:155], v[136:139], v[144:147], v[152:155]
	v_mfma_f32_16x16x32_bf16 v[156:159], v[112:115], v[180:183], v[156:159]
	v_mfma_f32_16x16x32_bf16 v[160:163], v[136:139], v[180:183], v[160:163]
	v_mfma_f32_16x16x32_bf16 v[164:167], v[112:115], v[188:191], v[164:167]
	v_mfma_f32_16x16x32_bf16 v[168:171], v[136:139], v[188:191], v[168:171]
	v_mfma_f32_16x16x32_bf16 v[0:3], v[112:115], v[196:199], v[0:3]
	v_mfma_f32_16x16x32_bf16 v[4:7], v[136:139], v[196:199], v[4:7]
	s_setprio 0
	s_barrier
	s_add_u32 s66, s42, 0x10180
	s_addc_u32 s67, s43, 0
	s_add_i32 s43, s57, s1
	v_lshl_add_u64 v[52:53], s[66:67], 0, v[42:43]
	s_mov_b32 m0, s43
	s_add_i32 s42, s43, 0x2000
	global_load_lds_dwordx4 v[52:53], off
	v_lshl_add_u64 v[52:53], s[66:67], 0, v[46:47]
	s_mov_b32 m0, s42
	s_nop 0
	global_load_lds_dwordx4 v[52:53], off
	s_waitcnt vmcnt(6)
	s_barrier
	s_setprio 1
	v_mfma_f32_16x16x32_bf16 v[8:11], v[200:203], v[140:143], v[8:11]
	v_mfma_f32_16x16x32_bf16 v[12:15], v[212:215], v[140:143], v[12:15]
	v_mfma_f32_16x16x32_bf16 v[64:67], v[200:203], v[172:175], v[64:67]
	v_mfma_f32_16x16x32_bf16 v[108:111], v[212:215], v[172:175], v[120:123]
	v_mfma_f32_16x16x32_bf16 v[112:115], v[200:203], v[184:187], v[124:127]
	v_mfma_f32_16x16x32_bf16 v[120:123], v[212:215], v[184:187], v[128:131]
	v_mfma_f32_16x16x32_bf16 v[100:103], v[200:203], v[192:195], v[100:103]
	v_mfma_f32_16x16x32_bf16 v[104:107], v[212:215], v[192:195], v[104:107]
	v_mfma_f32_16x16x32_bf16 v[8:11], v[208:211], v[144:147], v[8:11]
	v_mfma_f32_16x16x32_bf16 v[12:15], v[216:219], v[144:147], v[12:15]
	v_mfma_f32_16x16x32_bf16 v[64:67], v[208:211], v[180:183], v[64:67]
	v_mfma_f32_16x16x32_bf16 v[108:111], v[216:219], v[180:183], v[108:111]
	v_mfma_f32_16x16x32_bf16 v[112:115], v[208:211], v[188:191], v[112:115]
	v_mfma_f32_16x16x32_bf16 v[120:123], v[216:219], v[188:191], v[120:123]
	v_mfma_f32_16x16x32_bf16 v[100:103], v[208:211], v[196:199], v[100:103]
	v_mfma_f32_16x16x32_bf16 v[104:107], v[216:219], v[196:199], v[104:107]
	s_setprio 0
	s_barrier
	ds_read_b128 v[124:127], v57
	ds_read_b128 v[128:131], v57 offset:1024
	ds_read_b128 v[132:135], v57 offset:2048
	ds_read_b128 v[136:139], v57 offset:3072
	s_add_u32 s40, s40, 0x10180
	s_addc_u32 s41, s41, 0
	s_mov_b32 m0, s51
	v_lshl_add_u64 v[52:53], s[40:41], 0, v[40:41]
	ds_read_b128 v[140:143], v58
	ds_read_b128 v[144:147], v58 offset:1024
	ds_read_b128 v[172:175], v58 offset:2048
	ds_read_b128 v[180:183], v58 offset:3072
	ds_read_b128 v[184:187], v58 offset:4096
	ds_read_b128 v[188:191], v58 offset:5120
	ds_read_b128 v[192:195], v58 offset:6144
	ds_read_b128 v[196:199], v58 offset:7168
	global_load_lds_dwordx4 v[52:53], off
	v_lshl_add_u64 v[52:53], s[40:41], 0, v[44:45]
	s_mov_b32 m0, s52
	s_nop 0
	global_load_lds_dwordx4 v[52:53], off
	s_waitcnt lgkmcnt(8)
	s_barrier
	s_waitcnt lgkmcnt(0)
	s_setprio 1
	v_mfma_f32_16x16x32_bf16 v[68:71], v[124:127], v[140:143], v[68:71]
	v_mfma_f32_16x16x32_bf16 v[72:75], v[132:135], v[140:143], v[72:75]
	v_mfma_f32_16x16x32_bf16 v[76:79], v[124:127], v[172:175], v[76:79]
	v_mfma_f32_16x16x32_bf16 v[80:83], v[132:135], v[172:175], v[80:83]
	v_mfma_f32_16x16x32_bf16 v[84:87], v[124:127], v[184:187], v[84:87]
	v_mfma_f32_16x16x32_bf16 v[88:91], v[132:135], v[184:187], v[88:91]
	v_mfma_f32_16x16x32_bf16 v[92:95], v[124:127], v[192:195], v[92:95]
	v_mfma_f32_16x16x32_bf16 v[96:99], v[132:135], v[192:195], v[96:99]
	v_mfma_f32_16x16x32_bf16 v[68:71], v[128:131], v[144:147], v[68:71]
	v_mfma_f32_16x16x32_bf16 v[72:75], v[136:139], v[144:147], v[72:75]
	v_mfma_f32_16x16x32_bf16 v[76:79], v[128:131], v[180:183], v[76:79]
	v_mfma_f32_16x16x32_bf16 v[80:83], v[136:139], v[180:183], v[80:83]
	v_mfma_f32_16x16x32_bf16 v[84:87], v[128:131], v[188:191], v[84:87]
	v_mfma_f32_16x16x32_bf16 v[88:91], v[136:139], v[188:191], v[88:91]
	v_mfma_f32_16x16x32_bf16 v[92:95], v[128:131], v[196:199], v[92:95]
	v_mfma_f32_16x16x32_bf16 v[96:99], v[136:139], v[196:199], v[96:99]
	s_setprio 0
	s_barrier
	s_mov_b32 m0, s54
	v_lshl_add_u64 v[52:53], s[44:45], 0, v[42:43]
	ds_read_b128 v[200:203], v59
	ds_read_b128 v[208:211], v59 offset:1024
	ds_read_b128 v[212:215], v59 offset:2048
	ds_read_b128 v[216:219], v59 offset:3072
	global_load_lds_dwordx4 v[52:53], off
	v_lshl_add_u64 v[204:205], s[44:45], 0, v[46:47]
	s_mov_b32 m0, s3
	s_nop 0
	global_load_lds_dwordx4 v[204:205], off
	s_barrier
; #define PG8_STAGE(bufoff, gbase, voff) do { _Pragma("unroll") for (int _i = 0; _i < 2; ++_i) \
;         __builtin_amdgcn_global_load_lds((const unsigned*)((const char*)(gbase) + (voff)[_i]), (PG8_LAS unsigned*)(lds + (bufoff) + ldsw + _i * 8192), 16, 0, 0); } while (0)
; #define PG8_LDA(dst, b, h) do { _Pragma("unroll") for (int m = 0; m < 4; ++m) _Pragma("unroll") for (int k = 0; k < 2; ++k) dst[m][k] = *(const PG8_LAS bf16x8*)(lds + PG8_SA(b, h) + aoff + m * 2048 + k * 1024); } while (0)
; #define PG8_LDB(dst, b, h) do { _Pragma("unroll") for (int n = 0; n < 2; ++n) _Pragma("unroll") for (int k = 0; k < 2; ++k) dst[n][k] = *(const PG8_LAS bf16x8*)(lds + PG8_SB(b, h) + boff + n * 2048 + k * 1024); } while (0)
; #define PG8_MMA(ai, bj, At, Bt) do { __builtin_amdgcn_s_setprio(1); _Pragma("unroll") for (int m = 0; m < 4; ++m) _Pragma("unroll") for (int n = 0; n < 2; ++n) _Pragma("unroll") for (int k = 0; k < 2; ++k) \
;         acc[ai][bj][m][n] = __builtin_amdgcn_mfma_f32_16x16x32_bf16(Bt[n][k], At[m][k], acc[ai][bj][m][n], 0, 0, 0); __builtin_amdgcn_s_setprio(0); } while (0)
; #define PG8_WAIT_V(n) asm volatile("s_waitcnt vmcnt(" #n ")" ::: "memory")
; #define PG8_WAIT_L(n) asm volatile("s_waitcnt lgkmcnt(" #n ")" ::: "memory")
; #define PG8_BAR __builtin_amdgcn_s_barrier()
; #define PG8_SCHED __builtin_amdgcn_sched_barrier(0)
; template <class Epi, class Sched>
; __device__ __forceinline__ void gemm_phase(PG8_LAS unsigned char* lds, const Gemm g, const Sched& S, const Epi& E) {
;     ...
;             PG8_LDB(B1, 0, 1); PG8_STAGE(PG8_SB(0, 0), b2, voffB);
;             PG8_BAR; PG8_WAIT_L(0); PG8_MMA(0, 1, At, B1); PG8_BAR;
;             PG8_LDA(At, 0, 1); PG8_STAGE(PG8_SA(0, 0), a2, voffA);
;             PG8_BAR; PG8_WAIT_L(0); PG8_MMA(1, 0, At, B0); PG8_BAR; PG8_SCHED;
;             PG8_STAGE(PG8_SB(0, 1), b2 + hstep, voffB);
;             PG8_WAIT_V(6); PG8_BAR; PG8_MMA(1, 1, At, B1); PG8_BAR;
;             PG8_LDB(B0, 1, 0); PG8_SCHED; PG8_LDA(At, 1, 0); PG8_STAGE(PG8_SA(0, 1), a2 + hstep, voffA);
;             PG8_WAIT_L(8); PG8_BAR; PG8_WAIT_L(0); PG8_MMA(0, 0, At, B0); PG8_BAR; PG8_SCHED;
;             PG8_LDB(B1, 1, 1); PG8_STAGE(PG8_SB(1, 0), b3, voffB);
	s_waitcnt lgkmcnt(0)
	s_setprio 1
	v_mfma_f32_16x16x32_bf16 v[116:119], v[200:203], v[140:143], v[116:119]
	v_mfma_f32_16x16x32_bf16 v[16:19], v[212:215], v[140:143], v[16:19]
	v_mfma_f32_16x16x32_bf16 v[20:23], v[200:203], v[172:175], v[20:23]
	v_mfma_f32_16x16x32_bf16 v[24:27], v[212:215], v[172:175], v[24:27]
	v_mfma_f32_16x16x32_bf16 v[28:31], v[200:203], v[184:187], v[28:31]
	v_mfma_f32_16x16x32_bf16 v[32:35], v[212:215], v[184:187], v[32:35]
	v_mfma_f32_16x16x32_bf16 v[36:39], v[200:203], v[192:195], v[36:39]
	v_mfma_f32_16x16x32_bf16 v[60:63], v[212:215], v[192:195], v[60:63]
	v_mfma_f32_16x16x32_bf16 v[116:119], v[208:211], v[144:147], v[116:119]
	v_mfma_f32_16x16x32_bf16 v[16:19], v[216:219], v[144:147], v[16:19]
	v_mfma_f32_16x16x32_bf16 v[20:23], v[208:211], v[180:183], v[20:23]
	v_mfma_f32_16x16x32_bf16 v[24:27], v[216:219], v[180:183], v[24:27]
	v_mfma_f32_16x16x32_bf16 v[28:31], v[208:211], v[188:191], v[28:31]
	v_mfma_f32_16x16x32_bf16 v[32:35], v[216:219], v[188:191], v[32:35]
	v_mfma_f32_16x16x32_bf16 v[36:39], v[208:211], v[196:199], v[36:39]
	v_mfma_f32_16x16x32_bf16 v[60:63], v[216:219], v[196:199], v[60:63]
	s_setprio 0
	s_mov_b32 m0, s4
	v_lshl_add_u64 v[236:237], s[46:47], 0, v[40:41]
	s_barrier
	ds_read_b128 v[140:143], v58 offset:16384
	ds_read_b128 v[144:147], v58 offset:17408
	ds_read_b128 v[172:175], v58 offset:18432
	ds_read_b128 v[180:183], v58 offset:19456
	ds_read_b128 v[184:187], v58 offset:20480
	ds_read_b128 v[188:191], v58 offset:21504
	ds_read_b128 v[192:195], v58 offset:22528
	ds_read_b128 v[196:199], v58 offset:23552
	global_load_lds_dwordx4 v[236:237], off
	v_lshl_add_u64 v[238:239], s[46:47], 0, v[44:45]
	s_mov_b32 m0, s5
	s_nop 0
	global_load_lds_dwordx4 v[238:239], off
	s_barrier
	s_waitcnt lgkmcnt(0)
	s_setprio 1
	v_mfma_f32_16x16x32_bf16 v[148:151], v[124:127], v[140:143], v[148:151]
	v_mfma_f32_16x16x32_bf16 v[152:155], v[132:135], v[140:143], v[152:155]
	v_mfma_f32_16x16x32_bf16 v[156:159], v[124:127], v[172:175], v[156:159]
	v_mfma_f32_16x16x32_bf16 v[160:163], v[132:135], v[172:175], v[160:163]
	v_mfma_f32_16x16x32_bf16 v[164:167], v[124:127], v[184:187], v[164:167]
	v_mfma_f32_16x16x32_bf16 v[168:171], v[132:135], v[184:187], v[168:171]
	v_mfma_f32_16x16x32_bf16 v[0:3], v[124:127], v[192:195], v[0:3]
	v_mfma_f32_16x16x32_bf16 v[4:7], v[132:135], v[192:195], v[4:7]
	v_mfma_f32_16x16x32_bf16 v[148:151], v[128:131], v[144:147], v[148:151]
	v_mfma_f32_16x16x32_bf16 v[152:155], v[136:139], v[144:147], v[152:155]
	v_mfma_f32_16x16x32_bf16 v[156:159], v[128:131], v[180:183], v[156:159]
	v_mfma_f32_16x16x32_bf16 v[160:163], v[136:139], v[180:183], v[160:163]
	v_mfma_f32_16x16x32_bf16 v[164:167], v[128:131], v[188:191], v[164:167]
	v_mfma_f32_16x16x32_bf16 v[168:171], v[136:139], v[188:191], v[168:171]
	v_mfma_f32_16x16x32_bf16 v[0:3], v[128:131], v[196:199], v[0:3]
	v_mfma_f32_16x16x32_bf16 v[124:127], v[136:139], v[196:199], v[4:7]
	s_setprio 0
	s_barrier
	s_add_u32 s40, s44, 0x10000
	s_addc_u32 s41, s45, 0
	s_mov_b32 m0, s31
	v_lshl_add_u64 v[4:5], s[40:41], 0, v[42:43]
	global_load_lds_dwordx4 v[4:5], off
	v_lshl_add_u64 v[4:5], s[40:41], 0, v[46:47]
	s_mov_b32 m0, s29
	s_nop 0
	global_load_lds_dwordx4 v[4:5], off
	s_waitcnt vmcnt(6)
	s_barrier
	s_setprio 1
	v_mfma_f32_16x16x32_bf16 v[4:7], v[200:203], v[140:143], v[8:11]
	v_mfma_f32_16x16x32_bf16 v[8:11], v[208:211], v[144:147], v[4:7]
	v_mfma_f32_16x16x32_bf16 v[4:7], v[212:215], v[140:143], v[12:15]
	v_mfma_f32_16x16x32_bf16 v[12:15], v[216:219], v[144:147], v[4:7]
	v_mfma_f32_16x16x32_bf16 v[4:7], v[200:203], v[172:175], v[64:67]
	v_mfma_f32_16x16x32_bf16 v[64:67], v[208:211], v[180:183], v[4:7]
	v_mfma_f32_16x16x32_bf16 v[4:7], v[212:215], v[172:175], v[108:111]
	v_mfma_f32_16x16x32_bf16 v[108:111], v[216:219], v[180:183], v[4:7]
	v_mfma_f32_16x16x32_bf16 v[4:7], v[200:203], v[184:187], v[112:115]
	v_mfma_f32_16x16x32_bf16 v[112:115], v[208:211], v[188:191], v[4:7]
	v_mfma_f32_16x16x32_bf16 v[4:7], v[212:215], v[184:187], v[120:123]
	v_mfma_f32_16x16x32_bf16 v[120:123], v[216:219], v[188:191], v[4:7]
	v_mfma_f32_16x16x32_bf16 v[4:7], v[200:203], v[192:195], v[100:103]
	v_mfma_f32_16x16x32_bf16 v[100:103], v[208:211], v[196:199], v[4:7]
	v_mfma_f32_16x16x32_bf16 v[4:7], v[212:215], v[192:195], v[104:107]
	v_mfma_f32_16x16x32_bf16 v[104:107], v[216:219], v[196:199], v[4:7]
	s_setprio 0
	s_barrier
	s_nop 4
	ds_read_b128 v[4:7], v177
	ds_read_b128 v[128:131], v177 offset:1024
	ds_read_b128 v[132:135], v177 offset:2048
	ds_read_b128 v[136:139], v177 offset:3072
	s_add_u32 s40, s46, 0x10000
	s_addc_u32 s41, s47, 0
	s_mov_b32 m0, s33
	v_lshl_add_u64 v[200:201], s[40:41], 0, v[40:41]
	ds_read_b128 v[140:143], v58 offset:32768
	ds_read_b128 v[144:147], v58 offset:33792
	ds_read_b128 v[172:175], v58 offset:34816
	ds_read_b128 v[180:183], v58 offset:35840
	ds_read_b128 v[184:187], v58 offset:36864
	ds_read_b128 v[188:191], v58 offset:37888
	ds_read_b128 v[192:195], v58 offset:38912
	ds_read_b128 v[196:199], v58 offset:39936
	global_load_lds_dwordx4 v[200:201], off
	v_lshl_add_u64 v[200:201], s[40:41], 0, v[44:45]
	s_mov_b32 m0, s39
	s_nop 0
	global_load_lds_dwordx4 v[200:201], off
	s_waitcnt lgkmcnt(8)
	s_barrier
; #define PG8_STAGE(bufoff, gbase, voff) do { _Pragma("unroll") for (int _i = 0; _i < 2; ++_i) \
;         __builtin_amdgcn_global_load_lds((const unsigned*)((const char*)(gbase) + (voff)[_i]), (PG8_LAS unsigned*)(lds + (bufoff) + ldsw + _i * 8192), 16, 0, 0); } while (0)
; #define PG8_LDA(dst, b, h) do { _Pragma("unroll") for (int m = 0; m < 4; ++m) _Pragma("unroll") for (int k = 0; k < 2; ++k) dst[m][k] = *(const PG8_LAS bf16x8*)(lds + PG8_SA(b, h) + aoff + m * 2048 + k * 1024); } while (0)
; #define PG8_LDB(dst, b, h) do { _Pragma("unroll") for (int n = 0; n < 2; ++n) _Pragma("unroll") for (int k = 0; k < 2; ++k) dst[n][k] = *(const PG8_LAS bf16x8*)(lds + PG8_SB(b, h) + boff + n * 2048 + k * 1024); } while (0)
; #define PG8_MMA(ai, bj, At, Bt) do { __builtin_amdgcn_s_setprio(1); _Pragma("unroll") for (int m = 0; m < 4; ++m) _Pragma("unroll") for (int n = 0; n < 2; ++n) _Pragma("unroll") for (int k = 0; k < 2; ++k) \
;         acc[ai][bj][m][n] = __builtin_amdgcn_mfma_f32_16x16x32_bf16(Bt[n][k], At[m][k], acc[ai][bj][m][n], 0, 0, 0); __builtin_amdgcn_s_setprio(0); } while (0)
; #define PG8_WAIT_V(n) asm volatile("s_waitcnt vmcnt(" #n ")" ::: "memory")
; #define PG8_WAIT_L(n) asm volatile("s_waitcnt lgkmcnt(" #n ")" ::: "memory")
; #define PG8_BAR __builtin_amdgcn_s_barrier()
; #define PG8_SCHED __builtin_amdgcn_sched_barrier(0)
; template <class Epi, class Sched>
; __device__ __forceinline__ void gemm_phase(PG8_LAS unsigned char* lds, const Gemm g, const Sched& S, const Epi& E) {
;     ...
;             PG8_WAIT_L(8); PG8_BAR; PG8_WAIT_L(0); PG8_MMA(0, 0, At, B0); PG8_BAR; PG8_SCHED;
;             PG8_LDB(B1, 1, 1); PG8_STAGE(PG8_SB(1, 0), b3, voffB);
;             PG8_BAR; PG8_WAIT_L(0); PG8_MMA(0, 1, At, B1); PG8_BAR;
;             PG8_LDA(At, 1, 1); PG8_STAGE(PG8_SA(1, 0), a3, voffA);
;             PG8_BAR; PG8_WAIT_L(0); PG8_MMA(1, 0, At, B0); PG8_BAR; PG8_SCHED;
;             PG8_STAGE(PG8_SB(1, 1), b3 + hstep, voffB);
;             PG8_WAIT_V(6); PG8_BAR; PG8_MMA(1, 1, At, B1); PG8_BAR;
	s_waitcnt lgkmcnt(0)
	s_setprio 1
	v_mfma_f32_16x16x32_bf16 v[68:71], v[4:7], v[140:143], v[68:71]
	v_mfma_f32_16x16x32_bf16 v[72:75], v[132:135], v[140:143], v[72:75]
	v_mfma_f32_16x16x32_bf16 v[76:79], v[4:7], v[172:175], v[76:79]
	v_mfma_f32_16x16x32_bf16 v[80:83], v[132:135], v[172:175], v[80:83]
	v_mfma_f32_16x16x32_bf16 v[84:87], v[4:7], v[184:187], v[84:87]
	v_mfma_f32_16x16x32_bf16 v[88:91], v[132:135], v[184:187], v[88:91]
	v_mfma_f32_16x16x32_bf16 v[92:95], v[4:7], v[192:195], v[92:95]
	v_mfma_f32_16x16x32_bf16 v[96:99], v[132:135], v[192:195], v[96:99]
	v_mfma_f32_16x16x32_bf16 v[68:71], v[128:131], v[144:147], v[68:71]
	v_mfma_f32_16x16x32_bf16 v[72:75], v[136:139], v[144:147], v[72:75]
	v_mfma_f32_16x16x32_bf16 v[76:79], v[128:131], v[180:183], v[76:79]
	v_mfma_f32_16x16x32_bf16 v[80:83], v[136:139], v[180:183], v[80:83]
	v_mfma_f32_16x16x32_bf16 v[84:87], v[128:131], v[188:191], v[84:87]
	v_mfma_f32_16x16x32_bf16 v[88:91], v[136:139], v[188:191], v[88:91]
	v_mfma_f32_16x16x32_bf16 v[92:95], v[128:131], v[196:199], v[92:95]
	v_mfma_f32_16x16x32_bf16 v[96:99], v[136:139], v[196:199], v[96:99]
	s_setprio 0
	s_barrier
	s_mov_b32 m0, s65
	v_lshl_add_u64 v[52:53], v[52:53], 0, s[10:11]
	ds_read_b128 v[200:203], v207
	ds_read_b128 v[208:211], v207 offset:1024
	ds_read_b128 v[212:215], v207 offset:2048
	ds_read_b128 v[216:219], v207 offset:3072
	global_load_lds_dwordx4 v[52:53], off
	v_lshl_add_u64 v[52:53], v[204:205], 0, s[10:11]
	s_mov_b32 m0, s64
	s_nop 0
	global_load_lds_dwordx4 v[52:53], off
	s_barrier
	s_waitcnt lgkmcnt(0)
	s_setprio 1
	v_mfma_f32_16x16x32_bf16 v[16:19], v[212:215], v[140:143], v[16:19]
	v_mfma_f32_16x16x32_bf16 v[116:119], v[200:203], v[140:143], v[116:119]
	v_mfma_f32_16x16x32_bf16 v[140:143], v[216:219], v[144:147], v[16:19]
	v_mfma_f32_16x16x32_bf16 v[16:19], v[200:203], v[172:175], v[20:23]
	v_mfma_f32_16x16x32_bf16 v[116:119], v[208:211], v[144:147], v[116:119]
	v_mfma_f32_16x16x32_bf16 v[144:147], v[208:211], v[180:183], v[16:19]
	v_mfma_f32_16x16x32_bf16 v[16:19], v[212:215], v[172:175], v[24:27]
	v_mfma_f32_16x16x32_bf16 v[172:175], v[216:219], v[180:183], v[16:19]
	v_mfma_f32_16x16x32_bf16 v[16:19], v[200:203], v[184:187], v[28:31]
	v_mfma_f32_16x16x32_bf16 v[180:183], v[208:211], v[188:191], v[16:19]
	v_mfma_f32_16x16x32_bf16 v[16:19], v[212:215], v[184:187], v[32:35]
	v_mfma_f32_16x16x32_bf16 v[184:187], v[216:219], v[188:191], v[16:19]
	v_mfma_f32_16x16x32_bf16 v[16:19], v[200:203], v[192:195], v[36:39]
	v_mfma_f32_16x16x32_bf16 v[188:191], v[208:211], v[196:199], v[16:19]
	v_mfma_f32_16x16x32_bf16 v[16:19], v[212:215], v[192:195], v[60:63]
	v_mfma_f32_16x16x32_bf16 v[60:63], v[216:219], v[196:199], v[16:19]
	s_setprio 0
	s_mov_b32 m0, s48
	s_nop 4
	v_lshl_add_u64 v[16:17], v[236:237], 0, s[10:11]
	s_barrier
	ds_read_b128 v[24:27], v58 offset:49152
	ds_read_b128 v[28:31], v58 offset:50176
	ds_read_b128 v[192:195], v58 offset:51200
	ds_read_b128 v[196:199], v58 offset:52224
	ds_read_b128 v[220:223], v58 offset:53248
	ds_read_b128 v[224:227], v58 offset:54272
	ds_read_b128 v[228:231], v58 offset:55296
	ds_read_b128 v[232:235], v58 offset:56320
	global_load_lds_dwordx4 v[16:17], off
	v_lshl_add_u64 v[16:17], v[238:239], 0, s[10:11]
	s_mov_b32 m0, s49
	s_nop 0
	global_load_lds_dwordx4 v[16:17], off
	s_barrier
	s_waitcnt lgkmcnt(0)
	s_setprio 1
	v_mfma_f32_16x16x32_bf16 v[16:19], v[4:7], v[24:27], v[148:151]
	v_mfma_f32_16x16x32_bf16 v[148:151], v[128:131], v[28:31], v[16:19]
	v_mfma_f32_16x16x32_bf16 v[16:19], v[132:135], v[24:27], v[152:155]
	v_mfma_f32_16x16x32_bf16 v[152:155], v[136:139], v[28:31], v[16:19]
	v_mfma_f32_16x16x32_bf16 v[16:19], v[4:7], v[192:195], v[156:159]
	v_mfma_f32_16x16x32_bf16 v[36:39], v[128:131], v[196:199], v[16:19]
	v_mfma_f32_16x16x32_bf16 v[16:19], v[132:135], v[192:195], v[160:163]
	v_mfma_f32_16x16x32_bf16 v[32:35], v[136:139], v[196:199], v[16:19]
	v_mfma_f32_16x16x32_bf16 v[16:19], v[4:7], v[220:223], v[164:167]
	v_mfma_f32_16x16x32_bf16 v[0:3], v[4:7], v[228:231], v[0:3]
	v_mfma_f32_16x16x32_bf16 v[20:23], v[128:131], v[224:227], v[16:19]
	v_mfma_f32_16x16x32_bf16 v[16:19], v[132:135], v[220:223], v[168:171]
	v_mfma_f32_16x16x32_bf16 v[4:7], v[128:131], v[232:235], v[0:3]
	v_mfma_f32_16x16x32_bf16 v[0:3], v[132:135], v[228:231], v[124:127]
	v_mfma_f32_16x16x32_bf16 v[16:19], v[136:139], v[224:227], v[16:19]
	v_mfma_f32_16x16x32_bf16 v[0:3], v[136:139], v[232:235], v[0:3]
	s_setprio 0
	s_barrier
	s_add_u32 s40, s44, 0x10080
	s_addc_u32 s41, s45, 0
	s_mov_b32 m0, s43
	v_lshl_add_u64 v[52:53], s[40:41], 0, v[42:43]
	global_load_lds_dwordx4 v[52:53], off
	v_lshl_add_u64 v[52:53], s[40:41], 0, v[46:47]
	s_mov_b32 m0, s42
	s_nop 0
	global_load_lds_dwordx4 v[52:53], off
	s_waitcnt vmcnt(6)
	s_barrier
; __device__ __forceinline__ unsigned cvt_pk_bf16(float lo, float hi) { unsigned r; asm volatile("v_cvt_pk_bf16_f32 %0, %1, %2" : "=v"(r) : "v"(lo), "v"(hi)); return r; }
; #define PG8_MMA(ai, bj, At, Bt) do { __builtin_amdgcn_s_setprio(1); _Pragma("unroll") for (int m = 0; m < 4; ++m) _Pragma("unroll") for (int n = 0; n < 2; ++n) _Pragma("unroll") for (int k = 0; k < 2; ++k) \
;         acc[ai][bj][m][n] = __builtin_amdgcn_mfma_f32_16x16x32_bf16(Bt[n][k], At[m][k], acc[ai][bj][m][n], 0, 0, 0); __builtin_amdgcn_s_setprio(0); } while (0)
; #define PG8_WAIT_V(n) asm volatile("s_waitcnt vmcnt(" #n ")" ::: "memory")
; #define PG8_BAR __builtin_amdgcn_s_barrier()
; template <class Epi, class Sched>
; __device__ __forceinline__ void gemm_phase(PG8_LAS unsigned char* lds, const Gemm g, const Sched& S, const Epi& E) {
;     ...
;             PG8_WAIT_V(6); PG8_BAR; PG8_MMA(1, 1, At, B1); PG8_BAR;
;     __device__ __forceinline__ void operator()(const f32x4 (&acc)[2][2][4][2], const Unit& u, int wr, int wc, int fr, int fq, const float (&epre)[1]) const {
;         const int row0 = u.pm * 256 + wr * 64 + fr, col0 = u.pn * 256 + wc * 32 + 8 * fq;
; #pragma unroll
;         for (int ai = 0; ai < 2; ++ai)
; #pragma unroll
;             for (int m = 0; m < 4; ++m)
; #pragma unroll
;                 for (int bj = 0; bj < 2; ++bj) { const f32x4 v0 = acc[ai][bj][m][0], v1 = acc[ai][bj][m][1];
;                     u32x4 w; w.x = cvt_pk_bf16(v0[0], v0[1]); w.y = cvt_pk_bf16(v0[2], v0[3]); w.z = cvt_pk_bf16(v1[0], v1[1]); w.w = cvt_pk_bf16(v1[2], v1[3]);
;                     *(u32x4*)(O + (size_t)(row0 + ai * 128 + m * 16) * DM + col0 + bj * 128) = w; }
;     }
	s_setprio 1
	v_mfma_f32_16x16x32_bf16 v[8:11], v[200:203], v[24:27], v[8:11]
	v_mfma_f32_16x16x32_bf16 v[124:127], v[208:211], v[28:31], v[8:11]
	v_mfma_f32_16x16x32_bf16 v[8:11], v[212:215], v[24:27], v[12:15]
	v_mfma_f32_16x16x32_bf16 v[128:131], v[216:219], v[28:31], v[8:11]
	v_mfma_f32_16x16x32_bf16 v[8:11], v[200:203], v[192:195], v[64:67]
	v_mfma_f32_16x16x32_bf16 v[64:67], v[208:211], v[196:199], v[8:11]
	v_mfma_f32_16x16x32_bf16 v[8:11], v[212:215], v[192:195], v[108:111]
	v_mfma_f32_16x16x32_bf16 v[108:111], v[216:219], v[196:199], v[8:11]
	v_mfma_f32_16x16x32_bf16 v[8:11], v[200:203], v[220:223], v[112:115]
	v_mfma_f32_16x16x32_bf16 v[28:31], v[208:211], v[224:227], v[8:11]
	v_mfma_f32_16x16x32_bf16 v[8:11], v[212:215], v[220:223], v[120:123]
	v_mfma_f32_16x16x32_bf16 v[24:27], v[216:219], v[224:227], v[8:11]
	v_mfma_f32_16x16x32_bf16 v[8:11], v[200:203], v[228:231], v[100:103]
	v_mfma_f32_16x16x32_bf16 v[12:15], v[208:211], v[232:235], v[8:11]
	v_mfma_f32_16x16x32_bf16 v[8:11], v[212:215], v[228:231], v[104:107]
	v_mfma_f32_16x16x32_bf16 v[8:11], v[216:219], v[232:235], v[8:11]
	s_setprio 0
	v_lshl_add_u32 v100, s38, 8, v54
	v_lshl_or_b32 v52, s63, 8, v56
	v_ashrrev_i32_e32 v101, 31, v100
	v_ashrrev_i32_e32 v53, 31, v52
	v_lshlrev_b64 v[102:103], 11, v[100:101]
	s_barrier
	v_cvt_pk_bf16_f32 v68, v68, v69
	v_cvt_pk_bf16_f32 v69, v70, v71
	v_cvt_pk_bf16_f32 v70, v72, v73
	v_cvt_pk_bf16_f32 v71, v74, v75
	v_lshl_add_u64 v[72:73], s[82:83], 0, v[102:103]
	v_lshlrev_b64 v[74:75], 1, v[52:53]
	v_lshl_add_u64 v[52:53], v[72:73], 0, v[74:75]
	global_store_dwordx4 v[52:53], v[68:71], off
	v_readlane_b32 s64, v247, 38
	v_readlane_b32 s66, v247, 40
	v_cvt_pk_bf16_f32 v68, v116, v117
	v_cvt_pk_bf16_f32 v69, v118, v119
	v_cvt_pk_bf16_f32 v70, v140, v141
	v_cvt_pk_bf16_f32 v71, v142, v143
	global_store_dwordx4 v[52:53], v[68:71], off offset:256
	v_readlane_b32 s65, v247, 39
	v_readlane_b32 s67, v247, 41
	v_or_b32_e32 v68, 16, v100
	v_ashrrev_i32_e32 v69, 31, v68
	v_lshlrev_b64 v[72:73], 11, v[68:69]
	v_lshl_add_u64 v[72:73], s[82:83], 0, v[72:73]
	v_cvt_pk_bf16_f32 v68, v76, v77
	v_lshl_add_u64 v[72:73], v[72:73], 0, v[74:75]
	v_cvt_pk_bf16_f32 v69, v78, v79
	v_cvt_pk_bf16_f32 v70, v80, v81
	v_cvt_pk_bf16_f32 v71, v82, v83
	global_store_dwordx4 v[72:73], v[68:71], off
	s_add_i32 s50, s50, s66
	s_mov_b32 s38, s30
	v_cvt_pk_bf16_f32 v68, v144, v145
	v_cvt_pk_bf16_f32 v69, v146, v147
	v_cvt_pk_bf16_f32 v70, v172, v173
	v_cvt_pk_bf16_f32 v71, v174, v175
	global_store_dwordx4 v[72:73], v[68:71], off offset:256
	s_mov_b32 s63, s28
	s_mov_b64 s[42:43], s[36:37]
	v_or_b32_e32 v68, 32, v100
	v_ashrrev_i32_e32 v69, 31, v68
	v_lshlrev_b64 v[72:73], 11, v[68:69]
	v_lshl_add_u64 v[72:73], s[82:83], 0, v[72:73]
	v_cvt_pk_bf16_f32 v68, v84, v85
	v_lshl_add_u64 v[72:73], v[72:73], 0, v[74:75]
	v_cvt_pk_bf16_f32 v69, v86, v87
	v_cvt_pk_bf16_f32 v70, v88, v89
	v_cvt_pk_bf16_f32 v71, v90, v91
	global_store_dwordx4 v[72:73], v[68:71], off
	s_mov_b64 s[40:41], s[34:35]
	s_nop 0
	v_cvt_pk_bf16_f32 v68, v180, v181
	v_cvt_pk_bf16_f32 v69, v182, v183
	v_cvt_pk_bf16_f32 v70, v184, v185
	v_cvt_pk_bf16_f32 v71, v186, v187
	global_store_dwordx4 v[72:73], v[68:71], off offset:256
	s_nop 1
	v_or_b32_e32 v68, 48, v100
	v_ashrrev_i32_e32 v69, 31, v68
	v_lshlrev_b64 v[72:73], 11, v[68:69]
	v_lshl_add_u64 v[72:73], s[82:83], 0, v[72:73]
	v_cvt_pk_bf16_f32 v68, v92, v93
	v_cvt_pk_bf16_f32 v69, v94, v95
	v_cvt_pk_bf16_f32 v70, v96, v97
	v_lshl_add_u64 v[72:73], v[72:73], 0, v[74:75]
	v_cvt_pk_bf16_f32 v71, v98, v99
	global_store_dwordx4 v[72:73], v[68:71], off
	s_nop 1
	v_cvt_pk_bf16_f32 v68, v188, v189
	v_cvt_pk_bf16_f32 v69, v190, v191
	v_cvt_pk_bf16_f32 v70, v60, v61
	v_cvt_pk_bf16_f32 v71, v62, v63
	global_store_dwordx4 v[72:73], v[68:71], off offset:256
	v_cvt_pk_bf16_f32 v60, v148, v149
	v_cvt_pk_bf16_f32 v61, v150, v151
	v_cvt_pk_bf16_f32 v62, v152, v153
	v_cvt_pk_bf16_f32 v63, v154, v155
	s_nop 1
	v_add_co_u32_e32 v70, vcc, s55, v52
	v_lshl_add_u64 v[68:69], v[52:53], 0, s[18:19]
	s_nop 0
	v_addc_co_u32_e32 v71, vcc, 0, v53, vcc
	global_store_dwordx4 v[70:71], v[60:63], off
	s_nop 1
	v_cvt_pk_bf16_f32 v60, v124, v125
	v_cvt_pk_bf16_f32 v61, v126, v127
	v_cvt_pk_bf16_f32 v62, v128, v129
	v_cvt_pk_bf16_f32 v63, v130, v131
	global_store_dwordx4 v[68:69], v[60:63], off offset:256
	v_cvt_pk_bf16_f32 v36, v36, v37
	v_cvt_pk_bf16_f32 v37, v38, v39
	v_cvt_pk_bf16_f32 v38, v32, v33
	v_add_co_u32_e32 v32, vcc, s60, v52
	s_nop 0
	v_lshl_add_u64 v[60:61], v[52:53], 0, s[20:21]
	v_addc_co_u32_e32 v33, vcc, 0, v53, vcc
	v_cvt_pk_bf16_f32 v39, v34, v35
	global_store_dwordx4 v[32:33], v[36:39], off
	v_cvt_pk_bf16_f32 v32, v64, v65
	v_cvt_pk_bf16_f32 v33, v66, v67
	v_cvt_pk_bf16_f32 v34, v108, v109
	v_cvt_pk_bf16_f32 v35, v110, v111
	global_store_dwordx4 v[60:61], v[32:35], off offset:256
	v_cvt_pk_bf16_f32 v20, v20, v21
	v_cvt_pk_bf16_f32 v21, v22, v23
	v_cvt_pk_bf16_f32 v22, v16, v17
	v_add_co_u32_e32 v16, vcc, s61, v52
	s_nop 0
	v_lshl_add_u64 v[32:33], v[52:53], 0, s[22:23]
	v_addc_co_u32_e32 v17, vcc, 0, v53, vcc
	v_cvt_pk_bf16_f32 v23, v18, v19
	global_store_dwordx4 v[16:17], v[20:23], off
	v_cvt_pk_bf16_f32 v16, v28, v29
	v_cvt_pk_bf16_f32 v17, v30, v31
	v_cvt_pk_bf16_f32 v18, v24, v25
	v_cvt_pk_bf16_f32 v19, v26, v27
	global_store_dwordx4 v[32:33], v[16:19], off offset:256
	v_cvt_pk_bf16_f32 v4, v4, v5
	v_cvt_pk_bf16_f32 v5, v6, v7
	v_cvt_pk_bf16_f32 v6, v0, v1
	v_add_co_u32_e32 v0, vcc, s62, v52
	s_nop 0
	v_lshl_add_u64 v[16:17], v[52:53], 0, s[24:25]
	v_addc_co_u32_e32 v1, vcc, 0, v53, vcc
	s_andn2_b64 vcc, exec, s[6:7]
	v_cvt_pk_bf16_f32 v7, v2, v3
	global_store_dwordx4 v[0:1], v[4:7], off
	v_cvt_pk_bf16_f32 v0, v12, v13
	v_cvt_pk_bf16_f32 v1, v14, v15
	v_cvt_pk_bf16_f32 v2, v8, v9
	v_cvt_pk_bf16_f32 v3, v10, v11
	global_store_dwordx4 v[16:17], v[0:3], off offset:256
	s_cbranch_vccz .LBB0_863

; #define PG8_STAGE(bufoff, gbase, voff) do { _Pragma("unroll") for (int _i = 0; _i < 2; ++_i) \
;         __builtin_amdgcn_global_load_lds((const unsigned*)((const char*)(gbase) + (voff)[_i]), (PG8_LAS unsigned*)(lds + (bufoff) + ldsw + _i * 8192), 16, 0, 0); } while (0)
; #define PG8_LDA(dst, b, h) do { _Pragma("unroll") for (int m = 0; m < 4; ++m) _Pragma("unroll") for (int k = 0; k < 2; ++k) dst[m][k] = *(const PG8_LAS bf16x8*)(lds + PG8_SA(b, h) + aoff + m * 2048 + k * 1024); } while (0)
; #define PG8_LDB(dst, b, h) do { _Pragma("unroll") for (int n = 0; n < 2; ++n) _Pragma("unroll") for (int k = 0; k < 2; ++k) dst[n][k] = *(const PG8_LAS bf16x8*)(lds + PG8_SB(b, h) + boff + n * 2048 + k * 1024); } while (0)
; #define PG8_MMA(ai, bj, At, Bt) do { __builtin_amdgcn_s_setprio(1); _Pragma("unroll") for (int m = 0; m < 4; ++m) _Pragma("unroll") for (int n = 0; n < 2; ++n) _Pragma("unroll") for (int k = 0; k < 2; ++k) \
;         acc[ai][bj][m][n] = __builtin_amdgcn_mfma_f32_16x16x32_bf16(Bt[n][k], At[m][k], acc[ai][bj][m][n], 0, 0, 0); __builtin_amdgcn_s_setprio(0); } while (0)
; #define PG8_WAIT_L(n) asm volatile("s_waitcnt lgkmcnt(" #n ")" ::: "memory")
; #define PG8_BAR __builtin_amdgcn_s_barrier()
; #define PG8_SCHED __builtin_amdgcn_sched_barrier(0)
; template <class Epi, class Sched>
; __device__ __forceinline__ void gemm_phase(PG8_LAS unsigned char* lds, const Gemm g, const Sched& S, const Epi& E) {
;     ...
;             const bool last = (t == nt - 2);
;             const char* a1 = cA + (size_t)(t + 1) * kstep;
;             const char* a2 = last ? nA : cA + (size_t)(t + 2) * kstep; const char* b2 = last ? nB : cB + (size_t)(t + 2) * kstep;
;             const char* a3 = a2 + kstep; const char* b3 = b2 + kstep;
;             if (last && has_next) S.a_ready(nxt);
;             PG8_LDB(B0, 0, 0); PG8_SCHED; PG8_LDA(At, 0, 0); PG8_STAGE(PG8_SA(1, 1), a1 + hstep, voffA);
;             PG8_WAIT_L(8); PG8_BAR; PG8_WAIT_L(0); PG8_MMA(0, 0, At, B0); PG8_BAR; PG8_SCHED;
;             PG8_LDB(B1, 0, 1); PG8_STAGE(PG8_SB(0, 0), b2, voffB);
;             PG8_BAR; PG8_WAIT_L(0); PG8_MMA(0, 1, At, B1); PG8_BAR;
;             PG8_LDA(At, 0, 1); PG8_STAGE(PG8_SA(0, 0), a2, voffA);
;             PG8_BAR; PG8_WAIT_L(0); PG8_MMA(1, 0, At, B0); PG8_BAR; PG8_SCHED;
.LBB0_885:
	ds_read_b128 v[130:133], v209
	ds_read_b128 v[134:137], v209 offset:1024
	ds_read_b128 v[138:141], v209 offset:2048
	ds_read_b128 v[142:145], v209 offset:3072
	s_add_u32 s26, s24, 0xfffc0080
	s_addc_u32 s27, s25, -1
	s_cmp_eq_u32 s45, 12
	s_cselect_b32 s29, s19, s27
	s_cselect_b32 s28, s41, s26
	s_cselect_b32 s27, s17, s44
	s_cselect_b32 s26, s42, s43
	v_lshl_add_u64 v[174:175], s[24:25], 0, v[188:189]
	s_add_i32 m0, s30, 0xc000
	ds_read_b128 v[146:149], v210
	ds_read_b128 v[150:153], v210 offset:1024
	ds_read_b128 v[154:157], v210 offset:2048
	ds_read_b128 v[158:161], v210 offset:3072
	ds_read_b128 v[162:165], v210 offset:4096
	ds_read_b128 v[166:169], v210 offset:5120
	ds_read_b128 v[170:173], v210 offset:6144
	ds_read_b128 v[196:199], v210 offset:7168
	global_load_lds_dwordx4 v[174:175], off
	v_lshl_add_u64 v[174:175], s[24:25], 0, v[190:191]
	s_add_i32 m0, s30, 0xe000
	s_nop 0
	global_load_lds_dwordx4 v[174:175], off
	s_waitcnt lgkmcnt(8)
	s_barrier
	s_waitcnt lgkmcnt(0)
	s_setprio 1
	v_mfma_f32_16x16x32_bf16 v[124:127], v[130:133], v[146:149], v[124:127]
	v_mfma_f32_16x16x32_bf16 v[120:123], v[138:141], v[146:149], v[120:123]
	v_mfma_f32_16x16x32_bf16 v[108:111], v[130:133], v[154:157], v[108:111]
	v_mfma_f32_16x16x32_bf16 v[104:107], v[138:141], v[154:157], v[104:107]
	v_mfma_f32_16x16x32_bf16 v[92:95], v[130:133], v[162:165], v[92:95]
	v_mfma_f32_16x16x32_bf16 v[88:91], v[138:141], v[162:165], v[88:91]
	v_mfma_f32_16x16x32_bf16 v[76:79], v[130:133], v[170:173], v[76:79]
	v_mfma_f32_16x16x32_bf16 v[72:75], v[138:141], v[170:173], v[72:75]
	v_mfma_f32_16x16x32_bf16 v[124:127], v[134:137], v[150:153], v[124:127]
	v_mfma_f32_16x16x32_bf16 v[120:123], v[142:145], v[150:153], v[120:123]
	v_mfma_f32_16x16x32_bf16 v[108:111], v[134:137], v[158:161], v[108:111]
	v_mfma_f32_16x16x32_bf16 v[104:107], v[142:145], v[158:161], v[104:107]
	v_mfma_f32_16x16x32_bf16 v[92:95], v[134:137], v[166:169], v[92:95]
	v_mfma_f32_16x16x32_bf16 v[88:91], v[142:145], v[166:169], v[88:91]
	v_mfma_f32_16x16x32_bf16 v[76:79], v[134:137], v[196:199], v[76:79]
	v_mfma_f32_16x16x32_bf16 v[72:75], v[142:145], v[196:199], v[72:75]
	s_setprio 0
	s_barrier
	s_add_i32 s46, s38, s3
	v_lshl_add_u64 v[174:175], s[26:27], 0, v[182:183]
	s_mov_b32 m0, s46
	ds_read_b128 v[200:203], v211
	ds_read_b128 v[220:223], v211 offset:1024
	ds_read_b128 v[224:227], v211 offset:2048
	ds_read_b128 v[228:231], v211 offset:3072
	global_load_lds_dwordx4 v[174:175], off
	v_lshl_add_u64 v[204:205], s[26:27], 0, v[186:187]
	s_add_i32 m0, s46, 0x2000
	s_nop 0
	global_load_lds_dwordx4 v[204:205], off
	s_barrier
	s_waitcnt lgkmcnt(0)
	s_setprio 1
	v_mfma_f32_16x16x32_bf16 v[116:119], v[200:203], v[146:149], v[116:119]
	v_mfma_f32_16x16x32_bf16 v[112:115], v[224:227], v[146:149], v[112:115]
	v_mfma_f32_16x16x32_bf16 v[100:103], v[200:203], v[154:157], v[100:103]
	v_mfma_f32_16x16x32_bf16 v[96:99], v[224:227], v[154:157], v[96:99]
	v_mfma_f32_16x16x32_bf16 v[84:87], v[200:203], v[162:165], v[84:87]
	v_mfma_f32_16x16x32_bf16 v[80:83], v[224:227], v[162:165], v[80:83]
	v_mfma_f32_16x16x32_bf16 v[68:71], v[200:203], v[170:173], v[68:71]
	v_mfma_f32_16x16x32_bf16 v[64:67], v[224:227], v[170:173], v[64:67]
	v_mfma_f32_16x16x32_bf16 v[116:119], v[220:223], v[150:153], v[116:119]
	v_mfma_f32_16x16x32_bf16 v[112:115], v[228:231], v[150:153], v[112:115]
	v_mfma_f32_16x16x32_bf16 v[100:103], v[220:223], v[158:161], v[100:103]
	v_mfma_f32_16x16x32_bf16 v[96:99], v[228:231], v[158:161], v[96:99]
	v_mfma_f32_16x16x32_bf16 v[84:87], v[220:223], v[166:169], v[84:87]
	v_mfma_f32_16x16x32_bf16 v[80:83], v[228:231], v[166:169], v[80:83]
	v_mfma_f32_16x16x32_bf16 v[68:71], v[220:223], v[196:199], v[68:71]
	v_mfma_f32_16x16x32_bf16 v[64:67], v[228:231], v[196:199], v[64:67]
	s_setprio 0
	s_mov_b32 m0, s30
	v_lshl_add_u64 v[232:233], s[28:29], 0, v[180:181]
	s_barrier
	ds_read_b128 v[146:149], v210 offset:16384
	ds_read_b128 v[150:153], v210 offset:17408
	ds_read_b128 v[154:157], v210 offset:18432
	ds_read_b128 v[158:161], v210 offset:19456
	ds_read_b128 v[162:165], v210 offset:20480
	ds_read_b128 v[166:169], v210 offset:21504
	ds_read_b128 v[170:173], v210 offset:22528
	ds_read_b128 v[196:199], v210 offset:23552
	global_load_lds_dwordx4 v[232:233], off
	v_lshl_add_u64 v[234:235], s[28:29], 0, v[184:185]
	s_mov_b32 m0, s31
	s_nop 0
	global_load_lds_dwordx4 v[234:235], off
	s_barrier
	s_waitcnt lgkmcnt(0)
	s_setprio 1
	v_mfma_f32_16x16x32_bf16 v[60:63], v[130:133], v[146:149], v[60:63]
	v_mfma_f32_16x16x32_bf16 v[56:59], v[138:141], v[146:149], v[56:59]
	v_mfma_f32_16x16x32_bf16 v[44:47], v[130:133], v[154:157], v[44:47]
	v_mfma_f32_16x16x32_bf16 v[40:43], v[138:141], v[154:157], v[40:43]
	v_mfma_f32_16x16x32_bf16 v[28:31], v[130:133], v[162:165], v[28:31]
	v_mfma_f32_16x16x32_bf16 v[24:27], v[138:141], v[162:165], v[24:27]
	v_mfma_f32_16x16x32_bf16 v[12:15], v[130:133], v[170:173], v[12:15]
	v_mfma_f32_16x16x32_bf16 v[8:11], v[138:141], v[170:173], v[8:11]
	v_mfma_f32_16x16x32_bf16 v[60:63], v[134:137], v[150:153], v[60:63]
	v_mfma_f32_16x16x32_bf16 v[56:59], v[142:145], v[150:153], v[56:59]
	v_mfma_f32_16x16x32_bf16 v[44:47], v[134:137], v[158:161], v[44:47]
	v_mfma_f32_16x16x32_bf16 v[40:43], v[142:145], v[158:161], v[40:43]
	v_mfma_f32_16x16x32_bf16 v[28:31], v[134:137], v[166:169], v[28:31]
	v_mfma_f32_16x16x32_bf16 v[24:27], v[142:145], v[166:169], v[24:27]
	v_mfma_f32_16x16x32_bf16 v[12:15], v[134:137], v[196:199], v[12:15]
	v_mfma_f32_16x16x32_bf16 v[8:11], v[142:145], v[196:199], v[8:11]
	s_setprio 0
	s_barrier
; #define PG8_STAGE(bufoff, gbase, voff) do { _Pragma("unroll") for (int _i = 0; _i < 2; ++_i) \
;         __builtin_amdgcn_global_load_lds((const unsigned*)((const char*)(gbase) + (voff)[_i]), (PG8_LAS unsigned*)(lds + (bufoff) + ldsw + _i * 8192), 16, 0, 0); } while (0)
; #define PG8_LDA(dst, b, h) do { _Pragma("unroll") for (int m = 0; m < 4; ++m) _Pragma("unroll") for (int k = 0; k < 2; ++k) dst[m][k] = *(const PG8_LAS bf16x8*)(lds + PG8_SA(b, h) + aoff + m * 2048 + k * 1024); } while (0)
; #define PG8_LDB(dst, b, h) do { _Pragma("unroll") for (int n = 0; n < 2; ++n) _Pragma("unroll") for (int k = 0; k < 2; ++k) dst[n][k] = *(const PG8_LAS bf16x8*)(lds + PG8_SB(b, h) + boff + n * 2048 + k * 1024); } while (0)
; #define PG8_MMA(ai, bj, At, Bt) do { __builtin_amdgcn_s_setprio(1); _Pragma("unroll") for (int m = 0; m < 4; ++m) _Pragma("unroll") for (int n = 0; n < 2; ++n) _Pragma("unroll") for (int k = 0; k < 2; ++k) \
;         acc[ai][bj][m][n] = __builtin_amdgcn_mfma_f32_16x16x32_bf16(Bt[n][k], At[m][k], acc[ai][bj][m][n], 0, 0, 0); __builtin_amdgcn_s_setprio(0); } while (0)
; #define PG8_WAIT_V(n) asm volatile("s_waitcnt vmcnt(" #n ")" ::: "memory")
; #define PG8_WAIT_L(n) asm volatile("s_waitcnt lgkmcnt(" #n ")" ::: "memory")
; #define PG8_BAR __builtin_amdgcn_s_barrier()
; #define PG8_SCHED __builtin_amdgcn_sched_barrier(0)
; template <class Epi, class Sched>
; __device__ __forceinline__ void gemm_phase(PG8_LAS unsigned char* lds, const Gemm g, const Sched& S, const Epi& E) {
;     ...
;             PG8_STAGE(PG8_SB(0, 1), b2 + hstep, voffB);
;             PG8_WAIT_V(6); PG8_BAR; PG8_MMA(1, 1, At, B1); PG8_BAR;
;             PG8_LDB(B0, 1, 0); PG8_SCHED; PG8_LDA(At, 1, 0); PG8_STAGE(PG8_SA(0, 1), a2 + hstep, voffA);
;             PG8_WAIT_L(8); PG8_BAR; PG8_WAIT_L(0); PG8_MMA(0, 0, At, B0); PG8_BAR; PG8_SCHED;
;             PG8_LDB(B1, 1, 1); PG8_STAGE(PG8_SB(1, 0), b3, voffB);
;             PG8_BAR; PG8_WAIT_L(0); PG8_MMA(0, 1, At, B1); PG8_BAR;
;             PG8_LDA(At, 1, 1); PG8_STAGE(PG8_SA(1, 0), a3, voffA);
	s_add_u32 s46, s26, 0x40000
	s_addc_u32 s47, s27, 0
	s_add_i32 s48, s39, s3
	v_lshl_add_u64 v[130:131], s[46:47], 0, v[182:183]
	s_mov_b32 m0, s48
	s_nop 0
	global_load_lds_dwordx4 v[130:131], off
	v_lshl_add_u64 v[130:131], s[46:47], 0, v[186:187]
	s_add_i32 m0, s48, 0x2000
	s_nop 0
	global_load_lds_dwordx4 v[130:131], off
	s_waitcnt vmcnt(6)
	s_barrier
	s_setprio 1
	v_mfma_f32_16x16x32_bf16 v[52:55], v[200:203], v[146:149], v[52:55]
	v_mfma_f32_16x16x32_bf16 v[48:51], v[224:227], v[146:149], v[48:51]
	v_mfma_f32_16x16x32_bf16 v[36:39], v[200:203], v[154:157], v[36:39]
	v_mfma_f32_16x16x32_bf16 v[32:35], v[224:227], v[154:157], v[32:35]
	v_mfma_f32_16x16x32_bf16 v[20:23], v[200:203], v[162:165], v[20:23]
	v_mfma_f32_16x16x32_bf16 v[16:19], v[224:227], v[162:165], v[16:19]
	v_mfma_f32_16x16x32_bf16 v[4:7], v[200:203], v[170:173], v[4:7]
	v_mfma_f32_16x16x32_bf16 v[0:3], v[224:227], v[170:173], v[0:3]
	v_mfma_f32_16x16x32_bf16 v[52:55], v[220:223], v[150:153], v[52:55]
	v_mfma_f32_16x16x32_bf16 v[48:51], v[228:231], v[150:153], v[48:51]
	v_mfma_f32_16x16x32_bf16 v[36:39], v[220:223], v[158:161], v[36:39]
	v_mfma_f32_16x16x32_bf16 v[32:35], v[228:231], v[158:161], v[32:35]
	v_mfma_f32_16x16x32_bf16 v[20:23], v[220:223], v[166:169], v[20:23]
	v_mfma_f32_16x16x32_bf16 v[16:19], v[228:231], v[166:169], v[16:19]
	v_mfma_f32_16x16x32_bf16 v[4:7], v[220:223], v[196:199], v[4:7]
	v_mfma_f32_16x16x32_bf16 v[0:3], v[228:231], v[196:199], v[0:3]
	s_setprio 0
	s_add_i32 s46, 0, 0x18000
	v_add_u32_e32 v129, s46, v207
	s_barrier
	ds_read_b128 v[130:133], v129
	ds_read_b128 v[134:137], v129 offset:1024
	ds_read_b128 v[138:141], v129 offset:2048
	ds_read_b128 v[142:145], v129 offset:3072
	s_add_u32 s28, s28, 0x40000
	s_addc_u32 s29, s29, 0
	s_mov_b32 m0, s33
	v_lshl_add_u64 v[200:201], s[28:29], 0, v[180:181]
	ds_read_b128 v[146:149], v210 offset:32768
	ds_read_b128 v[150:153], v210 offset:33792
	ds_read_b128 v[154:157], v210 offset:34816
	ds_read_b128 v[158:161], v210 offset:35840
	ds_read_b128 v[162:165], v210 offset:36864
	ds_read_b128 v[166:169], v210 offset:37888
	ds_read_b128 v[170:173], v210 offset:38912
	ds_read_b128 v[196:199], v210 offset:39936
	global_load_lds_dwordx4 v[200:201], off
	v_lshl_add_u64 v[200:201], s[28:29], 0, v[184:185]
	s_mov_b32 m0, s34
	s_nop 0
	global_load_lds_dwordx4 v[200:201], off
	s_waitcnt lgkmcnt(8)
	s_barrier
	s_waitcnt lgkmcnt(0)
	s_setprio 1
	v_mfma_f32_16x16x32_bf16 v[124:127], v[130:133], v[146:149], v[124:127]
	v_mfma_f32_16x16x32_bf16 v[120:123], v[138:141], v[146:149], v[120:123]
	v_mfma_f32_16x16x32_bf16 v[108:111], v[130:133], v[154:157], v[108:111]
	v_mfma_f32_16x16x32_bf16 v[104:107], v[138:141], v[154:157], v[104:107]
	v_mfma_f32_16x16x32_bf16 v[92:95], v[130:133], v[162:165], v[92:95]
	v_mfma_f32_16x16x32_bf16 v[88:91], v[138:141], v[162:165], v[88:91]
	v_mfma_f32_16x16x32_bf16 v[76:79], v[130:133], v[170:173], v[76:79]
	v_mfma_f32_16x16x32_bf16 v[72:75], v[138:141], v[170:173], v[72:75]
	v_mfma_f32_16x16x32_bf16 v[124:127], v[134:137], v[150:153], v[124:127]
	v_mfma_f32_16x16x32_bf16 v[120:123], v[142:145], v[150:153], v[120:123]
	v_mfma_f32_16x16x32_bf16 v[108:111], v[134:137], v[158:161], v[108:111]
	v_mfma_f32_16x16x32_bf16 v[104:107], v[142:145], v[158:161], v[104:107]
	v_mfma_f32_16x16x32_bf16 v[92:95], v[134:137], v[166:169], v[92:95]
	v_mfma_f32_16x16x32_bf16 v[88:91], v[142:145], v[166:169], v[88:91]
	v_mfma_f32_16x16x32_bf16 v[76:79], v[134:137], v[196:199], v[76:79]
	v_mfma_f32_16x16x32_bf16 v[72:75], v[142:145], v[196:199], v[72:75]
	s_setprio 0
	s_barrier
	s_add_i32 s28, 0, 0x1c000
	s_add_i32 s29, s46, s3
	v_add_u32_e32 v129, s28, v207
	v_lshl_add_u64 v[174:175], v[174:175], 0, s[12:13]
	s_mov_b32 m0, s29
	ds_read_b128 v[200:203], v129
	ds_read_b128 v[220:223], v129 offset:1024
	ds_read_b128 v[224:227], v129 offset:2048
	ds_read_b128 v[228:231], v129 offset:3072
	global_load_lds_dwordx4 v[174:175], off
	v_lshl_add_u64 v[174:175], v[204:205], 0, s[12:13]
	s_add_i32 m0, s29, 0x2000
	s_nop 0
	global_load_lds_dwordx4 v[174:175], off
	s_barrier
	s_waitcnt lgkmcnt(0)
	s_setprio 1
	v_mfma_f32_16x16x32_bf16 v[116:119], v[200:203], v[146:149], v[116:119]
	v_mfma_f32_16x16x32_bf16 v[112:115], v[224:227], v[146:149], v[112:115]
	v_mfma_f32_16x16x32_bf16 v[100:103], v[200:203], v[154:157], v[100:103]
	v_mfma_f32_16x16x32_bf16 v[96:99], v[224:227], v[154:157], v[96:99]
	v_mfma_f32_16x16x32_bf16 v[84:87], v[200:203], v[162:165], v[84:87]
	v_mfma_f32_16x16x32_bf16 v[80:83], v[224:227], v[162:165], v[80:83]
	v_mfma_f32_16x16x32_bf16 v[68:71], v[200:203], v[170:173], v[68:71]
	v_mfma_f32_16x16x32_bf16 v[64:67], v[224:227], v[170:173], v[64:67]
	v_mfma_f32_16x16x32_bf16 v[116:119], v[220:223], v[150:153], v[116:119]
	v_mfma_f32_16x16x32_bf16 v[112:115], v[228:231], v[150:153], v[112:115]
	v_mfma_f32_16x16x32_bf16 v[100:103], v[220:223], v[158:161], v[100:103]
	v_mfma_f32_16x16x32_bf16 v[96:99], v[228:231], v[158:161], v[96:99]
	v_mfma_f32_16x16x32_bf16 v[84:87], v[220:223], v[166:169], v[84:87]
	v_mfma_f32_16x16x32_bf16 v[80:83], v[228:231], v[166:169], v[80:83]
	v_mfma_f32_16x16x32_bf16 v[68:71], v[220:223], v[196:199], v[68:71]
	v_mfma_f32_16x16x32_bf16 v[64:67], v[228:231], v[196:199], v[64:67]
	s_setprio 0
	s_mov_b32 m0, s36
	v_lshl_add_u64 v[174:175], v[232:233], 0, s[12:13]
	s_barrier
	ds_read_b128 v[146:149], v210 offset:49152
	ds_read_b128 v[150:153], v210 offset:50176
	ds_read_b128 v[154:157], v210 offset:51200
	ds_read_b128 v[158:161], v210 offset:52224
	ds_read_b128 v[162:165], v210 offset:53248
	ds_read_b128 v[166:169], v210 offset:54272
	ds_read_b128 v[170:173], v210 offset:55296
	ds_read_b128 v[196:199], v210 offset:56320
	global_load_lds_dwordx4 v[174:175], off
	v_lshl_add_u64 v[174:175], v[234:235], 0, s[12:13]
	s_mov_b32 m0, s37
	s_nop 0
	global_load_lds_dwordx4 v[174:175], off
	s_barrier
; #define PG8_STAGE(bufoff, gbase, voff) do { _Pragma("unroll") for (int _i = 0; _i < 2; ++_i) \
;         __builtin_amdgcn_global_load_lds((const unsigned*)((const char*)(gbase) + (voff)[_i]), (PG8_LAS unsigned*)(lds + (bufoff) + ldsw + _i * 8192), 16, 0, 0); } while (0)
; #define PG8_MMA(ai, bj, At, Bt) do { __builtin_amdgcn_s_setprio(1); _Pragma("unroll") for (int m = 0; m < 4; ++m) _Pragma("unroll") for (int n = 0; n < 2; ++n) _Pragma("unroll") for (int k = 0; k < 2; ++k) \
;         acc[ai][bj][m][n] = __builtin_amdgcn_mfma_f32_16x16x32_bf16(Bt[n][k], At[m][k], acc[ai][bj][m][n], 0, 0, 0); __builtin_amdgcn_s_setprio(0); } while (0)
; #define PG8_WAIT_V(n) asm volatile("s_waitcnt vmcnt(" #n ")" ::: "memory")
; #define PG8_WAIT_L(n) asm volatile("s_waitcnt lgkmcnt(" #n ")" ::: "memory")
; #define PG8_BAR __builtin_amdgcn_s_barrier()
; template <class Epi, class Sched>
; __device__ __forceinline__ void gemm_phase(PG8_LAS unsigned char* lds, const Gemm g, const Sched& S, const Epi& E) {
;     ...
;             PG8_BAR; PG8_WAIT_L(0); PG8_MMA(1, 0, At, B0); PG8_BAR; PG8_SCHED;
;             PG8_STAGE(PG8_SB(1, 1), b3 + hstep, voffB);
;             PG8_WAIT_V(6); PG8_BAR; PG8_MMA(1, 1, At, B1); PG8_BAR;
;     __device__ __forceinline__ void operator()(const f32x4 (&acc)[2][2][4][2], const Unit& u, int wr, int wc, int fr, int fq, const float (&epre)[8]) const {
;     ...
;         for (int ai = 0; ai < 2; ++ai) {
;             float ssv[4];
;             u32x4 hw[4][2], pw[4][2];
; #pragma unroll
;             for (int m = 0; m < 4; ++m)
; #pragma unroll
;                 for (int bj = 0; bj < 2; ++bj) { const size_t o = (size_t)(row0 + ai * 128 + m * 16) * DM + col0 + bj * 128; hw[m][bj] = *(const u32x4*)(HB + o); pw[m][bj] = *(const u32x4*)(PPb + o); }
; #pragma unroll
;             for (int m = 0; m < 4; ++m) { const int row = row0 + ai * 128 + m * 16;
;                 const float rstd = rsqrtf(epre[ai * 4 + m] * (1.0f / DM) + EPS);
;                 float ss = 0.f;
; #pragma unroll
;                 for (int bj = 0; bj < 2; ++bj) { const size_t o = (size_t)row * DM + col0 + bj * 128;
;                     f32x4 h0, h1, p0, p1; unpack8(hw[m][bj], h0, h1); unpack8(pw[m][bj], p0, p1);
; #pragma unroll
;                     for (int j = 0; j < 4; ++j) { h0[j] += sigmoidf_(acc[ai][bj][m][0][j] * rstd) * p0[j]; h1[j] += sigmoidf_(acc[ai][bj][m][1][j] * rstd) * p1[j]; }
	s_waitcnt lgkmcnt(0)
	s_setprio 1
	v_mfma_f32_16x16x32_bf16 v[60:63], v[130:133], v[146:149], v[60:63]
	v_mfma_f32_16x16x32_bf16 v[56:59], v[138:141], v[146:149], v[56:59]
	v_mfma_f32_16x16x32_bf16 v[44:47], v[130:133], v[154:157], v[44:47]
	v_mfma_f32_16x16x32_bf16 v[40:43], v[138:141], v[154:157], v[40:43]
	v_mfma_f32_16x16x32_bf16 v[28:31], v[130:133], v[162:165], v[28:31]
	v_mfma_f32_16x16x32_bf16 v[24:27], v[138:141], v[162:165], v[24:27]
	v_mfma_f32_16x16x32_bf16 v[12:15], v[130:133], v[170:173], v[12:15]
	v_mfma_f32_16x16x32_bf16 v[8:11], v[138:141], v[170:173], v[8:11]
	v_mfma_f32_16x16x32_bf16 v[60:63], v[134:137], v[150:153], v[60:63]
	v_mfma_f32_16x16x32_bf16 v[56:59], v[142:145], v[150:153], v[56:59]
	v_mfma_f32_16x16x32_bf16 v[44:47], v[134:137], v[158:161], v[44:47]
	v_mfma_f32_16x16x32_bf16 v[40:43], v[142:145], v[158:161], v[40:43]
	v_mfma_f32_16x16x32_bf16 v[28:31], v[134:137], v[166:169], v[28:31]
	v_mfma_f32_16x16x32_bf16 v[24:27], v[142:145], v[166:169], v[24:27]
	v_mfma_f32_16x16x32_bf16 v[12:15], v[134:137], v[196:199], v[12:15]
	v_mfma_f32_16x16x32_bf16 v[8:11], v[142:145], v[196:199], v[8:11]
	s_setprio 0
	s_barrier
	s_add_u32 s26, s26, 0x40080
	s_addc_u32 s27, s27, 0
	s_add_i32 s28, s28, s3
	v_lshl_add_u64 v[130:131], s[26:27], 0, v[182:183]
	s_mov_b32 m0, s28
	s_nop 0
	global_load_lds_dwordx4 v[130:131], off
	v_lshl_add_u64 v[130:131], s[26:27], 0, v[186:187]
	s_add_i32 m0, s28, 0x2000
	s_nop 0
	global_load_lds_dwordx4 v[130:131], off
	s_waitcnt vmcnt(6)
	s_barrier
	s_setprio 1
	v_mfma_f32_16x16x32_bf16 v[52:55], v[200:203], v[146:149], v[52:55]
	v_mfma_f32_16x16x32_bf16 v[48:51], v[224:227], v[146:149], v[48:51]
	v_mfma_f32_16x16x32_bf16 v[36:39], v[200:203], v[154:157], v[36:39]
	v_mfma_f32_16x16x32_bf16 v[32:35], v[224:227], v[154:157], v[32:35]
	v_mfma_f32_16x16x32_bf16 v[20:23], v[200:203], v[162:165], v[20:23]
	v_mfma_f32_16x16x32_bf16 v[16:19], v[224:227], v[162:165], v[16:19]
	v_mfma_f32_16x16x32_bf16 v[4:7], v[200:203], v[170:173], v[4:7]
	v_mfma_f32_16x16x32_bf16 v[0:3], v[224:227], v[170:173], v[0:3]
	v_mfma_f32_16x16x32_bf16 v[52:55], v[220:223], v[150:153], v[52:55]
	v_mfma_f32_16x16x32_bf16 v[48:51], v[228:231], v[150:153], v[48:51]
	v_mfma_f32_16x16x32_bf16 v[36:39], v[220:223], v[158:161], v[36:39]
	v_mfma_f32_16x16x32_bf16 v[32:35], v[228:231], v[158:161], v[32:35]
	v_mfma_f32_16x16x32_bf16 v[20:23], v[220:223], v[166:169], v[20:23]
	v_mfma_f32_16x16x32_bf16 v[16:19], v[228:231], v[166:169], v[16:19]
	v_mfma_f32_16x16x32_bf16 v[4:7], v[220:223], v[196:199], v[4:7]
	v_mfma_f32_16x16x32_bf16 v[0:3], v[228:231], v[196:199], v[0:3]
	s_setprio 0
	s_add_i32 s45, s45, 2
	s_add_u32 s24, s24, 0x100
	s_addc_u32 s25, s25, 0
	s_add_u32 s43, s43, 0x100
	s_addc_u32 s44, s44, 0
	s_cmp_gt_u32 s45, 13
	s_barrier
	s_cbranch_scc0 .LBB0_885
	v_lshl_add_u32 v198, s6, 8, v177
	v_lshl_or_b32 v196, s7, 8, v208
	v_ashrrev_i32_e32 v199, 31, v198
	v_ashrrev_i32_e32 v197, 31, v196
	v_lshlrev_b64 v[130:131], 10, v[198:199]
	v_lshl_add_u64 v[130:131], v[130:131], 0, v[196:197]
	v_lshlrev_b64 v[130:131], 1, v[130:131]
	v_lshl_add_u64 v[132:133], s[84:85], 0, v[130:131]
	global_load_dwordx4 v[220:223], v[132:133], off
	v_lshl_add_u64 v[132:133], s[82:83], 0, v[130:131]
	global_load_dwordx4 v[224:227], v[132:133], off
	s_waitcnt vmcnt(0)
	v_fmamk_f32 v128, v128, 0x3a800000, v212
	v_or_b32_e32 v204, 16, v198
	v_mul_f32_e32 v129, 0x4b800000, v128
	v_ashrrev_i32_e32 v205, 31, v204
	v_cmp_gt_f32_e64 s[6:7], s40, v128
	v_or_b32_e32 v130, 0x100, v130
	v_or_b32_e32 v200, 48, v198
	v_cndmask_b32_e64 v136, v128, v129, s[6:7]
	v_lshlrev_b64 v[128:129], 10, v[204:205]
	v_lshl_add_u64 v[128:129], v[128:129], 0, v[196:197]
	v_rsq_f32_e32 v242, v136
	v_lshlrev_b64 v[128:129], 1, v[128:129]
	v_lshl_add_u64 v[136:137], s[84:85], 0, v[130:131]
	v_lshl_add_u64 v[130:131], s[82:83], 0, v[130:131]
	v_lshl_add_u64 v[138:139], s[84:85], 0, v[128:129]
	v_lshl_add_u64 v[140:141], s[82:83], 0, v[128:129]
	global_load_dwordx4 v[228:231], v[136:137], off
	global_load_dwordx4 v[232:235], v[130:131], off
	global_load_dwordx4 v[172:175], v[138:139], off
	global_load_dwordx4 v[168:171], v[140:141], off
	v_ashrrev_i32_e32 v201, 31, v200
	v_lshlrev_b64 v[134:135], 10, v[200:201]
	v_lshl_add_u64 v[134:135], v[134:135], 0, v[196:197]
	v_lshlrev_b64 v[134:135], 1, v[134:135]
	v_lshl_add_u64 v[146:147], s[84:85], 0, v[134:135]
	v_lshl_add_u64 v[148:149], s[82:83], 0, v[134:135]
	v_or_b32_e32 v134, 0x100, v134
	v_lshl_add_u64 v[238:239], s[84:85], 0, v[134:135]
	v_lshl_add_u64 v[240:241], s[82:83], 0, v[134:135]
	v_mul_f32_e32 v134, 0x45800000, v242
	v_cndmask_b32_e64 v242, v242, v134, s[6:7]
	v_mul_f32_e32 v120, v242, v120
	v_mul_f32_e32 v120, 0xbfb8aa3b, v120
	v_exp_f32_e32 v120, v120
	v_or_b32_e32 v202, 32, v198
	v_ashrrev_i32_e32 v203, 31, v202
	v_lshlrev_b64 v[132:133], 10, v[202:203]
	v_mul_f32_e32 v121, v242, v121
	v_lshl_add_u64 v[132:133], v[132:133], 0, v[196:197]
	v_add_f32_e32 v120, 1.0, v120
	v_mul_f32_e32 v121, 0xbfb8aa3b, v121
	v_lshlrev_b64 v[132:133], 1, v[132:133]
	v_rcp_f32_e32 v120, v120
	v_exp_f32_e32 v121, v121
	v_or_b32_e32 v128, 0x100, v128
	v_lshl_add_u64 v[142:143], s[84:85], 0, v[132:133]
	v_lshl_add_u64 v[144:145], s[82:83], 0, v[132:133]
	v_or_b32_e32 v132, 0x100, v132
	v_lshl_add_u64 v[130:131], s[84:85], 0, v[128:129]
	v_lshl_add_u64 v[128:129], s[82:83], 0, v[128:129]
	global_load_dwordx4 v[156:159], v[142:143], off
	global_load_dwordx4 v[152:155], v[144:145], off
	v_lshl_add_u64 v[144:145], s[84:85], 0, v[132:133]
	v_lshl_add_u64 v[132:133], s[82:83], 0, v[132:133]
	global_load_dwordx4 v[140:143], v[146:147], off
; __device__ __forceinline__ unsigned cvt_pk_bf16(float lo, float hi) { unsigned r; asm volatile("v_cvt_pk_bf16_f32 %0, %1, %2" : "=v"(r) : "v"(lo), "v"(hi)); return r; }
; __device__ __forceinline__ float sigmoidf_(float x) { return frcp(1.0f + __expf(-x)); }
;     __device__ __forceinline__ void operator()(const f32x4 (&acc)[2][2][4][2], const Unit& u, int wr, int wc, int fr, int fq, const float (&epre)[8]) const {
;     ...
;             for (int m = 0; m < 4; ++m) { const int row = row0 + ai * 128 + m * 16;
;                 const float rstd = rsqrtf(epre[ai * 4 + m] * (1.0f / DM) + EPS);
;                 float ss = 0.f;
; #pragma unroll
;                 for (int bj = 0; bj < 2; ++bj) { const size_t o = (size_t)row * DM + col0 + bj * 128;
;                     f32x4 h0, h1, p0, p1; unpack8(hw[m][bj], h0, h1); unpack8(pw[m][bj], p0, p1);
; #pragma unroll
;                     for (int j = 0; j < 4; ++j) { h0[j] += sigmoidf_(acc[ai][bj][m][0][j] * rstd) * p0[j]; h1[j] += sigmoidf_(acc[ai][bj][m][1][j] * rstd) * p1[j]; }
;                     u32x4 w; w.x = cvt_pk_bf16(h0[0], h0[1]); w.y = cvt_pk_bf16(h0[2], h0[3]); w.z = cvt_pk_bf16(h1[0], h1[1]); w.w = cvt_pk_bf16(h1[2], h1[3]);
;                     *(u32x4*)(H3 + o) = w;
;                     ss += (h0[0] * h0[0] + h0[1] * h0[1]) + (h0[2] * h0[2] + h0[3] * h0[3]) + (h1[0] * h1[0] + h1[1] * h1[1]) + (h1[2] * h1[2] + h1[3] * h1[3]); }
	global_load_dwordx4 v[136:139], v[148:149], off
	global_load_dwordx4 v[164:167], v[130:131], off
	global_load_dwordx4 v[160:163], v[128:129], off
	s_nop 0
	global_load_dwordx4 v[148:151], v[144:145], off
	s_nop 0
	global_load_dwordx4 v[144:147], v[132:133], off
	s_nop 0
	global_load_dwordx4 v[132:135], v[238:239], off
	global_load_dwordx4 v[128:131], v[240:241], off
	v_mul_f32_e32 v122, v242, v122
	v_mul_f32_e32 v122, 0xbfb8aa3b, v122
	v_exp_f32_e32 v122, v122
	v_mul_f32_e32 v124, v242, v124
	v_mul_f32_e32 v125, v242, v125
	v_mul_f32_e32 v123, v242, v123
	v_mul_f32_e32 v124, 0xbfb8aa3b, v124
	v_mul_f32_e32 v125, 0xbfb8aa3b, v125
	v_mul_f32_e32 v123, 0xbfb8aa3b, v123
	v_exp_f32_e32 v124, v124
	v_exp_f32_e32 v125, v125
	v_exp_f32_e32 v123, v123
	v_mul_f32_e32 v112, v242, v112
	v_mul_f32_e32 v112, 0xbfb8aa3b, v112
	v_exp_f32_e32 v112, v112
	v_add_f32_e32 v124, 1.0, v124
	v_add_f32_e32 v125, 1.0, v125
	v_add_f32_e32 v123, 1.0, v123
	v_rcp_f32_e32 v124, v124
	v_rcp_f32_e32 v125, v125
	v_rcp_f32_e32 v123, v123
	v_mul_f32_e32 v113, v242, v113
	v_add_f32_e32 v112, 1.0, v112
	v_mul_f32_e32 v113, 0xbfb8aa3b, v113
	v_lshlrev_b32_e32 v240, 16, v222
	v_and_b32_e32 v222, 0xffff0000, v222
	v_lshlrev_b32_e32 v245, 16, v226
	v_fmac_f32_e32 v240, v120, v245
	v_add_f32_e32 v120, 1.0, v121
	v_mul_f32_e32 v121, v242, v126
	v_mul_f32_e32 v121, 0xbfb8aa3b, v121
	v_rcp_f32_e32 v120, v120
	v_exp_f32_e32 v121, v121
	v_and_b32_e32 v226, 0xffff0000, v226
	v_lshlrev_b64 v[236:237], 11, v[198:199]
	v_fmac_f32_e32 v222, v120, v226
	v_add_f32_e32 v120, 1.0, v121
	v_add_f32_e32 v121, 1.0, v122
	v_mul_f32_e32 v122, v242, v127
	v_mul_f32_e32 v122, 0xbfb8aa3b, v122
	v_exp_f32_e32 v122, v122
	v_rcp_f32_e32 v120, v120
	v_rcp_f32_e32 v121, v121
	v_lshlrev_b32_e32 v239, 16, v221
	v_add_f32_e32 v122, 1.0, v122
	v_rcp_f32_e32 v122, v122
	v_lshlrev_b32_e32 v241, 16, v223
	v_lshlrev_b32_e32 v244, 16, v225
	v_lshlrev_b32_e32 v246, 16, v227
	v_rcp_f32_e32 v112, v112
	v_exp_f32_e32 v113, v113
	v_lshlrev_b32_e32 v238, 16, v220
	v_and_b32_e32 v220, 0xffff0000, v220
	v_and_b32_e32 v221, 0xffff0000, v221
	v_and_b32_e32 v223, 0xffff0000, v223
	v_lshlrev_b32_e32 v243, 16, v224
	v_and_b32_e32 v224, 0xffff0000, v224
	v_and_b32_e32 v225, 0xffff0000, v225
	v_and_b32_e32 v227, 0xffff0000, v227
	v_fmac_f32_e32 v239, v120, v244
	v_fmac_f32_e32 v241, v121, v246
	v_lshl_add_u64 v[126:127], s[68:69], 0, v[236:237]
	v_lshlrev_b64 v[120:121], 1, v[196:197]
	v_fmac_f32_e32 v238, v124, v243
	v_fmac_f32_e32 v220, v125, v224
	v_fmac_f32_e32 v221, v122, v225
	v_fmac_f32_e32 v223, v123, v227
	v_cvt_pk_bf16_f32 v122, v238, v220
	v_cvt_pk_bf16_f32 v123, v239, v221
	v_cvt_pk_bf16_f32 v124, v240, v222
	v_cvt_pk_bf16_f32 v125, v241, v223
	v_lshl_add_u64 v[126:127], v[126:127], 0, v[120:121]
	global_store_dwordx4 v[126:127], v[122:125], off
	v_mul_f32_e32 v114, v242, v114
	v_mul_f32_e32 v114, 0xbfb8aa3b, v114
	v_mul_f32_e32 v122, v220, v220
	v_mul_f32_e32 v123, v221, v221
	s_waitcnt vmcnt(0)
	v_lshlrev_b32_e32 v125, 16, v229
	v_and_b32_e32 v220, 0xffff0000, v229
	v_lshlrev_b32_e32 v221, 16, v230
	v_lshlrev_b32_e32 v229, 16, v234
	v_fmac_f32_e32 v221, v112, v229
	v_add_f32_e32 v112, 1.0, v113
	v_mul_f32_e32 v113, v242, v118
	v_mul_f32_e32 v113, 0xbfb8aa3b, v113
	v_rcp_f32_e32 v112, v112
	v_exp_f32_e32 v113, v113
	v_exp_f32_e32 v114, v114
	v_fmac_f32_e32 v122, v238, v238
	v_fmac_f32_e32 v123, v239, v239
	v_add_f32_e32 v122, v122, v123
	v_mul_f32_e32 v123, v222, v222
	v_and_b32_e32 v222, 0xffff0000, v230
	v_and_b32_e32 v230, 0xffff0000, v234
	v_mul_f32_e32 v116, v242, v116
	v_mul_f32_e32 v117, v242, v117
	v_fmac_f32_e32 v222, v112, v230
	v_add_f32_e32 v112, 1.0, v113
	v_add_f32_e32 v113, 1.0, v114
	v_mul_f32_e32 v114, v242, v119
	v_mul_f32_e32 v116, 0xbfb8aa3b, v116
	v_mul_f32_e32 v117, 0xbfb8aa3b, v117
	v_mul_f32_e32 v114, 0xbfb8aa3b, v114
	v_mul_f32_e32 v115, v242, v115
	v_exp_f32_e32 v116, v116
	v_exp_f32_e32 v117, v117
	v_exp_f32_e32 v114, v114
	v_mul_f32_e32 v115, 0xbfb8aa3b, v115
	v_exp_f32_e32 v115, v115
	v_add_f32_e32 v116, 1.0, v116
	v_add_f32_e32 v117, 1.0, v117
	v_add_f32_e32 v114, 1.0, v114
	v_fmac_f32_e32 v123, v240, v240
	v_rcp_f32_e32 v116, v116
	v_rcp_f32_e32 v117, v117
	v_rcp_f32_e32 v112, v112
	v_rcp_f32_e32 v113, v113
	v_rcp_f32_e32 v114, v114
	v_add_f32_e32 v115, 1.0, v115
	v_add_f32_e32 v122, v123, v122
	v_mul_f32_e32 v123, v223, v223
	v_rcp_f32_e32 v115, v115
	v_fmac_f32_e32 v123, v241, v241
	v_add_f32_e32 v122, v123, v122
	v_lshlrev_b32_e32 v123, 16, v228
	v_and_b32_e32 v124, 0xffff0000, v228
	v_lshlrev_b32_e32 v223, 16, v231
	v_and_b32_e32 v224, 0xffff0000, v231
	v_lshlrev_b32_e32 v225, 16, v232
	v_and_b32_e32 v226, 0xffff0000, v232
	v_lshlrev_b32_e32 v227, 16, v233
	v_and_b32_e32 v228, 0xffff0000, v233
	v_lshlrev_b32_e32 v231, 16, v235
	v_and_b32_e32 v232, 0xffff0000, v235
	v_fmac_f32_e32 v123, v116, v225
	v_fmac_f32_e32 v124, v117, v226
	v_fmac_f32_e32 v125, v112, v227
	v_fmac_f32_e32 v223, v113, v231
	v_fmac_f32_e32 v220, v114, v228
	v_cvt_pk_bf16_f32 v112, v123, v124
	v_cvt_pk_bf16_f32 v113, v125, v220
	v_cvt_pk_bf16_f32 v114, v221, v222
	v_fmac_f32_e32 v224, v115, v232
	v_cvt_pk_bf16_f32 v115, v223, v224
	global_store_dwordx4 v[126:127], v[112:115], off offset:256
	v_lshlrev_b32_e32 v116, 16, v172
	v_and_b32_e32 v117, 0xffff0000, v172
	v_fmamk_f32 v114, v219, 0x3a800000, v212
	v_mul_f32_e32 v112, v124, v124
	v_mul_f32_e32 v113, v220, v220
	v_mul_f32_e32 v115, 0x4b800000, v114
	v_cmp_gt_f32_e64 s[6:7], s40, v114
	v_fmac_f32_e32 v112, v123, v123
	v_fmac_f32_e32 v113, v125, v125
	v_cndmask_b32_e64 v114, v114, v115, s[6:7]
	v_add_f32_e32 v112, v112, v113
	v_mul_f32_e32 v113, v222, v222
; __device__ __forceinline__ unsigned cvt_pk_bf16(float lo, float hi) { unsigned r; asm volatile("v_cvt_pk_bf16_f32 %0, %1, %2" : "=v"(r) : "v"(lo), "v"(hi)); return r; }
; __device__ __forceinline__ float sigmoidf_(float x) { return frcp(1.0f + __expf(-x)); }
;     __device__ __forceinline__ void operator()(const f32x4 (&acc)[2][2][4][2], const Unit& u, int wr, int wc, int fr, int fq, const float (&epre)[8]) const {
;     ...
;             for (int m = 0; m < 4; ++m) { const int row = row0 + ai * 128 + m * 16;
;                 const float rstd = rsqrtf(epre[ai * 4 + m] * (1.0f / DM) + EPS);
;                 float ss = 0.f;
; #pragma unroll
;                 for (int bj = 0; bj < 2; ++bj) { const size_t o = (size_t)row * DM + col0 + bj * 128;
;                     f32x4 h0, h1, p0, p1; unpack8(hw[m][bj], h0, h1); unpack8(pw[m][bj], p0, p1);
; #pragma unroll
;                     for (int j = 0; j < 4; ++j) { h0[j] += sigmoidf_(acc[ai][bj][m][0][j] * rstd) * p0[j]; h1[j] += sigmoidf_(acc[ai][bj][m][1][j] * rstd) * p1[j]; }
;                     u32x4 w; w.x = cvt_pk_bf16(h0[0], h0[1]); w.y = cvt_pk_bf16(h0[2], h0[3]); w.z = cvt_pk_bf16(h1[0], h1[1]); w.w = cvt_pk_bf16(h1[2], h1[3]);
;                     *(u32x4*)(H3 + o) = w;
;                     ss += (h0[0] * h0[0] + h0[1] * h0[1]) + (h0[2] * h0[2] + h0[3] * h0[3]) + (h1[0] * h1[0] + h1[1] * h1[1]) + (h1[2] * h1[2] + h1[3] * h1[3]); }
;                 ssv[m] = ss;
;             }
	v_rsq_f32_e32 v114, v114
	v_fmac_f32_e32 v113, v221, v221
	v_add_f32_e32 v112, v113, v112
	v_mul_f32_e32 v113, v224, v224
	v_fmac_f32_e32 v113, v223, v223
	v_add_f32_e32 v112, v113, v112
	v_mul_f32_e32 v113, 0x45800000, v114
	v_cndmask_b32_e64 v113, v114, v113, s[6:7]
	v_mul_f32_e32 v104, v113, v104
	v_mul_f32_e32 v104, 0xbfb8aa3b, v104
	v_exp_f32_e32 v104, v104
	v_mul_f32_e32 v105, v113, v105
	v_mul_f32_e32 v105, 0xbfb8aa3b, v105
	v_exp_f32_e32 v105, v105
	v_add_f32_e32 v104, 1.0, v104
	v_rcp_f32_e32 v104, v104
	v_add_f32_e32 v112, v122, v112
	v_lshlrev_b32_e32 v122, 16, v174
	v_lshlrev_b32_e32 v172, 16, v170
	v_fmac_f32_e32 v122, v104, v172
	v_add_f32_e32 v104, 1.0, v105
	v_mul_f32_e32 v105, v113, v110
	v_mul_f32_e32 v106, v113, v106
	v_mul_f32_e32 v105, 0xbfb8aa3b, v105
	v_mul_f32_e32 v106, 0xbfb8aa3b, v106
	v_rcp_f32_e32 v104, v104
	v_exp_f32_e32 v105, v105
	v_exp_f32_e32 v106, v106
	v_and_b32_e32 v123, 0xffff0000, v174
	v_mul_f32_e32 v108, v113, v108
	v_and_b32_e32 v170, 0xffff0000, v170
	v_mul_f32_e32 v109, v113, v109
	v_mul_f32_e32 v108, 0xbfb8aa3b, v108
	v_mul_f32_e32 v109, 0xbfb8aa3b, v109
	v_fmac_f32_e32 v123, v104, v170
	v_add_f32_e32 v104, 1.0, v105
	v_add_f32_e32 v105, 1.0, v106
	v_mul_f32_e32 v106, v113, v111
	v_exp_f32_e32 v108, v108
	v_exp_f32_e32 v109, v109
	v_mul_f32_e32 v106, 0xbfb8aa3b, v106
	v_mul_f32_e32 v107, v113, v107
	v_exp_f32_e32 v106, v106
	v_mul_f32_e32 v107, 0xbfb8aa3b, v107
	v_exp_f32_e32 v107, v107
	v_mul_f32_e32 v96, v113, v96
	v_add_f32_e32 v108, 1.0, v108
	v_add_f32_e32 v109, 1.0, v109
	v_mul_f32_e32 v96, 0xbfb8aa3b, v96
	v_rcp_f32_e32 v108, v108
	v_rcp_f32_e32 v109, v109
	v_add_f32_e32 v106, 1.0, v106
	v_exp_f32_e32 v96, v96
	v_rcp_f32_e32 v104, v104
	v_rcp_f32_e32 v105, v105
	v_rcp_f32_e32 v106, v106
	v_add_f32_e32 v107, 1.0, v107
	v_rcp_f32_e32 v107, v107
	v_lshlrev_b64 v[114:115], 11, v[204:205]
	v_lshlrev_b32_e32 v126, 16, v168
	v_and_b32_e32 v127, 0xffff0000, v168
	v_mul_f32_e32 v97, v113, v97
	v_lshlrev_b32_e32 v118, 16, v173
	v_and_b32_e32 v119, 0xffff0000, v173
	v_lshlrev_b32_e32 v124, 16, v175
	v_lshlrev_b32_e32 v168, 16, v169
	v_and_b32_e32 v169, 0xffff0000, v169
	v_lshlrev_b32_e32 v173, 16, v171
	v_fmac_f32_e32 v116, v108, v126
	v_fmac_f32_e32 v117, v109, v127
	v_lshl_add_u64 v[108:109], s[68:69], 0, v[114:115]
	v_add_f32_e32 v96, 1.0, v96
	v_mul_f32_e32 v97, 0xbfb8aa3b, v97
	v_and_b32_e32 v125, 0xffff0000, v175
	v_and_b32_e32 v171, 0xffff0000, v171
	v_fmac_f32_e32 v118, v104, v168
	v_fmac_f32_e32 v124, v105, v173
	v_fmac_f32_e32 v119, v106, v169
	v_cvt_pk_bf16_f32 v104, v116, v117
	v_cvt_pk_bf16_f32 v105, v118, v119
	v_lshl_add_u64 v[108:109], v[108:109], 0, v[120:121]
	v_rcp_f32_e32 v96, v96
	v_exp_f32_e32 v97, v97
	v_fmac_f32_e32 v125, v107, v171
	v_cvt_pk_bf16_f32 v106, v122, v123
	v_cvt_pk_bf16_f32 v107, v124, v125
	global_store_dwordx4 v[108:109], v[104:107], off
	v_lshlrev_b32_e32 v111, 16, v166
	v_mul_f32_e32 v98, v113, v98
	v_mul_f32_e32 v104, v117, v117
	v_mul_f32_e32 v105, v119, v119
	v_fmac_f32_e32 v104, v116, v116
	v_fmac_f32_e32 v105, v118, v118
	v_add_f32_e32 v104, v104, v105
	v_mul_f32_e32 v105, v123, v123
	v_lshlrev_b32_e32 v123, 16, v162
	v_fmac_f32_e32 v111, v96, v123
	v_add_f32_e32 v96, 1.0, v97
	v_mul_f32_e32 v97, v113, v102
	v_mul_f32_e32 v97, 0xbfb8aa3b, v97
	v_mul_f32_e32 v98, 0xbfb8aa3b, v98
	v_rcp_f32_e32 v96, v96
	v_exp_f32_e32 v97, v97
	v_exp_f32_e32 v98, v98
	v_fmac_f32_e32 v105, v122, v122
	v_add_f32_e32 v104, v105, v104
	v_mul_f32_e32 v105, v125, v125
	v_fmac_f32_e32 v105, v124, v124
	v_and_b32_e32 v114, 0xffff0000, v166
	v_and_b32_e32 v124, 0xffff0000, v162
	v_mul_f32_e32 v100, v113, v100
	v_mul_f32_e32 v101, v113, v101
	v_fmac_f32_e32 v114, v96, v124
	v_add_f32_e32 v96, 1.0, v97
	v_add_f32_e32 v97, 1.0, v98
	v_mul_f32_e32 v98, v113, v103
	v_mul_f32_e32 v100, 0xbfb8aa3b, v100
	v_mul_f32_e32 v101, 0xbfb8aa3b, v101
	v_mul_f32_e32 v98, 0xbfb8aa3b, v98
	v_mul_f32_e32 v99, v113, v99
	v_exp_f32_e32 v100, v100
	v_exp_f32_e32 v101, v101
	v_exp_f32_e32 v98, v98
	v_mul_f32_e32 v99, 0xbfb8aa3b, v99
	v_exp_f32_e32 v99, v99
	v_add_f32_e32 v100, 1.0, v100
	v_add_f32_e32 v101, 1.0, v101
	v_add_f32_e32 v98, 1.0, v98
	v_rcp_f32_e32 v100, v100
	v_rcp_f32_e32 v101, v101
	v_rcp_f32_e32 v96, v96
	v_rcp_f32_e32 v97, v97
	v_rcp_f32_e32 v98, v98
	v_add_f32_e32 v99, 1.0, v99
	v_rcp_f32_e32 v99, v99
	v_add_f32_e32 v104, v105, v104
	v_lshlrev_b32_e32 v105, 16, v164
	v_and_b32_e32 v106, 0xffff0000, v164
	v_lshlrev_b32_e32 v107, 16, v165
	v_and_b32_e32 v110, 0xffff0000, v165
	v_lshlrev_b32_e32 v115, 16, v167
	v_lshlrev_b32_e32 v117, 16, v160
	v_and_b32_e32 v118, 0xffff0000, v160
	v_lshlrev_b32_e32 v119, 16, v161
	v_and_b32_e32 v122, 0xffff0000, v161
	v_lshlrev_b32_e32 v125, 16, v163
	v_and_b32_e32 v116, 0xffff0000, v167
	v_and_b32_e32 v126, 0xffff0000, v163
	v_fmac_f32_e32 v105, v100, v117
	v_fmac_f32_e32 v106, v101, v118
	v_fmac_f32_e32 v107, v96, v119
	v_fmac_f32_e32 v115, v97, v125
	v_fmac_f32_e32 v110, v98, v122
	v_cvt_pk_bf16_f32 v96, v105, v106
	v_cvt_pk_bf16_f32 v97, v107, v110
	v_cvt_pk_bf16_f32 v98, v111, v114
	v_fmac_f32_e32 v116, v99, v126
	v_cvt_pk_bf16_f32 v99, v115, v116
	global_store_dwordx4 v[108:109], v[96:99], off offset:256
	v_lshlrev_b32_e32 v113, 16, v154
	v_lshlrev_b32_e32 v100, 16, v156
	v_mul_f32_e32 v96, v106, v106
	v_mul_f32_e32 v97, v110, v110
	v_fmamk_f32 v98, v218, 0x3a800000, v212
	v_fmac_f32_e32 v96, v105, v105
	v_fmac_f32_e32 v97, v107, v107
	v_mul_f32_e32 v99, 0x4b800000, v98
	v_cmp_gt_f32_e64 s[6:7], s40, v98
	v_add_f32_e32 v96, v96, v97
	v_mul_f32_e32 v97, v114, v114
	v_cndmask_b32_e64 v98, v98, v99, s[6:7]
	v_fmac_f32_e32 v97, v111, v111
; __device__ __forceinline__ unsigned cvt_pk_bf16(float lo, float hi) { unsigned r; asm volatile("v_cvt_pk_bf16_f32 %0, %1, %2" : "=v"(r) : "v"(lo), "v"(hi)); return r; }
; __device__ __forceinline__ float sigmoidf_(float x) { return frcp(1.0f + __expf(-x)); }
;     __device__ __forceinline__ void operator()(const f32x4 (&acc)[2][2][4][2], const Unit& u, int wr, int wc, int fr, int fq, const float (&epre)[8]) const {
;     ...
;             for (int m = 0; m < 4; ++m) { const int row = row0 + ai * 128 + m * 16;
;                 const float rstd = rsqrtf(epre[ai * 4 + m] * (1.0f / DM) + EPS);
;                 float ss = 0.f;
; #pragma unroll
;                 for (int bj = 0; bj < 2; ++bj) { const size_t o = (size_t)row * DM + col0 + bj * 128;
;                     f32x4 h0, h1, p0, p1; unpack8(hw[m][bj], h0, h1); unpack8(pw[m][bj], p0, p1);
; #pragma unroll
;                     for (int j = 0; j < 4; ++j) { h0[j] += sigmoidf_(acc[ai][bj][m][0][j] * rstd) * p0[j]; h1[j] += sigmoidf_(acc[ai][bj][m][1][j] * rstd) * p1[j]; }
;                     u32x4 w; w.x = cvt_pk_bf16(h0[0], h0[1]); w.y = cvt_pk_bf16(h0[2], h0[3]); w.z = cvt_pk_bf16(h1[0], h1[1]); w.w = cvt_pk_bf16(h1[2], h1[3]);
;                     *(u32x4*)(H3 + o) = w;
;                     ss += (h0[0] * h0[0] + h0[1] * h0[1]) + (h0[2] * h0[2] + h0[3] * h0[3]) + (h1[0] * h1[0] + h1[1] * h1[1]) + (h1[2] * h1[2] + h1[3] * h1[3]); }
;                 ssv[m] = ss;
;             }
	v_rsq_f32_e32 v98, v98
	v_add_f32_e32 v96, v97, v96
	v_mul_f32_e32 v97, v116, v116
	v_fmac_f32_e32 v97, v115, v115
	v_add_f32_e32 v96, v97, v96
	v_add_f32_e32 v99, v104, v96
	v_mul_f32_e32 v96, 0x45800000, v98
	v_cndmask_b32_e64 v98, v98, v96, s[6:7]
	v_mul_f32_e32 v88, v98, v88
	v_mul_f32_e32 v88, 0xbfb8aa3b, v88
	v_exp_f32_e32 v88, v88
	v_mul_f32_e32 v89, v98, v89
	v_mul_f32_e32 v89, 0xbfb8aa3b, v89
	v_exp_f32_e32 v89, v89
	v_add_f32_e32 v88, 1.0, v88
	v_rcp_f32_e32 v88, v88
	v_lshlrev_b32_e32 v104, 16, v158
	v_mul_f32_e32 v90, v98, v90
	v_mul_f32_e32 v90, 0xbfb8aa3b, v90
	v_fmac_f32_e32 v104, v88, v113
	v_add_f32_e32 v88, 1.0, v89
	v_mul_f32_e32 v89, v98, v94
	v_mul_f32_e32 v89, 0xbfb8aa3b, v89
	v_rcp_f32_e32 v88, v88
	v_exp_f32_e32 v89, v89
	v_exp_f32_e32 v90, v90
	v_and_b32_e32 v105, 0xffff0000, v158
	v_mul_f32_e32 v92, v98, v92
	v_and_b32_e32 v114, 0xffff0000, v154
	v_mul_f32_e32 v93, v98, v93
	v_mul_f32_e32 v92, 0xbfb8aa3b, v92
	v_mul_f32_e32 v93, 0xbfb8aa3b, v93
	v_fmac_f32_e32 v105, v88, v114
	v_add_f32_e32 v88, 1.0, v89
	v_add_f32_e32 v89, 1.0, v90
	v_mul_f32_e32 v90, v98, v95
	v_exp_f32_e32 v92, v92
	v_exp_f32_e32 v93, v93
	v_mul_f32_e32 v90, 0xbfb8aa3b, v90
	v_mul_f32_e32 v91, v98, v91
	v_exp_f32_e32 v90, v90
	v_mul_f32_e32 v91, 0xbfb8aa3b, v91
	v_exp_f32_e32 v91, v91
	v_mul_f32_e32 v80, v98, v80
	v_add_f32_e32 v92, 1.0, v92
	v_add_f32_e32 v93, 1.0, v93
	v_mul_f32_e32 v80, 0xbfb8aa3b, v80
	v_rcp_f32_e32 v92, v92
	v_rcp_f32_e32 v93, v93
	v_add_f32_e32 v90, 1.0, v90
	v_exp_f32_e32 v80, v80
	v_rcp_f32_e32 v88, v88
	v_rcp_f32_e32 v89, v89
	v_rcp_f32_e32 v90, v90
	v_add_f32_e32 v91, 1.0, v91
	v_rcp_f32_e32 v91, v91
	v_lshlrev_b64 v[96:97], 11, v[202:203]
	v_and_b32_e32 v101, 0xffff0000, v156
	v_lshlrev_b32_e32 v108, 16, v152
	v_and_b32_e32 v109, 0xffff0000, v152
	v_mul_f32_e32 v81, v98, v81
	v_lshlrev_b32_e32 v102, 16, v157
	v_and_b32_e32 v103, 0xffff0000, v157
	v_lshlrev_b32_e32 v106, 16, v159
	v_lshlrev_b32_e32 v110, 16, v153
	v_and_b32_e32 v111, 0xffff0000, v153
	v_lshlrev_b32_e32 v115, 16, v155
	v_fmac_f32_e32 v100, v92, v108
	v_fmac_f32_e32 v101, v93, v109
	v_lshl_add_u64 v[92:93], s[68:69], 0, v[96:97]
	v_add_f32_e32 v80, 1.0, v80
	v_mul_f32_e32 v81, 0xbfb8aa3b, v81
	v_and_b32_e32 v107, 0xffff0000, v159
	v_and_b32_e32 v116, 0xffff0000, v155
	v_fmac_f32_e32 v102, v88, v110
	v_fmac_f32_e32 v106, v89, v115
	v_fmac_f32_e32 v103, v90, v111
	v_cvt_pk_bf16_f32 v88, v100, v101
	v_cvt_pk_bf16_f32 v89, v102, v103
	v_lshl_add_u64 v[92:93], v[92:93], 0, v[120:121]
	v_rcp_f32_e32 v80, v80
	v_exp_f32_e32 v81, v81
	v_fmac_f32_e32 v107, v91, v116
	v_cvt_pk_bf16_f32 v90, v104, v105
	v_cvt_pk_bf16_f32 v91, v106, v107
	global_store_dwordx4 v[92:93], v[88:91], off
	v_lshlrev_b32_e32 v95, 16, v150
	v_mul_f32_e32 v82, v98, v82
	v_mul_f32_e32 v88, v101, v101
	v_mul_f32_e32 v89, v103, v103
	v_fmac_f32_e32 v88, v100, v100
	v_fmac_f32_e32 v89, v102, v102
	v_add_f32_e32 v88, v88, v89
	v_mul_f32_e32 v89, v105, v105
	v_lshlrev_b32_e32 v105, 16, v146
	v_fmac_f32_e32 v95, v80, v105
	v_add_f32_e32 v80, 1.0, v81
	v_mul_f32_e32 v81, v98, v86
	v_mul_f32_e32 v81, 0xbfb8aa3b, v81
	v_mul_f32_e32 v82, 0xbfb8aa3b, v82
	v_rcp_f32_e32 v80, v80
	v_exp_f32_e32 v81, v81
	v_exp_f32_e32 v82, v82
	v_fmac_f32_e32 v89, v104, v104
	v_add_f32_e32 v88, v89, v88
	v_mul_f32_e32 v89, v107, v107
	v_fmac_f32_e32 v89, v106, v106
	v_and_b32_e32 v96, 0xffff0000, v150
	v_and_b32_e32 v106, 0xffff0000, v146
	v_mul_f32_e32 v84, v98, v84
	v_mul_f32_e32 v85, v98, v85
	v_fmac_f32_e32 v96, v80, v106
	v_add_f32_e32 v80, 1.0, v81
	v_add_f32_e32 v81, 1.0, v82
	v_mul_f32_e32 v82, v98, v87
	v_mul_f32_e32 v84, 0xbfb8aa3b, v84
	v_mul_f32_e32 v85, 0xbfb8aa3b, v85
	v_mul_f32_e32 v82, 0xbfb8aa3b, v82
	v_mul_f32_e32 v83, v98, v83
	v_exp_f32_e32 v84, v84
	v_exp_f32_e32 v85, v85
	v_exp_f32_e32 v82, v82
	v_mul_f32_e32 v83, 0xbfb8aa3b, v83
	v_exp_f32_e32 v83, v83
	v_add_f32_e32 v84, 1.0, v84
	v_add_f32_e32 v85, 1.0, v85
	v_add_f32_e32 v82, 1.0, v82
	v_rcp_f32_e32 v84, v84
	v_rcp_f32_e32 v85, v85
	v_rcp_f32_e32 v80, v80
	v_rcp_f32_e32 v81, v81
	v_rcp_f32_e32 v82, v82
	v_add_f32_e32 v83, 1.0, v83
	v_rcp_f32_e32 v83, v83
	v_add_f32_e32 v88, v89, v88
	v_lshlrev_b32_e32 v89, 16, v148
	v_and_b32_e32 v90, 0xffff0000, v148
	v_lshlrev_b32_e32 v91, 16, v149
	v_and_b32_e32 v94, 0xffff0000, v149
	v_lshlrev_b32_e32 v97, 16, v151
	v_lshlrev_b32_e32 v101, 16, v144
	v_and_b32_e32 v102, 0xffff0000, v144
	v_lshlrev_b32_e32 v103, 16, v145
	v_and_b32_e32 v104, 0xffff0000, v145
	v_lshlrev_b32_e32 v107, 16, v147
	v_and_b32_e32 v100, 0xffff0000, v151
	v_and_b32_e32 v108, 0xffff0000, v147
	v_fmac_f32_e32 v89, v84, v101
	v_fmac_f32_e32 v90, v85, v102
	v_fmac_f32_e32 v91, v80, v103
	v_fmac_f32_e32 v97, v81, v107
	v_fmac_f32_e32 v94, v82, v104
	v_cvt_pk_bf16_f32 v80, v89, v90
	v_cvt_pk_bf16_f32 v81, v91, v94
	v_cvt_pk_bf16_f32 v82, v95, v96
	v_fmac_f32_e32 v100, v83, v108
	v_cvt_pk_bf16_f32 v83, v97, v100
	global_store_dwordx4 v[92:93], v[80:83], off offset:256
	v_lshlrev_b32_e32 v84, 16, v140
	v_and_b32_e32 v85, 0xffff0000, v140
	v_mul_f32_e32 v80, v90, v90
	v_mul_f32_e32 v81, v94, v94
	v_fmamk_f32 v82, v217, 0x3a800000, v212
	v_fmac_f32_e32 v80, v89, v89
	v_fmac_f32_e32 v81, v91, v91
	v_mul_f32_e32 v83, 0x4b800000, v82
	v_cmp_gt_f32_e64 s[6:7], s40, v82
	v_add_f32_e32 v80, v80, v81
	v_mul_f32_e32 v81, v96, v96
	v_cndmask_b32_e64 v82, v82, v83, s[6:7]
	v_fmac_f32_e32 v81, v95, v95
	v_rsq_f32_e32 v82, v82
	v_add_f32_e32 v80, v81, v80
	v_mul_f32_e32 v81, v100, v100
	v_fmac_f32_e32 v81, v97, v97
	v_add_f32_e32 v80, v81, v80
	v_add_f32_e32 v83, v88, v80
	v_mul_f32_e32 v80, 0x45800000, v82
	v_cndmask_b32_e64 v82, v82, v80, s[6:7]
; __device__ __forceinline__ unsigned cvt_pk_bf16(float lo, float hi) { unsigned r; asm volatile("v_cvt_pk_bf16_f32 %0, %1, %2" : "=v"(r) : "v"(lo), "v"(hi)); return r; }
; __device__ __forceinline__ float sigmoidf_(float x) { return frcp(1.0f + __expf(-x)); }
;     __device__ __forceinline__ void operator()(const f32x4 (&acc)[2][2][4][2], const Unit& u, int wr, int wc, int fr, int fq, const float (&epre)[8]) const {
;     ...
;             for (int m = 0; m < 4; ++m) { const int row = row0 + ai * 128 + m * 16;
;                 const float rstd = rsqrtf(epre[ai * 4 + m] * (1.0f / DM) + EPS);
;                 float ss = 0.f;
; #pragma unroll
;                 for (int bj = 0; bj < 2; ++bj) { const size_t o = (size_t)row * DM + col0 + bj * 128;
;                     f32x4 h0, h1, p0, p1; unpack8(hw[m][bj], h0, h1); unpack8(pw[m][bj], p0, p1);
; #pragma unroll
;                     for (int j = 0; j < 4; ++j) { h0[j] += sigmoidf_(acc[ai][bj][m][0][j] * rstd) * p0[j]; h1[j] += sigmoidf_(acc[ai][bj][m][1][j] * rstd) * p1[j]; }
;                     u32x4 w; w.x = cvt_pk_bf16(h0[0], h0[1]); w.y = cvt_pk_bf16(h0[2], h0[3]); w.z = cvt_pk_bf16(h1[0], h1[1]); w.w = cvt_pk_bf16(h1[2], h1[3]);
;                     *(u32x4*)(H3 + o) = w;
;                     ss += (h0[0] * h0[0] + h0[1] * h0[1]) + (h0[2] * h0[2] + h0[3] * h0[3]) + (h1[0] * h1[0] + h1[1] * h1[1]) + (h1[2] * h1[2] + h1[3] * h1[3]); }
;                 ssv[m] = ss;
;             }
; #pragma unroll
;             for (int m = 0; m < 4; ++m) ssv[m] += __shfl_xor(ssv[m], 16);
; #pragma unroll
;             for (int m = 0; m < 4; ++m) ssv[m] += __shfl_xor(ssv[m], 32);
;             if (fq == 0) {
; #pragma unroll
;                 for (int m = 0; m < 4; ++m) atomicAdd(sumsq3 + row0 + ai * 128 + m * 16, ssv[m]); }
	v_mul_f32_e32 v72, v82, v72
	v_mul_f32_e32 v72, 0xbfb8aa3b, v72
	v_exp_f32_e32 v72, v72
	v_mul_f32_e32 v73, v82, v73
	v_mul_f32_e32 v73, 0xbfb8aa3b, v73
	v_exp_f32_e32 v73, v73
	v_add_f32_e32 v72, 1.0, v72
	v_rcp_f32_e32 v72, v72
	v_lshlrev_b32_e32 v88, 16, v142
	v_lshlrev_b32_e32 v96, 16, v138
	v_mul_f32_e32 v74, v82, v74
	v_fmac_f32_e32 v88, v72, v96
	v_add_f32_e32 v72, 1.0, v73
	v_mul_f32_e32 v73, v82, v78
	v_mul_f32_e32 v73, 0xbfb8aa3b, v73
	v_mul_f32_e32 v74, 0xbfb8aa3b, v74
	v_rcp_f32_e32 v72, v72
	v_exp_f32_e32 v73, v73
	v_exp_f32_e32 v74, v74
	v_and_b32_e32 v89, 0xffff0000, v142
	v_mul_f32_e32 v76, v82, v76
	v_and_b32_e32 v97, 0xffff0000, v138
	v_mul_f32_e32 v77, v82, v77
	v_mul_f32_e32 v76, 0xbfb8aa3b, v76
	v_mul_f32_e32 v77, 0xbfb8aa3b, v77
	v_fmac_f32_e32 v89, v72, v97
	v_add_f32_e32 v72, 1.0, v73
	v_add_f32_e32 v73, 1.0, v74
	v_mul_f32_e32 v74, v82, v79
	v_exp_f32_e32 v76, v76
	v_exp_f32_e32 v77, v77
	v_mul_f32_e32 v74, 0xbfb8aa3b, v74
	v_mul_f32_e32 v75, v82, v75
	v_exp_f32_e32 v74, v74
	v_mul_f32_e32 v75, 0xbfb8aa3b, v75
	v_exp_f32_e32 v75, v75
	v_mul_f32_e32 v64, v82, v64
	v_add_f32_e32 v76, 1.0, v76
	v_add_f32_e32 v77, 1.0, v77
	v_mul_f32_e32 v64, 0xbfb8aa3b, v64
	v_rcp_f32_e32 v76, v76
	v_rcp_f32_e32 v77, v77
	v_add_f32_e32 v74, 1.0, v74
	v_exp_f32_e32 v64, v64
	v_rcp_f32_e32 v72, v72
	v_rcp_f32_e32 v73, v73
	v_rcp_f32_e32 v74, v74
	v_add_f32_e32 v75, 1.0, v75
	v_rcp_f32_e32 v75, v75
	v_lshlrev_b64 v[80:81], 11, v[200:201]
	v_lshlrev_b32_e32 v92, 16, v136
	v_and_b32_e32 v93, 0xffff0000, v136
	v_mul_f32_e32 v65, v82, v65
	v_lshlrev_b32_e32 v86, 16, v141
	v_and_b32_e32 v87, 0xffff0000, v141
	v_lshlrev_b32_e32 v90, 16, v143
	v_lshlrev_b32_e32 v94, 16, v137
	v_and_b32_e32 v95, 0xffff0000, v137
	v_lshlrev_b32_e32 v98, 16, v139
	v_fmac_f32_e32 v84, v76, v92
	v_fmac_f32_e32 v85, v77, v93
	v_lshl_add_u64 v[76:77], s[68:69], 0, v[80:81]
	v_add_f32_e32 v64, 1.0, v64
	v_mul_f32_e32 v65, 0xbfb8aa3b, v65
	v_and_b32_e32 v91, 0xffff0000, v143
	v_and_b32_e32 v100, 0xffff0000, v139
	v_fmac_f32_e32 v86, v72, v94
	v_fmac_f32_e32 v90, v73, v98
	v_fmac_f32_e32 v87, v74, v95
	v_cvt_pk_bf16_f32 v72, v84, v85
	v_cvt_pk_bf16_f32 v73, v86, v87
	v_lshl_add_u64 v[76:77], v[76:77], 0, v[120:121]
	v_rcp_f32_e32 v64, v64
	v_exp_f32_e32 v65, v65
	v_fmac_f32_e32 v91, v75, v100
	v_cvt_pk_bf16_f32 v74, v88, v89
	v_cvt_pk_bf16_f32 v75, v90, v91
	global_store_dwordx4 v[76:77], v[72:75], off
	v_lshlrev_b32_e32 v80, 16, v134
	v_mul_f32_e32 v66, v82, v66
	v_mul_f32_e32 v72, v85, v85
	v_mul_f32_e32 v73, v87, v87
	v_fmac_f32_e32 v72, v84, v84
	v_fmac_f32_e32 v73, v86, v86
	v_add_f32_e32 v72, v72, v73
	v_mul_f32_e32 v73, v89, v89
	v_lshlrev_b32_e32 v89, 16, v130
	v_fmac_f32_e32 v80, v64, v89
	v_add_f32_e32 v64, 1.0, v65
	v_mul_f32_e32 v65, v82, v70
	v_mul_f32_e32 v65, 0xbfb8aa3b, v65
	v_mul_f32_e32 v66, 0xbfb8aa3b, v66
	v_rcp_f32_e32 v64, v64
	v_exp_f32_e32 v65, v65
	v_exp_f32_e32 v66, v66
	v_fmac_f32_e32 v73, v88, v88
	v_add_f32_e32 v72, v73, v72
	v_mul_f32_e32 v73, v91, v91
	v_fmac_f32_e32 v73, v90, v90
	v_and_b32_e32 v81, 0xffff0000, v134
	v_and_b32_e32 v90, 0xffff0000, v130
	v_mul_f32_e32 v69, v82, v69
	v_fmac_f32_e32 v81, v64, v90
	v_add_f32_e32 v64, 1.0, v65
	v_add_f32_e32 v65, 1.0, v66
	v_mul_f32_e32 v66, v82, v71
	v_mul_f32_e32 v68, v82, v68
	v_mul_f32_e32 v69, 0xbfb8aa3b, v69
	v_mul_f32_e32 v66, 0xbfb8aa3b, v66
	v_mul_f32_e32 v68, 0xbfb8aa3b, v68
	v_exp_f32_e32 v69, v69
	v_exp_f32_e32 v66, v66
	v_exp_f32_e32 v68, v68
	v_mul_f32_e32 v67, v82, v67
	v_mul_f32_e32 v67, 0xbfb8aa3b, v67
	v_add_f32_e32 v69, 1.0, v69
	v_exp_f32_e32 v67, v67
	v_add_f32_e32 v66, 1.0, v66
	v_add_f32_e32 v68, 1.0, v68
	v_rcp_f32_e32 v69, v69
	v_rcp_f32_e32 v66, v66
	v_rcp_f32_e32 v68, v68
	v_rcp_f32_e32 v64, v64
	v_rcp_f32_e32 v65, v65
	v_and_b32_e32 v75, 0xffff0000, v132
	v_and_b32_e32 v79, 0xffff0000, v133
	v_and_b32_e32 v86, 0xffff0000, v128
	v_and_b32_e32 v88, 0xffff0000, v129
	v_add_f32_e32 v67, 1.0, v67
	v_add_f32_e32 v73, v73, v72
	v_lshlrev_b32_e32 v74, 16, v132
	v_lshlrev_b32_e32 v78, 16, v133
	v_lshlrev_b32_e32 v84, 16, v135
	v_lshlrev_b32_e32 v72, 16, v128
	v_lshlrev_b32_e32 v87, 16, v129
	v_lshlrev_b32_e32 v91, 16, v131
	v_fmac_f32_e32 v75, v69, v86
	v_rcp_f32_e32 v67, v67
	v_fmac_f32_e32 v79, v66, v88
	v_fmac_f32_e32 v74, v68, v72
	v_fmac_f32_e32 v78, v64, v87
	v_fmac_f32_e32 v84, v65, v91
	v_mul_f32_e32 v64, v75, v75
	v_mul_f32_e32 v65, v79, v79
	v_fmac_f32_e32 v64, v74, v74
	v_fmac_f32_e32 v65, v78, v78
	v_and_b32_e32 v85, 0xffff0000, v135
	v_and_b32_e32 v92, 0xffff0000, v131
	v_add_f32_e32 v64, v64, v65
	v_mul_f32_e32 v65, v81, v81
	v_fmac_f32_e32 v85, v67, v92
	v_fmac_f32_e32 v65, v80, v80
	v_add_f32_e32 v64, v65, v64
	v_mul_f32_e32 v65, v85, v85
	v_fmac_f32_e32 v65, v84, v84
	v_add_f32_e32 v64, v65, v64
	v_and_b32_e32 v65, 64, v179
	v_add_f32_e32 v67, v73, v64
	v_xor_b32_e32 v64, 16, v179
	v_add_u32_e32 v68, 64, v65
	v_cmp_lt_i32_e64 s[6:7], v64, v68
	v_cvt_pk_bf16_f32 v72, v74, v75
	v_cvt_pk_bf16_f32 v73, v78, v79
	v_cvt_pk_bf16_f32 v74, v80, v81
	v_cvt_pk_bf16_f32 v75, v84, v85
	global_store_dwordx4 v[76:77], v[72:75], off offset:256
	s_nop 0
	v_cndmask_b32_e64 v64, v179, v64, s[6:7]
	v_lshlrev_b32_e32 v122, 2, v64
	ds_bpermute_b32 v69, v122, v67
	ds_bpermute_b32 v64, v122, v112
	ds_bpermute_b32 v65, v122, v99
	ds_bpermute_b32 v66, v122, v83
	s_waitcnt lgkmcnt(0)
	v_add_f32_e32 v67, v67, v69
	v_xor_b32_e32 v69, 32, v179
	v_cmp_lt_i32_e64 s[6:7], v69, v68
	v_add_f32_e32 v64, v112, v64
	v_add_f32_e32 v65, v99, v65
	v_cndmask_b32_e64 v68, v179, v69, s[6:7]
	v_add_f32_e32 v66, v83, v66
	v_lshlrev_b32_e32 v123, 2, v68
	ds_bpermute_b32 v68, v123, v64
	ds_bpermute_b32 v69, v123, v65
	ds_bpermute_b32 v70, v123, v66
	ds_bpermute_b32 v71, v123, v67
	v_lshl_add_u64 v[112:113], v[198:199], 2, s[10:11]
	s_and_saveexec_b64 s[6:7], s[4:5]
	s_cbranch_execz .LBB0_888
	s_waitcnt lgkmcnt(3)
	v_add_f32_e32 v64, v64, v68
	s_waitcnt lgkmcnt(0)
	v_add_f32_e32 v67, v67, v71
	v_add_f32_e32 v66, v66, v70
	v_add_f32_e32 v65, v65, v69
	global_atomic_add_f32 v[112:113], v64, off
	global_atomic_add_f32 v[112:113], v65, off offset:64
	global_atomic_add_f32 v[112:113], v66, off offset:128
	global_atomic_add_f32 v[112:113], v67, off offset:192
